# accumulator zeroing with 64 v_mov_b64 instead of 127 v_mov_b32 per tile; paired s_waitcnt merged in GEMM load segments (on top of XCD barrier at first seam, GEMM-loop edge edits, saddr DMA, f8f6f4 fp8
# speedup vs baseline: 1.0209x; 1.0010x over previous
; #define PG8_WAIT_V(n) asm volatile("s_waitcnt vmcnt(" #n ")" ::: "memory")
; #define PG8_WAIT_L(n) asm volatile("s_waitcnt lgkmcnt(" #n ")" ::: "memory")
; template <class Epi, bool FP8 = false>
; __device__ __forceinline__ void gemm_phase(LAS unsigned char* lds, const Gemm g, const StaticOrder& S_, const Epi& E, const int tid) {
;     ...
;         const bool has_next = S_.next(ui + 1, nxt);
;         const char* nA = has_next ? (const char*)g.A + (size_t)nxt.pm * tstepA : cA; const char* nB = has_next ? (const char*)g.Bt + (size_t)nxt.pn * tstepB : cB;
;         for (int t = 0; t < nt; t += 2) {
;             const bool last = (t == nt - 2);
;             const char* a1 = cA + (size_t)(t + 1) * kstep;
;             const char* a2 = last ? nA : cA + (size_t)(t + 2) * kstep; const char* b2 = last ? nB : cB + (size_t)(t + 2) * kstep;
;             const char* a3 = a2 + kstep; const char* b3 = b2 + kstep;
;             PG8_LDB(B0, 0, 0); PG8_LDB(B1, 0, 1); PG8_SCHED; PG8_LDA(At, 0, 0); PG8_STAGE(PG8_SA(1, 1), a1 + hstepA, voffA);
;             PG8_WAIT_V(8); PG8_WAIT_L(0); PG8_BAR; PG8_MMA(0, 0, At, B0); PG8_MMA(0, 1, At, B1); PG8_BAR; PG8_SCHED;
;             PG8_LDA(At, 0, 1); PG8_STAGE(PG8_SB(0, 0), b2, voffB); PG8_STAGE(PG8_SB(0, 1), b2 + hstepB, voffB); PG8_STAGE(PG8_SA(0, 0), a2, voffA);
;             PG8_WAIT_V(8); PG8_WAIT_L(0); PG8_BAR; PG8_MMA(1, 0, At, B0); PG8_MMA(1, 1, At, B1); PG8_BAR; PG8_SCHED;
;             PG8_LDB(B0, 1, 0); PG8_LDB(B1, 1, 1); PG8_SCHED; PG8_LDA(At, 1, 0); PG8_STAGE(PG8_SA(0, 1), a2 + hstepA, voffA);
;             PG8_WAIT_V(8); PG8_WAIT_L(0); PG8_BAR; PG8_MMA(0, 0, At, B0); PG8_MMA(0, 1, At, B1); PG8_BAR; PG8_SCHED;
;             PG8_LDA(At, 1, 1); PG8_STAGE(PG8_SB(1, 0), b3, voffB); PG8_STAGE(PG8_SB(1, 1), b3 + hstepB, voffB); PG8_STAGE(PG8_SA(1, 0), a3, voffA);
;             PG8_WAIT_V(8); PG8_WAIT_L(0); PG8_BAR; PG8_MMA(1, 0, At, B0); PG8_MMA(1, 1, At, B1); PG8_BAR; PG8_SCHED;
;         }
;         if (wr == 0) PG8_BAR;
;         E(acc, cur, wr, wc, fr, fq);
;         if (!has_next) break;
; #pragma unroll
;         for (int a = 0; a < 2; ++a)
; #pragma unroll
;             for (int b = 0; b < 2; ++b)
; #pragma unroll
;                 for (int m = 0; m < 4; ++m)
; #pragma unroll
;                     for (int n = 0; n < 2; ++n) acc[a][b][m][n] = (f32x4){0.f, 0.f, 0.f, 0.f};
;         cur = nxt; cA = nA; cB = nB; ++ui;
.LBB0_232:
	s_ashr_i32 s17, s16, 31
	s_lshl_b64 s[18:19], s[16:17], 20
	s_add_u32 s18, s35, s18
	s_addc_u32 s19, s48, s19
	s_and_b64 s[20:21], s[4:5], exec
	s_cselect_b32 s17, s19, s31
	s_cselect_b32 s43, s18, s30
	s_ashr_i32 s15, s14, 31
	s_lshl_b64 s[20:21], s[14:15], 20
	s_add_u32 s20, s49, s20
	s_addc_u32 s21, s50, s21
	s_and_b64 s[46:47], s[4:5], exec
	s_cselect_b32 s15, s21, s45
	s_cselect_b32 s66, s20, s44
	s_add_u32 s30, s30, 0x80080
	s_addc_u32 s31, s31, 0
	s_add_u32 s68, s44, 0x100
	v_mov_b32_e32 v0, 0
	s_addc_u32 s69, s45, 0
	s_mov_b32 s70, -2
	v_mov_b64_e32 v[0:1], 0
	v_mov_b64_e32 v[2:3], 0
	v_mov_b64_e32 v[4:5], 0
	v_mov_b64_e32 v[6:7], 0
	v_mov_b64_e32 v[8:9], 0
	v_mov_b64_e32 v[10:11], 0
	v_mov_b64_e32 v[12:13], 0
	v_mov_b64_e32 v[14:15], 0
	v_mov_b64_e32 v[16:17], 0
	v_mov_b64_e32 v[18:19], 0
	v_mov_b64_e32 v[20:21], 0
	v_mov_b64_e32 v[22:23], 0
	v_mov_b64_e32 v[24:25], 0
	v_mov_b64_e32 v[26:27], 0
	v_mov_b64_e32 v[28:29], 0
	v_mov_b64_e32 v[30:31], 0
	v_mov_b64_e32 v[32:33], 0
	v_mov_b64_e32 v[34:35], 0
	v_mov_b64_e32 v[36:37], 0
	v_mov_b64_e32 v[38:39], 0
	v_mov_b64_e32 v[40:41], 0
	v_mov_b64_e32 v[42:43], 0
	v_mov_b64_e32 v[44:45], 0
	v_mov_b64_e32 v[46:47], 0
	v_mov_b64_e32 v[48:49], 0
	v_mov_b64_e32 v[50:51], 0
	v_mov_b64_e32 v[52:53], 0
	v_mov_b64_e32 v[54:55], 0
	v_mov_b64_e32 v[56:57], 0
	v_mov_b64_e32 v[58:59], 0
	v_mov_b64_e32 v[60:61], 0
	v_mov_b64_e32 v[62:63], 0
	v_mov_b64_e32 v[64:65], 0
	v_mov_b64_e32 v[66:67], 0
	v_mov_b64_e32 v[68:69], 0
	v_mov_b64_e32 v[70:71], 0
	v_mov_b64_e32 v[72:73], 0
	v_mov_b64_e32 v[74:75], 0
	v_mov_b64_e32 v[76:77], 0
	v_mov_b64_e32 v[78:79], 0
	v_mov_b64_e32 v[80:81], 0
	v_mov_b64_e32 v[82:83], 0
	v_mov_b64_e32 v[84:85], 0
	v_mov_b64_e32 v[86:87], 0
	v_mov_b64_e32 v[88:89], 0
	v_mov_b64_e32 v[90:91], 0
	v_mov_b64_e32 v[92:93], 0
	v_mov_b64_e32 v[94:95], 0
	v_mov_b64_e32 v[96:97], 0
	v_mov_b64_e32 v[98:99], 0
	v_mov_b64_e32 v[100:101], 0
	v_mov_b64_e32 v[102:103], 0
	v_mov_b64_e32 v[104:105], 0
	v_mov_b64_e32 v[106:107], 0
	v_mov_b64_e32 v[108:109], 0
	v_mov_b64_e32 v[110:111], 0
	v_mov_b64_e32 v[112:113], 0
	v_mov_b64_e32 v[114:115], 0
	v_mov_b64_e32 v[116:117], 0
	v_mov_b64_e32 v[118:119], 0
	v_mov_b64_e32 v[120:121], 0
	v_mov_b64_e32 v[122:123], 0
	v_mov_b64_e32 v[124:125], 0
	v_mov_b64_e32 v[126:127], 0
.LBB0_233:
	ds_read_b128 v[150:153], v147
	ds_read_b128 v[154:157], v147 offset:1024
	ds_read_b128 v[158:161], v147 offset:2048
	ds_read_b128 v[162:165], v147 offset:3072
	ds_read_b128 v[166:169], v148
	ds_read_b128 v[170:173], v148 offset:1024
	ds_read_b128 v[174:177], v148 offset:2048
	ds_read_b128 v[178:181], v148 offset:3072
	s_add_u32 s44, s30, 0xfff80080
	s_addc_u32 s45, s31, -1
	s_cmp_eq_u32 s70, 28
	s_cselect_b32 s47, s17, s45
	s_cselect_b32 s46, s43, s44
	s_cselect_b32 s45, s15, s69
	s_cselect_b32 s44, s66, s68
	s_add_i32 m0, s29, 0xc000
	ds_read_b128 v[182:185], v149
	ds_read_b128 v[186:189], v149 offset:1024
	ds_read_b128 v[190:193], v149 offset:2048
	ds_read_b128 v[194:197], v149 offset:3072
	ds_read_b128 v[198:201], v149 offset:4096
	ds_read_b128 v[202:205], v149 offset:5120
	ds_read_b128 v[206:209], v149 offset:6144
	ds_read_b128 v[210:213], v149 offset:7168
	global_load_lds_dwordx4 v136, s[30:31]
	s_add_i32 m0, s29, 0xe000
	s_nop 0
	global_load_lds_dwordx4 v138, s[30:31]
	s_waitcnt vmcnt(8) lgkmcnt(0)
	s_setprio 1
	s_barrier
	v_mfma_f32_16x16x32_bf16 v[124:127], v[150:153], v[182:185], v[124:127]
	v_mfma_f32_16x16x32_bf16 v[120:123], v[158:161], v[182:185], v[120:123]
	v_mfma_f32_16x16x32_bf16 v[108:111], v[150:153], v[190:193], v[108:111]
	v_mfma_f32_16x16x32_bf16 v[104:107], v[158:161], v[190:193], v[104:107]
	v_mfma_f32_16x16x32_bf16 v[92:95], v[150:153], v[198:201], v[92:95]
	v_mfma_f32_16x16x32_bf16 v[88:91], v[158:161], v[198:201], v[88:91]
	v_mfma_f32_16x16x32_bf16 v[76:79], v[150:153], v[206:209], v[76:79]
	v_mfma_f32_16x16x32_bf16 v[72:75], v[158:161], v[206:209], v[72:75]
	v_mfma_f32_16x16x32_bf16 v[124:127], v[154:157], v[186:189], v[124:127]
	v_mfma_f32_16x16x32_bf16 v[120:123], v[162:165], v[186:189], v[120:123]
	v_mfma_f32_16x16x32_bf16 v[108:111], v[154:157], v[194:197], v[108:111]
	v_mfma_f32_16x16x32_bf16 v[104:107], v[162:165], v[194:197], v[104:107]
	v_mfma_f32_16x16x32_bf16 v[92:95], v[154:157], v[202:205], v[92:95]
	v_mfma_f32_16x16x32_bf16 v[88:91], v[162:165], v[202:205], v[88:91]
	v_mfma_f32_16x16x32_bf16 v[76:79], v[154:157], v[210:213], v[76:79]
	v_mfma_f32_16x16x32_bf16 v[72:75], v[162:165], v[210:213], v[72:75]
	v_mfma_f32_16x16x32_bf16 v[116:119], v[166:169], v[182:185], v[116:119]
	v_mfma_f32_16x16x32_bf16 v[112:115], v[174:177], v[182:185], v[112:115]
	v_mfma_f32_16x16x32_bf16 v[100:103], v[166:169], v[190:193], v[100:103]
	v_mfma_f32_16x16x32_bf16 v[96:99], v[174:177], v[190:193], v[96:99]
	v_mfma_f32_16x16x32_bf16 v[84:87], v[166:169], v[198:201], v[84:87]
	v_mfma_f32_16x16x32_bf16 v[80:83], v[174:177], v[198:201], v[80:83]
	v_mfma_f32_16x16x32_bf16 v[68:71], v[166:169], v[206:209], v[68:71]
	v_mfma_f32_16x16x32_bf16 v[64:67], v[174:177], v[206:209], v[64:67]
	v_mfma_f32_16x16x32_bf16 v[116:119], v[170:173], v[186:189], v[116:119]
	v_mfma_f32_16x16x32_bf16 v[112:115], v[178:181], v[186:189], v[112:115]
	v_mfma_f32_16x16x32_bf16 v[100:103], v[170:173], v[194:197], v[100:103]
	v_mfma_f32_16x16x32_bf16 v[96:99], v[178:181], v[194:197], v[96:99]
	v_mfma_f32_16x16x32_bf16 v[84:87], v[170:173], v[202:205], v[84:87]
	v_mfma_f32_16x16x32_bf16 v[80:83], v[178:181], v[202:205], v[80:83]
	v_mfma_f32_16x16x32_bf16 v[68:71], v[170:173], v[210:213], v[68:71]
	s_setprio 0
	v_mfma_f32_16x16x32_bf16 v[64:67], v[178:181], v[210:213], v[64:67]
	s_barrier
; #define PG8_STAGE(bufoff, gbase, voff) do { _Pragma("unroll") for (int _i = 0; _i < 2; ++_i) \
;         __builtin_amdgcn_global_load_lds((const unsigned*)((const char*)(gbase) + (voff)[_i]), (LAS unsigned*)(lds + (bufoff) + ldsw + _i * 8192), 16, 0, 0); } while (0)
; #define PG8_LDA(dst, b, h) do { _Pragma("unroll") for (int m = 0; m < 4; ++m) _Pragma("unroll") for (int k = 0; k < 2; ++k) dst[m][k] = *(const LAS bf16x8*)(lds + PG8_SA(b, h) + aoff + m * 2048 + k * 1024); } while (0)
; #define PG8_LDB(dst, b, h) do { _Pragma("unroll") for (int n = 0; n < 2; ++n) _Pragma("unroll") for (int k = 0; k < 2; ++k) dst[n][k] = *(const LAS bf16x8*)(lds + PG8_SB(b, h) + boff + n * 2048 + k * 1024); } while (0)
; #define PG8_WAIT_V(n) asm volatile("s_waitcnt vmcnt(" #n ")" ::: "memory")
; #define PG8_WAIT_L(n) asm volatile("s_waitcnt lgkmcnt(" #n ")" ::: "memory")
; #define PG8_BAR __builtin_amdgcn_s_barrier()
; #define PG8_SCHED __builtin_amdgcn_sched_barrier(0)
; template <class Epi, bool FP8 = false>
; __device__ __forceinline__ void gemm_phase(LAS unsigned char* lds, const Gemm g, const StaticOrder& S_, const Epi& E, const int tid) {
;     ...
;             PG8_LDA(At, 0, 1); PG8_STAGE(PG8_SB(0, 0), b2, voffB); PG8_STAGE(PG8_SB(0, 1), b2 + hstepB, voffB); PG8_STAGE(PG8_SA(0, 0), a2, voffA);
;             PG8_WAIT_V(8); PG8_WAIT_L(0); PG8_BAR; PG8_MMA(1, 0, At, B0); PG8_MMA(1, 1, At, B1); PG8_BAR; PG8_SCHED;
;             PG8_LDB(B0, 1, 0); PG8_LDB(B1, 1, 1); PG8_SCHED; PG8_LDA(At, 1, 0); PG8_STAGE(PG8_SA(0, 1), a2 + hstepA, voffA);
;             PG8_WAIT_V(8); PG8_WAIT_L(0); PG8_BAR; PG8_MMA(0, 0, At, B0); PG8_MMA(0, 1, At, B1); PG8_BAR; PG8_SCHED;
	s_add_u32 s98, s44, s10
	s_addc_u32 s99, s45, s11
	s_add_u32 s100, s46, s10
	s_addc_u32 s101, s47, s11
	s_add_i32 s71, s61, s51
	s_mov_b32 m0, s71
	ds_read_b128 v[182:185], v149 offset:16384
	ds_read_b128 v[186:189], v149 offset:17408
	ds_read_b128 v[190:193], v149 offset:18432
	ds_read_b128 v[194:197], v149 offset:19456
	ds_read_b128 v[198:201], v149 offset:20480
	ds_read_b128 v[202:205], v149 offset:21504
	ds_read_b128 v[206:209], v149 offset:22528
	ds_read_b128 v[210:213], v149 offset:23552
	global_load_lds_dwordx4 v128, s[44:45]
	s_add_i32 m0, s71, 0x2000
	s_add_u32 s72, s44, 0x80000
	s_addc_u32 s73, s45, 0
	s_add_i32 s71, s62, s51
	global_load_lds_dwordx4 v130, s[44:45]
	s_mov_b32 m0, s71
	s_nop 0
	global_load_lds_dwordx4 v128, s[72:73]
	s_add_i32 m0, s71, 0x2000
	s_nop 0
	global_load_lds_dwordx4 v130, s[72:73]
	s_mov_b32 m0, s29
	s_nop 0
	global_load_lds_dwordx4 v134, s[46:47]
	s_mov_b32 m0, s54
	s_nop 0
	global_load_lds_dwordx4 v132, s[46:47]
	s_waitcnt vmcnt(8) lgkmcnt(0)
	s_setprio 1
	s_barrier
	v_mfma_f32_16x16x32_bf16 v[60:63], v[150:153], v[182:185], v[60:63]
	v_mfma_f32_16x16x32_bf16 v[56:59], v[158:161], v[182:185], v[56:59]
	v_mfma_f32_16x16x32_bf16 v[44:47], v[150:153], v[190:193], v[44:47]
	v_mfma_f32_16x16x32_bf16 v[40:43], v[158:161], v[190:193], v[40:43]
	v_mfma_f32_16x16x32_bf16 v[28:31], v[150:153], v[198:201], v[28:31]
	v_mfma_f32_16x16x32_bf16 v[24:27], v[158:161], v[198:201], v[24:27]
	v_mfma_f32_16x16x32_bf16 v[12:15], v[150:153], v[206:209], v[12:15]
	v_mfma_f32_16x16x32_bf16 v[8:11], v[158:161], v[206:209], v[8:11]
	v_mfma_f32_16x16x32_bf16 v[60:63], v[154:157], v[186:189], v[60:63]
	v_mfma_f32_16x16x32_bf16 v[56:59], v[162:165], v[186:189], v[56:59]
	v_mfma_f32_16x16x32_bf16 v[44:47], v[154:157], v[194:197], v[44:47]
	v_mfma_f32_16x16x32_bf16 v[40:43], v[162:165], v[194:197], v[40:43]
	v_mfma_f32_16x16x32_bf16 v[28:31], v[154:157], v[202:205], v[28:31]
	v_mfma_f32_16x16x32_bf16 v[24:27], v[162:165], v[202:205], v[24:27]
	v_mfma_f32_16x16x32_bf16 v[12:15], v[154:157], v[210:213], v[12:15]
	v_mfma_f32_16x16x32_bf16 v[8:11], v[162:165], v[210:213], v[8:11]
	v_mfma_f32_16x16x32_bf16 v[52:55], v[166:169], v[182:185], v[52:55]
	v_mfma_f32_16x16x32_bf16 v[48:51], v[174:177], v[182:185], v[48:51]
	v_mfma_f32_16x16x32_bf16 v[36:39], v[166:169], v[190:193], v[36:39]
	v_mfma_f32_16x16x32_bf16 v[32:35], v[174:177], v[190:193], v[32:35]
	v_mfma_f32_16x16x32_bf16 v[20:23], v[166:169], v[198:201], v[20:23]
	v_mfma_f32_16x16x32_bf16 v[16:19], v[174:177], v[198:201], v[16:19]
	v_mfma_f32_16x16x32_bf16 v[4:7], v[166:169], v[206:209], v[4:7]
	v_mfma_f32_16x16x32_bf16 v[0:3], v[174:177], v[206:209], v[0:3]
	v_mfma_f32_16x16x32_bf16 v[52:55], v[170:173], v[186:189], v[52:55]
	v_mfma_f32_16x16x32_bf16 v[48:51], v[178:181], v[186:189], v[48:51]
	v_mfma_f32_16x16x32_bf16 v[36:39], v[170:173], v[194:197], v[36:39]
	v_mfma_f32_16x16x32_bf16 v[32:35], v[178:181], v[194:197], v[32:35]
	v_mfma_f32_16x16x32_bf16 v[20:23], v[170:173], v[202:205], v[20:23]
	v_mfma_f32_16x16x32_bf16 v[16:19], v[178:181], v[202:205], v[16:19]
	v_mfma_f32_16x16x32_bf16 v[4:7], v[170:173], v[210:213], v[4:7]
	s_setprio 0
	v_mfma_f32_16x16x32_bf16 v[0:3], v[178:181], v[210:213], v[0:3]
	s_barrier
	s_add_i32 s71, 0, 0x18000
	s_add_i32 s72, 0, 0x1c000
	v_add_u32_e32 v162, s71, v145
	v_add_u32_e32 v178, s72, v145
	ds_read_b128 v[150:153], v162
	ds_read_b128 v[154:157], v162 offset:1024
	ds_read_b128 v[158:161], v162 offset:2048
	ds_read_b128 v[162:165], v162 offset:3072
	ds_read_b128 v[166:169], v178
	ds_read_b128 v[170:173], v178 offset:1024
	ds_read_b128 v[174:177], v178 offset:2048
	ds_read_b128 v[178:181], v178 offset:3072
	s_add_u32 s46, s46, 0x80000
	s_addc_u32 s47, s47, 0
	s_mov_b32 m0, s55
	ds_read_b128 v[182:185], v149 offset:32768
	ds_read_b128 v[186:189], v149 offset:33792
	ds_read_b128 v[190:193], v149 offset:34816
	ds_read_b128 v[194:197], v149 offset:35840
	ds_read_b128 v[198:201], v149 offset:36864
	ds_read_b128 v[202:205], v149 offset:37888
	ds_read_b128 v[206:209], v149 offset:38912
	ds_read_b128 v[210:213], v149 offset:39936
	global_load_lds_dwordx4 v134, s[46:47]
	s_mov_b32 m0, s56
	s_nop 0
	global_load_lds_dwordx4 v132, s[46:47]
	s_waitcnt vmcnt(8) lgkmcnt(0)
	s_setprio 1
	s_barrier
; #define PG8_STAGE(bufoff, gbase, voff) do { _Pragma("unroll") for (int _i = 0; _i < 2; ++_i) \
;         __builtin_amdgcn_global_load_lds((const unsigned*)((const char*)(gbase) + (voff)[_i]), (LAS unsigned*)(lds + (bufoff) + ldsw + _i * 8192), 16, 0, 0); } while (0)
; #define PG8_LDA(dst, b, h) do { _Pragma("unroll") for (int m = 0; m < 4; ++m) _Pragma("unroll") for (int k = 0; k < 2; ++k) dst[m][k] = *(const LAS bf16x8*)(lds + PG8_SA(b, h) + aoff + m * 2048 + k * 1024); } while (0)
; #define PG8_WAIT_V(n) asm volatile("s_waitcnt vmcnt(" #n ")" ::: "memory")
; #define PG8_WAIT_L(n) asm volatile("s_waitcnt lgkmcnt(" #n ")" ::: "memory")
; #define PG8_BAR __builtin_amdgcn_s_barrier()
; #define PG8_SCHED __builtin_amdgcn_sched_barrier(0)
; template <class Epi, bool FP8 = false>
; __device__ __forceinline__ void gemm_phase(LAS unsigned char* lds, const Gemm g, const StaticOrder& S_, const Epi& E, const int tid) {
;     ...
;             PG8_WAIT_V(8); PG8_WAIT_L(0); PG8_BAR; PG8_MMA(0, 0, At, B0); PG8_MMA(0, 1, At, B1); PG8_BAR; PG8_SCHED;
;             PG8_LDA(At, 1, 1); PG8_STAGE(PG8_SB(1, 0), b3, voffB); PG8_STAGE(PG8_SB(1, 1), b3 + hstepB, voffB); PG8_STAGE(PG8_SA(1, 0), a3, voffA);
;             PG8_WAIT_V(8); PG8_WAIT_L(0); PG8_BAR; PG8_MMA(1, 0, At, B0); PG8_MMA(1, 1, At, B1); PG8_BAR; PG8_SCHED;
;         }
;         if (wr == 0) PG8_BAR;
	v_mfma_f32_16x16x32_bf16 v[124:127], v[150:153], v[182:185], v[124:127]
	v_mfma_f32_16x16x32_bf16 v[120:123], v[158:161], v[182:185], v[120:123]
	v_mfma_f32_16x16x32_bf16 v[108:111], v[150:153], v[190:193], v[108:111]
	v_mfma_f32_16x16x32_bf16 v[104:107], v[158:161], v[190:193], v[104:107]
	v_mfma_f32_16x16x32_bf16 v[92:95], v[150:153], v[198:201], v[92:95]
	v_mfma_f32_16x16x32_bf16 v[88:91], v[158:161], v[198:201], v[88:91]
	v_mfma_f32_16x16x32_bf16 v[76:79], v[150:153], v[206:209], v[76:79]
	v_mfma_f32_16x16x32_bf16 v[72:75], v[158:161], v[206:209], v[72:75]
	v_mfma_f32_16x16x32_bf16 v[124:127], v[154:157], v[186:189], v[124:127]
	v_mfma_f32_16x16x32_bf16 v[120:123], v[162:165], v[186:189], v[120:123]
	v_mfma_f32_16x16x32_bf16 v[108:111], v[154:157], v[194:197], v[108:111]
	v_mfma_f32_16x16x32_bf16 v[104:107], v[162:165], v[194:197], v[104:107]
	v_mfma_f32_16x16x32_bf16 v[92:95], v[154:157], v[202:205], v[92:95]
	v_mfma_f32_16x16x32_bf16 v[88:91], v[162:165], v[202:205], v[88:91]
	v_mfma_f32_16x16x32_bf16 v[76:79], v[154:157], v[210:213], v[76:79]
	v_mfma_f32_16x16x32_bf16 v[72:75], v[162:165], v[210:213], v[72:75]
	v_mfma_f32_16x16x32_bf16 v[116:119], v[166:169], v[182:185], v[116:119]
	v_mfma_f32_16x16x32_bf16 v[112:115], v[174:177], v[182:185], v[112:115]
	v_mfma_f32_16x16x32_bf16 v[100:103], v[166:169], v[190:193], v[100:103]
	v_mfma_f32_16x16x32_bf16 v[96:99], v[174:177], v[190:193], v[96:99]
	v_mfma_f32_16x16x32_bf16 v[84:87], v[166:169], v[198:201], v[84:87]
	v_mfma_f32_16x16x32_bf16 v[80:83], v[174:177], v[198:201], v[80:83]
	v_mfma_f32_16x16x32_bf16 v[68:71], v[166:169], v[206:209], v[68:71]
	v_mfma_f32_16x16x32_bf16 v[64:67], v[174:177], v[206:209], v[64:67]
	v_mfma_f32_16x16x32_bf16 v[116:119], v[170:173], v[186:189], v[116:119]
	v_mfma_f32_16x16x32_bf16 v[112:115], v[178:181], v[186:189], v[112:115]
	v_mfma_f32_16x16x32_bf16 v[100:103], v[170:173], v[194:197], v[100:103]
	v_mfma_f32_16x16x32_bf16 v[96:99], v[178:181], v[194:197], v[96:99]
	v_mfma_f32_16x16x32_bf16 v[84:87], v[170:173], v[202:205], v[84:87]
	v_mfma_f32_16x16x32_bf16 v[80:83], v[178:181], v[202:205], v[80:83]
	v_mfma_f32_16x16x32_bf16 v[68:71], v[170:173], v[210:213], v[68:71]
	s_setprio 0
	v_mfma_f32_16x16x32_bf16 v[64:67], v[178:181], v[210:213], v[64:67]
	s_barrier
	s_add_i32 s46, s71, s51
	s_mov_b32 m0, s46
	ds_read_b128 v[182:185], v149 offset:49152
	ds_read_b128 v[186:189], v149 offset:50176
	ds_read_b128 v[190:193], v149 offset:51200
	ds_read_b128 v[194:197], v149 offset:52224
	ds_read_b128 v[198:201], v149 offset:53248
	ds_read_b128 v[202:205], v149 offset:54272
	ds_read_b128 v[206:209], v149 offset:55296
	ds_read_b128 v[210:213], v149 offset:56320
	global_load_lds_dwordx4 v128, s[98:99]
	s_add_i32 m0, s46, 0x2000
	s_add_u32 s44, s44, 0x80080
	s_addc_u32 s45, s45, 0
	s_add_i32 s46, s72, s51
	global_load_lds_dwordx4 v130, s[98:99]
	s_mov_b32 m0, s46
	s_nop 0
	global_load_lds_dwordx4 v128, s[44:45]
	s_add_i32 m0, s46, 0x2000
	s_nop 0
	global_load_lds_dwordx4 v130, s[44:45]
	s_mov_b32 m0, s58
	s_nop 0
	global_load_lds_dwordx4 v134, s[100:101]
	s_mov_b32 m0, s59
	s_nop 0
	global_load_lds_dwordx4 v132, s[100:101]
	s_waitcnt vmcnt(8) lgkmcnt(0)
	s_setprio 1
	s_barrier
	v_mfma_f32_16x16x32_bf16 v[60:63], v[150:153], v[182:185], v[60:63]
	v_mfma_f32_16x16x32_bf16 v[56:59], v[158:161], v[182:185], v[56:59]
	v_mfma_f32_16x16x32_bf16 v[44:47], v[150:153], v[190:193], v[44:47]
	v_mfma_f32_16x16x32_bf16 v[40:43], v[158:161], v[190:193], v[40:43]
	v_mfma_f32_16x16x32_bf16 v[28:31], v[150:153], v[198:201], v[28:31]
	v_mfma_f32_16x16x32_bf16 v[24:27], v[158:161], v[198:201], v[24:27]
	v_mfma_f32_16x16x32_bf16 v[12:15], v[150:153], v[206:209], v[12:15]
	v_mfma_f32_16x16x32_bf16 v[8:11], v[158:161], v[206:209], v[8:11]
	v_mfma_f32_16x16x32_bf16 v[60:63], v[154:157], v[186:189], v[60:63]
	v_mfma_f32_16x16x32_bf16 v[56:59], v[162:165], v[186:189], v[56:59]
	v_mfma_f32_16x16x32_bf16 v[44:47], v[154:157], v[194:197], v[44:47]
	v_mfma_f32_16x16x32_bf16 v[40:43], v[162:165], v[194:197], v[40:43]
	v_mfma_f32_16x16x32_bf16 v[28:31], v[154:157], v[202:205], v[28:31]
	v_mfma_f32_16x16x32_bf16 v[24:27], v[162:165], v[202:205], v[24:27]
	v_mfma_f32_16x16x32_bf16 v[12:15], v[154:157], v[210:213], v[12:15]
	v_mfma_f32_16x16x32_bf16 v[8:11], v[162:165], v[210:213], v[8:11]
	v_mfma_f32_16x16x32_bf16 v[52:55], v[166:169], v[182:185], v[52:55]
	v_mfma_f32_16x16x32_bf16 v[48:51], v[174:177], v[182:185], v[48:51]
	v_mfma_f32_16x16x32_bf16 v[36:39], v[166:169], v[190:193], v[36:39]
	v_mfma_f32_16x16x32_bf16 v[32:35], v[174:177], v[190:193], v[32:35]
	v_mfma_f32_16x16x32_bf16 v[20:23], v[166:169], v[198:201], v[20:23]
	v_mfma_f32_16x16x32_bf16 v[16:19], v[174:177], v[198:201], v[16:19]
	v_mfma_f32_16x16x32_bf16 v[4:7], v[166:169], v[206:209], v[4:7]
	v_mfma_f32_16x16x32_bf16 v[0:3], v[174:177], v[206:209], v[0:3]
	v_mfma_f32_16x16x32_bf16 v[52:55], v[170:173], v[186:189], v[52:55]
	v_mfma_f32_16x16x32_bf16 v[48:51], v[178:181], v[186:189], v[48:51]
	v_mfma_f32_16x16x32_bf16 v[36:39], v[170:173], v[194:197], v[36:39]
	v_mfma_f32_16x16x32_bf16 v[32:35], v[178:181], v[194:197], v[32:35]
	v_mfma_f32_16x16x32_bf16 v[20:23], v[170:173], v[202:205], v[20:23]
	v_mfma_f32_16x16x32_bf16 v[16:19], v[178:181], v[202:205], v[16:19]
	v_mfma_f32_16x16x32_bf16 v[4:7], v[170:173], v[210:213], v[4:7]
	s_setprio 0
	v_mfma_f32_16x16x32_bf16 v[0:3], v[178:181], v[210:213], v[0:3]
	s_barrier
	s_add_i32 s70, s70, 2
	s_add_u32 s30, s30, 0x100
	s_addc_u32 s31, s31, 0
	s_add_u32 s68, s68, 0x100
	s_addc_u32 s69, s69, 0
	s_cmp_gt_u32 s70, 29
	s_cbranch_scc0 .LBB0_233
	s_and_b64 vcc, exec, s[12:13]
	s_cbranch_vccz .LBB0_236
	s_barrier

; #define PG8_STAGE(bufoff, gbase, voff) do { _Pragma("unroll") for (int _i = 0; _i < 2; ++_i) \
;         __builtin_amdgcn_global_load_lds((const unsigned*)((const char*)(gbase) + (voff)[_i]), (LAS unsigned*)(lds + (bufoff) + ldsw + _i * 8192), 16, 0, 0); } while (0)
; #define PG8_LDA(dst, b, h) do { _Pragma("unroll") for (int m = 0; m < 4; ++m) _Pragma("unroll") for (int k = 0; k < 2; ++k) dst[m][k] = *(const LAS bf16x8*)(lds + PG8_SA(b, h) + aoff + m * 2048 + k * 1024); } while (0)
; #define PG8_LDB(dst, b, h) do { _Pragma("unroll") for (int n = 0; n < 2; ++n) _Pragma("unroll") for (int k = 0; k < 2; ++k) dst[n][k] = *(const LAS bf16x8*)(lds + PG8_SB(b, h) + boff + n * 2048 + k * 1024); } while (0)
; #define PG8_WAIT_V(n) asm volatile("s_waitcnt vmcnt(" #n ")" ::: "memory")
; #define PG8_WAIT_L(n) asm volatile("s_waitcnt lgkmcnt(" #n ")" ::: "memory")
; #define PG8_BAR __builtin_amdgcn_s_barrier()
; #define PG8_SCHED __builtin_amdgcn_sched_barrier(0)
; template <class Epi, bool FP8 = false>
; __device__ __forceinline__ void gemm_phase(LAS unsigned char* lds, const Gemm g, const StaticOrder& S_, const Epi& E, const int tid) {
;     ...
;             PG8_LDB(B0, 0, 0); PG8_LDB(B1, 0, 1); PG8_SCHED; PG8_LDA(At, 0, 0); PG8_STAGE(PG8_SA(1, 1), a1 + hstepA, voffA);
;             PG8_WAIT_V(8); PG8_WAIT_L(0); PG8_BAR; PG8_MMA(0, 0, At, B0); PG8_MMA(0, 1, At, B1); PG8_BAR; PG8_SCHED;
;     ...
;         for (int a = 0; a < 2; ++a)
; #pragma unroll
;             for (int b = 0; b < 2; ++b)
; #pragma unroll
;                 for (int m = 0; m < 4; ++m)
; #pragma unroll
;                     for (int n = 0; n < 2; ++n) acc[a][b][m][n] = (f32x4){0.f, 0.f, 0.f, 0.f};
;         cur = nxt; cA = nA; cB = nB; ++ui;
.LBB0_318:
	s_add_u32 s75, s50, 0x100
	v_mov_b32_e32 v0, 0
	s_addc_u32 s76, s51, 0
	s_mov_b32 s77, -2
	v_mov_b64_e32 v[0:1], 0
	v_mov_b64_e32 v[2:3], 0
	v_mov_b64_e32 v[4:5], 0
	v_mov_b64_e32 v[6:7], 0
	v_mov_b64_e32 v[8:9], 0
	v_mov_b64_e32 v[10:11], 0
	v_mov_b64_e32 v[12:13], 0
	v_mov_b64_e32 v[14:15], 0
	v_mov_b64_e32 v[16:17], 0
	v_mov_b64_e32 v[18:19], 0
	v_mov_b64_e32 v[20:21], 0
	v_mov_b64_e32 v[22:23], 0
	v_mov_b64_e32 v[24:25], 0
	v_mov_b64_e32 v[26:27], 0
	v_mov_b64_e32 v[28:29], 0
	v_mov_b64_e32 v[30:31], 0
	v_mov_b64_e32 v[32:33], 0
	v_mov_b64_e32 v[34:35], 0
	v_mov_b64_e32 v[36:37], 0
	v_mov_b64_e32 v[38:39], 0
	v_mov_b64_e32 v[40:41], 0
	v_mov_b64_e32 v[42:43], 0
	v_mov_b64_e32 v[44:45], 0
	v_mov_b64_e32 v[46:47], 0
	v_mov_b64_e32 v[48:49], 0
	v_mov_b64_e32 v[50:51], 0
	v_mov_b64_e32 v[52:53], 0
	v_mov_b64_e32 v[54:55], 0
	v_mov_b64_e32 v[56:57], 0
	v_mov_b64_e32 v[58:59], 0
	v_mov_b64_e32 v[60:61], 0
	v_mov_b64_e32 v[62:63], 0
	v_mov_b64_e32 v[64:65], 0
	v_mov_b64_e32 v[66:67], 0
	v_mov_b64_e32 v[68:69], 0
	v_mov_b64_e32 v[70:71], 0
	v_mov_b64_e32 v[72:73], 0
	v_mov_b64_e32 v[74:75], 0
	v_mov_b64_e32 v[76:77], 0
	v_mov_b64_e32 v[78:79], 0
	v_mov_b64_e32 v[80:81], 0
	v_mov_b64_e32 v[82:83], 0
	v_mov_b64_e32 v[84:85], 0
	v_mov_b64_e32 v[86:87], 0
	v_mov_b64_e32 v[88:89], 0
	v_mov_b64_e32 v[90:91], 0
	v_mov_b64_e32 v[92:93], 0
	v_mov_b64_e32 v[94:95], 0
	v_mov_b64_e32 v[96:97], 0
	v_mov_b64_e32 v[98:99], 0
	v_mov_b64_e32 v[100:101], 0
	v_mov_b64_e32 v[102:103], 0
	v_mov_b64_e32 v[104:105], 0
	v_mov_b64_e32 v[106:107], 0
	v_mov_b64_e32 v[108:109], 0
	v_mov_b64_e32 v[110:111], 0
	v_mov_b64_e32 v[112:113], 0
	v_mov_b64_e32 v[114:115], 0
	v_mov_b64_e32 v[116:117], 0
	v_mov_b64_e32 v[118:119], 0
	v_mov_b64_e32 v[120:121], 0
	v_mov_b64_e32 v[122:123], 0
	v_mov_b64_e32 v[124:125], 0
	v_mov_b64_e32 v[126:127], 0
.LBB0_319:
	ds_read_b128 v[150:153], v146
	ds_read_b128 v[154:157], v146 offset:1024
	ds_read_b128 v[158:161], v146 offset:2048
	ds_read_b128 v[162:165], v146 offset:3072
	ds_read_b128 v[166:169], v147
	ds_read_b128 v[170:173], v147 offset:1024
	ds_read_b128 v[174:177], v147 offset:2048
	ds_read_b128 v[178:181], v147 offset:3072
	s_add_u32 s50, s48, 0x100
	s_addc_u32 s51, s49, 0
	s_cmpk_eq_i32 s77, 0x54
	s_cselect_b32 s55, s7, s51
	s_cselect_b32 s54, s6, s50
	s_cselect_b32 s53, s45, s76
	s_cselect_b32 s52, s44, s75
	s_add_i32 m0, s60, 0xc000
	ds_read_b128 v[182:185], v148
	ds_read_b128 v[186:189], v148 offset:1024
	ds_read_b128 v[190:193], v148 offset:2048
	ds_read_b128 v[194:197], v148 offset:3072
	ds_read_b128 v[198:201], v148 offset:4096
	ds_read_b128 v[202:205], v148 offset:5120
	ds_read_b128 v[206:209], v148 offset:6144
	ds_read_b128 v[210:213], v148 offset:7168
	global_load_lds_dwordx4 v132, s[48:49]
	s_add_i32 m0, s60, 0xe000
	s_nop 0
	global_load_lds_dwordx4 v134, s[48:49]
	s_waitcnt vmcnt(8) lgkmcnt(0)
	s_setprio 1
	s_barrier
	v_mfma_f32_16x16x32_bf16 v[124:127], v[150:153], v[182:185], v[124:127]
	v_mfma_f32_16x16x32_bf16 v[120:123], v[158:161], v[182:185], v[120:123]
	v_mfma_f32_16x16x32_bf16 v[112:115], v[150:153], v[190:193], v[112:115]
	v_mfma_f32_16x16x32_bf16 v[104:107], v[158:161], v[190:193], v[104:107]
	v_mfma_f32_16x16x32_bf16 v[96:99], v[150:153], v[198:201], v[96:99]
	v_mfma_f32_16x16x32_bf16 v[88:91], v[158:161], v[198:201], v[88:91]
	v_mfma_f32_16x16x32_bf16 v[80:83], v[150:153], v[206:209], v[80:83]
	v_mfma_f32_16x16x32_bf16 v[72:75], v[158:161], v[206:209], v[72:75]
	v_mfma_f32_16x16x32_bf16 v[124:127], v[154:157], v[186:189], v[124:127]
	v_mfma_f32_16x16x32_bf16 v[120:123], v[162:165], v[186:189], v[120:123]
	v_mfma_f32_16x16x32_bf16 v[112:115], v[154:157], v[194:197], v[112:115]
	v_mfma_f32_16x16x32_bf16 v[104:107], v[162:165], v[194:197], v[104:107]
	v_mfma_f32_16x16x32_bf16 v[96:99], v[154:157], v[202:205], v[96:99]
	v_mfma_f32_16x16x32_bf16 v[88:91], v[162:165], v[202:205], v[88:91]
	v_mfma_f32_16x16x32_bf16 v[80:83], v[154:157], v[210:213], v[80:83]
	v_mfma_f32_16x16x32_bf16 v[72:75], v[162:165], v[210:213], v[72:75]
	v_mfma_f32_16x16x32_bf16 v[116:119], v[166:169], v[182:185], v[116:119]
	v_mfma_f32_16x16x32_bf16 v[108:111], v[174:177], v[182:185], v[108:111]
	v_mfma_f32_16x16x32_bf16 v[100:103], v[166:169], v[190:193], v[100:103]
	v_mfma_f32_16x16x32_bf16 v[92:95], v[174:177], v[190:193], v[92:95]
	v_mfma_f32_16x16x32_bf16 v[84:87], v[166:169], v[198:201], v[84:87]
	v_mfma_f32_16x16x32_bf16 v[76:79], v[174:177], v[198:201], v[76:79]
	v_mfma_f32_16x16x32_bf16 v[68:71], v[166:169], v[206:209], v[68:71]
	v_mfma_f32_16x16x32_bf16 v[64:67], v[174:177], v[206:209], v[64:67]
	v_mfma_f32_16x16x32_bf16 v[116:119], v[170:173], v[186:189], v[116:119]
	v_mfma_f32_16x16x32_bf16 v[108:111], v[178:181], v[186:189], v[108:111]
	v_mfma_f32_16x16x32_bf16 v[100:103], v[170:173], v[194:197], v[100:103]
	v_mfma_f32_16x16x32_bf16 v[92:95], v[178:181], v[194:197], v[92:95]
	v_mfma_f32_16x16x32_bf16 v[84:87], v[170:173], v[202:205], v[84:87]
	v_mfma_f32_16x16x32_bf16 v[76:79], v[178:181], v[202:205], v[76:79]
	v_mfma_f32_16x16x32_bf16 v[68:71], v[170:173], v[210:213], v[68:71]
	s_setprio 0
	v_mfma_f32_16x16x32_bf16 v[64:67], v[178:181], v[210:213], v[64:67]
	s_barrier
; #define PG8_STAGE(bufoff, gbase, voff) do { _Pragma("unroll") for (int _i = 0; _i < 2; ++_i) \
;         __builtin_amdgcn_global_load_lds((const unsigned*)((const char*)(gbase) + (voff)[_i]), (LAS unsigned*)(lds + (bufoff) + ldsw + _i * 8192), 16, 0, 0); } while (0)
; #define PG8_LDA(dst, b, h) do { _Pragma("unroll") for (int m = 0; m < 4; ++m) _Pragma("unroll") for (int k = 0; k < 2; ++k) dst[m][k] = *(const LAS bf16x8*)(lds + PG8_SA(b, h) + aoff + m * 2048 + k * 1024); } while (0)
; #define PG8_LDB(dst, b, h) do { _Pragma("unroll") for (int n = 0; n < 2; ++n) _Pragma("unroll") for (int k = 0; k < 2; ++k) dst[n][k] = *(const LAS bf16x8*)(lds + PG8_SB(b, h) + boff + n * 2048 + k * 1024); } while (0)
; #define PG8_WAIT_V(n) asm volatile("s_waitcnt vmcnt(" #n ")" ::: "memory")
; #define PG8_WAIT_L(n) asm volatile("s_waitcnt lgkmcnt(" #n ")" ::: "memory")
; #define PG8_BAR __builtin_amdgcn_s_barrier()
; #define PG8_SCHED __builtin_amdgcn_sched_barrier(0)
; template <class Epi, bool FP8 = false>
; __device__ __forceinline__ void gemm_phase(LAS unsigned char* lds, const Gemm g, const StaticOrder& S_, const Epi& E, const int tid) {
;     ...
;             PG8_LDA(At, 0, 1); PG8_STAGE(PG8_SB(0, 0), b2, voffB); PG8_STAGE(PG8_SB(0, 1), b2 + hstepB, voffB); PG8_STAGE(PG8_SA(0, 0), a2, voffA);
;             PG8_WAIT_V(8); PG8_WAIT_L(0); PG8_BAR; PG8_MMA(1, 0, At, B0); PG8_MMA(1, 1, At, B1); PG8_BAR; PG8_SCHED;
;             PG8_LDB(B0, 1, 0); PG8_LDB(B1, 1, 1); PG8_SCHED; PG8_LDA(At, 1, 0); PG8_STAGE(PG8_SA(0, 1), a2 + hstepA, voffA);
;             PG8_WAIT_V(8); PG8_WAIT_L(0); PG8_BAR; PG8_MMA(0, 0, At, B0); PG8_MMA(0, 1, At, B1); PG8_BAR; PG8_SCHED;
	s_add_u32 s98, s52, s14
	s_addc_u32 s99, s53, s15
	s_add_u32 s100, s54, s14
	s_addc_u32 s101, s55, s15
	s_add_i32 s48, s71, s59
	s_mov_b32 m0, s48
	ds_read_b128 v[182:185], v148 offset:16384
	ds_read_b128 v[186:189], v148 offset:17408
	ds_read_b128 v[190:193], v148 offset:18432
	ds_read_b128 v[194:197], v148 offset:19456
	ds_read_b128 v[198:201], v148 offset:20480
	ds_read_b128 v[202:205], v148 offset:21504
	ds_read_b128 v[206:209], v148 offset:22528
	ds_read_b128 v[210:213], v148 offset:23552
	global_load_lds_dwordx4 v128, s[52:53]
	s_add_i32 m0, s48, 0x2000
	s_add_u32 s48, s52, 0x160000
	s_addc_u32 s49, s53, 0
	s_add_i32 s78, s72, s59
	global_load_lds_dwordx4 v130, s[52:53]
	s_mov_b32 m0, s78
	s_nop 0
	global_load_lds_dwordx4 v128, s[48:49]
	s_add_i32 m0, s78, 0x2000
	s_nop 0
	global_load_lds_dwordx4 v130, s[48:49]
	s_mov_b32 m0, s60
	s_nop 0
	global_load_lds_dwordx4 v128, s[54:55]
	s_mov_b32 m0, s61
	s_nop 0
	global_load_lds_dwordx4 v130, s[54:55]
	s_waitcnt vmcnt(8) lgkmcnt(0)
	s_setprio 1
	s_barrier
	v_mfma_f32_16x16x32_bf16 v[60:63], v[150:153], v[182:185], v[60:63]
	v_mfma_f32_16x16x32_bf16 v[56:59], v[158:161], v[182:185], v[56:59]
	v_mfma_f32_16x16x32_bf16 v[48:51], v[150:153], v[190:193], v[48:51]
	v_mfma_f32_16x16x32_bf16 v[40:43], v[158:161], v[190:193], v[40:43]
	v_mfma_f32_16x16x32_bf16 v[32:35], v[150:153], v[198:201], v[32:35]
	v_mfma_f32_16x16x32_bf16 v[24:27], v[158:161], v[198:201], v[24:27]
	v_mfma_f32_16x16x32_bf16 v[16:19], v[150:153], v[206:209], v[16:19]
	v_mfma_f32_16x16x32_bf16 v[8:11], v[158:161], v[206:209], v[8:11]
	v_mfma_f32_16x16x32_bf16 v[60:63], v[154:157], v[186:189], v[60:63]
	v_mfma_f32_16x16x32_bf16 v[56:59], v[162:165], v[186:189], v[56:59]
	v_mfma_f32_16x16x32_bf16 v[48:51], v[154:157], v[194:197], v[48:51]
	v_mfma_f32_16x16x32_bf16 v[40:43], v[162:165], v[194:197], v[40:43]
	v_mfma_f32_16x16x32_bf16 v[32:35], v[154:157], v[202:205], v[32:35]
	v_mfma_f32_16x16x32_bf16 v[24:27], v[162:165], v[202:205], v[24:27]
	v_mfma_f32_16x16x32_bf16 v[16:19], v[154:157], v[210:213], v[16:19]
	v_mfma_f32_16x16x32_bf16 v[8:11], v[162:165], v[210:213], v[8:11]
	v_mfma_f32_16x16x32_bf16 v[52:55], v[166:169], v[182:185], v[52:55]
	v_mfma_f32_16x16x32_bf16 v[44:47], v[174:177], v[182:185], v[44:47]
	v_mfma_f32_16x16x32_bf16 v[36:39], v[166:169], v[190:193], v[36:39]
	v_mfma_f32_16x16x32_bf16 v[28:31], v[174:177], v[190:193], v[28:31]
	v_mfma_f32_16x16x32_bf16 v[20:23], v[166:169], v[198:201], v[20:23]
	v_mfma_f32_16x16x32_bf16 v[12:15], v[174:177], v[198:201], v[12:15]
	v_mfma_f32_16x16x32_bf16 v[4:7], v[166:169], v[206:209], v[4:7]
	v_mfma_f32_16x16x32_bf16 v[0:3], v[174:177], v[206:209], v[0:3]
	v_mfma_f32_16x16x32_bf16 v[52:55], v[170:173], v[186:189], v[52:55]
	v_mfma_f32_16x16x32_bf16 v[44:47], v[178:181], v[186:189], v[44:47]
	v_mfma_f32_16x16x32_bf16 v[36:39], v[170:173], v[194:197], v[36:39]
	v_mfma_f32_16x16x32_bf16 v[28:31], v[178:181], v[194:197], v[28:31]
	v_mfma_f32_16x16x32_bf16 v[20:23], v[170:173], v[202:205], v[20:23]
	v_mfma_f32_16x16x32_bf16 v[12:15], v[178:181], v[202:205], v[12:15]
	v_mfma_f32_16x16x32_bf16 v[4:7], v[170:173], v[210:213], v[4:7]
	s_setprio 0
	v_mfma_f32_16x16x32_bf16 v[0:3], v[178:181], v[210:213], v[0:3]
	s_barrier
	s_add_i32 s78, 0, 0x18000
	v_add_u32_e32 v149, s78, v144
	s_add_i32 s79, 0, 0x1c000
	ds_read_b128 v[150:153], v149
	ds_read_b128 v[154:157], v149 offset:1024
	ds_read_b128 v[158:161], v149 offset:2048
	ds_read_b128 v[162:165], v149 offset:3072
	v_add_u32_e32 v149, s79, v144
	ds_read_b128 v[166:169], v149
	ds_read_b128 v[170:173], v149 offset:1024
	ds_read_b128 v[174:177], v149 offset:2048
	ds_read_b128 v[178:181], v149 offset:3072
	s_add_u32 s48, s54, 0x160000
	s_addc_u32 s49, s55, 0
	s_mov_b32 m0, s62
	ds_read_b128 v[182:185], v148 offset:32768
	ds_read_b128 v[186:189], v148 offset:33792
	ds_read_b128 v[190:193], v148 offset:34816
	ds_read_b128 v[194:197], v148 offset:35840
	ds_read_b128 v[198:201], v148 offset:36864
	ds_read_b128 v[202:205], v148 offset:37888
	ds_read_b128 v[206:209], v148 offset:38912
	ds_read_b128 v[210:213], v148 offset:39936
	global_load_lds_dwordx4 v128, s[48:49]
	s_mov_b32 m0, s63
	s_nop 0
	global_load_lds_dwordx4 v130, s[48:49]
	s_waitcnt vmcnt(8) lgkmcnt(0)
	s_setprio 1
	s_barrier
; #define PG8_STAGE(bufoff, gbase, voff) do { _Pragma("unroll") for (int _i = 0; _i < 2; ++_i) \
;         __builtin_amdgcn_global_load_lds((const unsigned*)((const char*)(gbase) + (voff)[_i]), (LAS unsigned*)(lds + (bufoff) + ldsw + _i * 8192), 16, 0, 0); } while (0)
; #define PG8_LDA(dst, b, h) do { _Pragma("unroll") for (int m = 0; m < 4; ++m) _Pragma("unroll") for (int k = 0; k < 2; ++k) dst[m][k] = *(const LAS bf16x8*)(lds + PG8_SA(b, h) + aoff + m * 2048 + k * 1024); } while (0)
; #define PG8_WAIT_V(n) asm volatile("s_waitcnt vmcnt(" #n ")" ::: "memory")
; #define PG8_WAIT_L(n) asm volatile("s_waitcnt lgkmcnt(" #n ")" ::: "memory")
; #define PG8_BAR __builtin_amdgcn_s_barrier()
; #define PG8_SCHED __builtin_amdgcn_sched_barrier(0)
; template <class Epi, bool FP8 = false>
; __device__ __forceinline__ void gemm_phase(LAS unsigned char* lds, const Gemm g, const StaticOrder& S_, const Epi& E, const int tid) {
;     ...
;             PG8_WAIT_V(8); PG8_WAIT_L(0); PG8_BAR; PG8_MMA(0, 0, At, B0); PG8_MMA(0, 1, At, B1); PG8_BAR; PG8_SCHED;
;             PG8_LDA(At, 1, 1); PG8_STAGE(PG8_SB(1, 0), b3, voffB); PG8_STAGE(PG8_SB(1, 1), b3 + hstepB, voffB); PG8_STAGE(PG8_SA(1, 0), a3, voffA);
;             PG8_WAIT_V(8); PG8_WAIT_L(0); PG8_BAR; PG8_MMA(1, 0, At, B0); PG8_MMA(1, 1, At, B1); PG8_BAR; PG8_SCHED;
;         }
;         if (wr == 0) PG8_BAR;
	v_mfma_f32_16x16x32_bf16 v[124:127], v[150:153], v[182:185], v[124:127]
	v_mfma_f32_16x16x32_bf16 v[120:123], v[158:161], v[182:185], v[120:123]
	v_mfma_f32_16x16x32_bf16 v[112:115], v[150:153], v[190:193], v[112:115]
	v_mfma_f32_16x16x32_bf16 v[104:107], v[158:161], v[190:193], v[104:107]
	v_mfma_f32_16x16x32_bf16 v[96:99], v[150:153], v[198:201], v[96:99]
	v_mfma_f32_16x16x32_bf16 v[88:91], v[158:161], v[198:201], v[88:91]
	v_mfma_f32_16x16x32_bf16 v[80:83], v[150:153], v[206:209], v[80:83]
	v_mfma_f32_16x16x32_bf16 v[72:75], v[158:161], v[206:209], v[72:75]
	v_mfma_f32_16x16x32_bf16 v[124:127], v[154:157], v[186:189], v[124:127]
	v_mfma_f32_16x16x32_bf16 v[120:123], v[162:165], v[186:189], v[120:123]
	v_mfma_f32_16x16x32_bf16 v[112:115], v[154:157], v[194:197], v[112:115]
	v_mfma_f32_16x16x32_bf16 v[104:107], v[162:165], v[194:197], v[104:107]
	v_mfma_f32_16x16x32_bf16 v[96:99], v[154:157], v[202:205], v[96:99]
	v_mfma_f32_16x16x32_bf16 v[88:91], v[162:165], v[202:205], v[88:91]
	v_mfma_f32_16x16x32_bf16 v[80:83], v[154:157], v[210:213], v[80:83]
	v_mfma_f32_16x16x32_bf16 v[72:75], v[162:165], v[210:213], v[72:75]
	v_mfma_f32_16x16x32_bf16 v[116:119], v[166:169], v[182:185], v[116:119]
	v_mfma_f32_16x16x32_bf16 v[108:111], v[174:177], v[182:185], v[108:111]
	v_mfma_f32_16x16x32_bf16 v[100:103], v[166:169], v[190:193], v[100:103]
	v_mfma_f32_16x16x32_bf16 v[92:95], v[174:177], v[190:193], v[92:95]
	v_mfma_f32_16x16x32_bf16 v[84:87], v[166:169], v[198:201], v[84:87]
	v_mfma_f32_16x16x32_bf16 v[76:79], v[174:177], v[198:201], v[76:79]
	v_mfma_f32_16x16x32_bf16 v[68:71], v[166:169], v[206:209], v[68:71]
	v_mfma_f32_16x16x32_bf16 v[64:67], v[174:177], v[206:209], v[64:67]
	v_mfma_f32_16x16x32_bf16 v[116:119], v[170:173], v[186:189], v[116:119]
	v_mfma_f32_16x16x32_bf16 v[108:111], v[178:181], v[186:189], v[108:111]
	v_mfma_f32_16x16x32_bf16 v[100:103], v[170:173], v[194:197], v[100:103]
	v_mfma_f32_16x16x32_bf16 v[92:95], v[178:181], v[194:197], v[92:95]
	v_mfma_f32_16x16x32_bf16 v[84:87], v[170:173], v[202:205], v[84:87]
	v_mfma_f32_16x16x32_bf16 v[76:79], v[178:181], v[202:205], v[76:79]
	v_mfma_f32_16x16x32_bf16 v[68:71], v[170:173], v[210:213], v[68:71]
	s_setprio 0
	v_mfma_f32_16x16x32_bf16 v[64:67], v[178:181], v[210:213], v[64:67]
	s_barrier
	s_add_i32 s48, s78, s59
	s_mov_b32 m0, s48
	ds_read_b128 v[182:185], v148 offset:49152
	ds_read_b128 v[186:189], v148 offset:50176
	ds_read_b128 v[190:193], v148 offset:51200
	ds_read_b128 v[194:197], v148 offset:52224
	ds_read_b128 v[198:201], v148 offset:53248
	ds_read_b128 v[202:205], v148 offset:54272
	ds_read_b128 v[206:209], v148 offset:55296
	ds_read_b128 v[210:213], v148 offset:56320
	global_load_lds_dwordx4 v128, s[98:99]
	s_add_i32 m0, s48, 0x2000
	s_add_u32 s48, s52, 0x160080
	s_addc_u32 s49, s53, 0
	s_add_i32 s52, s79, s59
	global_load_lds_dwordx4 v130, s[98:99]
	s_mov_b32 m0, s52
	s_nop 0
	global_load_lds_dwordx4 v128, s[48:49]
	s_add_i32 m0, s52, 0x2000
	s_nop 0
	global_load_lds_dwordx4 v130, s[48:49]
	s_mov_b32 m0, s68
	s_nop 0
	global_load_lds_dwordx4 v128, s[100:101]
	s_mov_b32 m0, s69
	s_nop 0
	global_load_lds_dwordx4 v130, s[100:101]
	s_waitcnt vmcnt(8) lgkmcnt(0)
	s_setprio 1
	s_barrier
	v_mfma_f32_16x16x32_bf16 v[60:63], v[150:153], v[182:185], v[60:63]
	v_mfma_f32_16x16x32_bf16 v[56:59], v[158:161], v[182:185], v[56:59]
	v_mfma_f32_16x16x32_bf16 v[48:51], v[150:153], v[190:193], v[48:51]
	v_mfma_f32_16x16x32_bf16 v[40:43], v[158:161], v[190:193], v[40:43]
	v_mfma_f32_16x16x32_bf16 v[32:35], v[150:153], v[198:201], v[32:35]
	v_mfma_f32_16x16x32_bf16 v[24:27], v[158:161], v[198:201], v[24:27]
	v_mfma_f32_16x16x32_bf16 v[16:19], v[150:153], v[206:209], v[16:19]
	v_mfma_f32_16x16x32_bf16 v[8:11], v[158:161], v[206:209], v[8:11]
	v_mfma_f32_16x16x32_bf16 v[60:63], v[154:157], v[186:189], v[60:63]
	v_mfma_f32_16x16x32_bf16 v[56:59], v[162:165], v[186:189], v[56:59]
	v_mfma_f32_16x16x32_bf16 v[48:51], v[154:157], v[194:197], v[48:51]
	v_mfma_f32_16x16x32_bf16 v[40:43], v[162:165], v[194:197], v[40:43]
	v_mfma_f32_16x16x32_bf16 v[32:35], v[154:157], v[202:205], v[32:35]
	v_mfma_f32_16x16x32_bf16 v[24:27], v[162:165], v[202:205], v[24:27]
	v_mfma_f32_16x16x32_bf16 v[16:19], v[154:157], v[210:213], v[16:19]
	v_mfma_f32_16x16x32_bf16 v[8:11], v[162:165], v[210:213], v[8:11]
	v_mfma_f32_16x16x32_bf16 v[52:55], v[166:169], v[182:185], v[52:55]
	v_mfma_f32_16x16x32_bf16 v[44:47], v[174:177], v[182:185], v[44:47]
	v_mfma_f32_16x16x32_bf16 v[36:39], v[166:169], v[190:193], v[36:39]
	v_mfma_f32_16x16x32_bf16 v[28:31], v[174:177], v[190:193], v[28:31]
	v_mfma_f32_16x16x32_bf16 v[20:23], v[166:169], v[198:201], v[20:23]
	v_mfma_f32_16x16x32_bf16 v[12:15], v[174:177], v[198:201], v[12:15]
	v_mfma_f32_16x16x32_bf16 v[4:7], v[166:169], v[206:209], v[4:7]
	v_mfma_f32_16x16x32_bf16 v[0:3], v[174:177], v[206:209], v[0:3]
	v_mfma_f32_16x16x32_bf16 v[52:55], v[170:173], v[186:189], v[52:55]
	v_mfma_f32_16x16x32_bf16 v[44:47], v[178:181], v[186:189], v[44:47]
	v_mfma_f32_16x16x32_bf16 v[36:39], v[170:173], v[194:197], v[36:39]
	v_mfma_f32_16x16x32_bf16 v[28:31], v[178:181], v[194:197], v[28:31]
	v_mfma_f32_16x16x32_bf16 v[20:23], v[170:173], v[202:205], v[20:23]
	v_mfma_f32_16x16x32_bf16 v[12:15], v[178:181], v[202:205], v[12:15]
	v_mfma_f32_16x16x32_bf16 v[4:7], v[170:173], v[210:213], v[4:7]
	s_setprio 0
	v_mfma_f32_16x16x32_bf16 v[0:3], v[178:181], v[210:213], v[0:3]
	s_barrier
	s_add_i32 s77, s77, 2
	s_add_u32 s75, s75, 0x100
	s_addc_u32 s76, s76, 0
	s_cmpk_gt_u32 s77, 0x55
	s_mov_b64 s[48:49], s[50:51]
	s_cbranch_scc0 .LBB0_319
	s_and_b64 vcc, exec, s[16:17]
	s_cbranch_vccz .LBB0_322
	s_barrier

; #define PG8_WAIT_V(n) asm volatile("s_waitcnt vmcnt(" #n ")" ::: "memory")
; #define PG8_WAIT_L(n) asm volatile("s_waitcnt lgkmcnt(" #n ")" ::: "memory")
; template <class Epi, bool FP8 = false>
; __device__ __forceinline__ void gemm_phase(LAS unsigned char* lds, const Gemm g, const StaticOrder& S_, const Epi& E, const int tid) {
;     ...
;         const bool has_next = S_.next(ui + 1, nxt);
;         const char* nA = has_next ? (const char*)g.A + (size_t)nxt.pm * tstepA : cA; const char* nB = has_next ? (const char*)g.Bt + (size_t)nxt.pn * tstepB : cB;
;         for (int t = 0; t < nt; t += 2) {
;             const bool last = (t == nt - 2);
;             const char* a1 = cA + (size_t)(t + 1) * kstep;
;             const char* a2 = last ? nA : cA + (size_t)(t + 2) * kstep; const char* b2 = last ? nB : cB + (size_t)(t + 2) * kstep;
;             const char* a3 = a2 + kstep; const char* b3 = b2 + kstep;
;             PG8_LDB(B0, 0, 0); PG8_LDB(B1, 0, 1); PG8_SCHED; PG8_LDA(At, 0, 0); PG8_STAGE(PG8_SA(1, 1), a1 + hstepA, voffA);
;             PG8_WAIT_V(8); PG8_WAIT_L(0); PG8_BAR; PG8_MMA(0, 0, At, B0); PG8_MMA(0, 1, At, B1); PG8_BAR; PG8_SCHED;
;             PG8_LDA(At, 0, 1); PG8_STAGE(PG8_SB(0, 0), b2, voffB); PG8_STAGE(PG8_SB(0, 1), b2 + hstepB, voffB); PG8_STAGE(PG8_SA(0, 0), a2, voffA);
;             PG8_WAIT_V(8); PG8_WAIT_L(0); PG8_BAR; PG8_MMA(1, 0, At, B0); PG8_MMA(1, 1, At, B1); PG8_BAR; PG8_SCHED;
;             PG8_LDB(B0, 1, 0); PG8_LDB(B1, 1, 1); PG8_SCHED; PG8_LDA(At, 1, 0); PG8_STAGE(PG8_SA(0, 1), a2 + hstepA, voffA);
;             PG8_WAIT_V(8); PG8_WAIT_L(0); PG8_BAR; PG8_MMA(0, 0, At, B0); PG8_MMA(0, 1, At, B1); PG8_BAR; PG8_SCHED;
;             PG8_LDA(At, 1, 1); PG8_STAGE(PG8_SB(1, 0), b3, voffB); PG8_STAGE(PG8_SB(1, 1), b3 + hstepB, voffB); PG8_STAGE(PG8_SA(1, 0), a3, voffA);
;             PG8_WAIT_V(8); PG8_WAIT_L(0); PG8_BAR; PG8_MMA(1, 0, At, B0); PG8_MMA(1, 1, At, B1); PG8_BAR; PG8_SCHED;
;         }
;         if (wr == 0) PG8_BAR;
;         E(acc, cur, wr, wc, fr, fq);
;         if (!has_next) break;
; #pragma unroll
;         for (int a = 0; a < 2; ++a)
; #pragma unroll
;             for (int b = 0; b < 2; ++b)
; #pragma unroll
;                 for (int m = 0; m < 4; ++m)
; #pragma unroll
;                     for (int n = 0; n < 2; ++n) acc[a][b][m][n] = (f32x4){0.f, 0.f, 0.f, 0.f};
;         cur = nxt; cA = nA; cB = nB; ++ui;
.LBB0_456:
	s_ashr_i32 s49, s48, 31
	s_lshl_b64 s[42:43], s[48:49], 20
	s_add_u32 s50, s3, s42
	s_addc_u32 s51, s35, s43
	s_and_b64 s[42:43], s[4:5], exec
	s_cselect_b32 s7, s51, s55
	s_cselect_b32 s42, s50, s54
	s_ashr_i32 s27, s26, 31
	s_lshl_b64 s[52:53], s[26:27], 20
	s_add_u32 s52, s68, s52
	s_addc_u32 s53, s69, s53
	s_and_b64 s[58:59], s[4:5], exec
	s_cselect_b32 s27, s53, s57
	s_cselect_b32 s43, s52, s56
	s_add_u32 s54, s54, 0x80080
	s_addc_u32 s55, s55, 0
	s_add_u32 s49, s56, 0x100
	v_mov_b32_e32 v0, 0
	s_addc_u32 s60, s57, 0
	s_mov_b32 s61, -2
	v_mov_b64_e32 v[0:1], 0
	v_mov_b64_e32 v[2:3], 0
	v_mov_b64_e32 v[4:5], 0
	v_mov_b64_e32 v[6:7], 0
	v_mov_b64_e32 v[8:9], 0
	v_mov_b64_e32 v[10:11], 0
	v_mov_b64_e32 v[12:13], 0
	v_mov_b64_e32 v[14:15], 0
	v_mov_b64_e32 v[16:17], 0
	v_mov_b64_e32 v[18:19], 0
	v_mov_b64_e32 v[20:21], 0
	v_mov_b64_e32 v[22:23], 0
	v_mov_b64_e32 v[24:25], 0
	v_mov_b64_e32 v[26:27], 0
	v_mov_b64_e32 v[28:29], 0
	v_mov_b64_e32 v[30:31], 0
	v_mov_b64_e32 v[32:33], 0
	v_mov_b64_e32 v[34:35], 0
	v_mov_b64_e32 v[36:37], 0
	v_mov_b64_e32 v[38:39], 0
	v_mov_b64_e32 v[40:41], 0
	v_mov_b64_e32 v[42:43], 0
	v_mov_b64_e32 v[44:45], 0
	v_mov_b64_e32 v[46:47], 0
	v_mov_b64_e32 v[48:49], 0
	v_mov_b64_e32 v[50:51], 0
	v_mov_b64_e32 v[52:53], 0
	v_mov_b64_e32 v[54:55], 0
	v_mov_b64_e32 v[56:57], 0
	v_mov_b64_e32 v[58:59], 0
	v_mov_b64_e32 v[60:61], 0
	v_mov_b64_e32 v[62:63], 0
	v_mov_b64_e32 v[64:65], 0
	v_mov_b64_e32 v[66:67], 0
	v_mov_b64_e32 v[68:69], 0
	v_mov_b64_e32 v[70:71], 0
	v_mov_b64_e32 v[72:73], 0
	v_mov_b64_e32 v[74:75], 0
	v_mov_b64_e32 v[76:77], 0
	v_mov_b64_e32 v[78:79], 0
	v_mov_b64_e32 v[80:81], 0
	v_mov_b64_e32 v[82:83], 0
	v_mov_b64_e32 v[84:85], 0
	v_mov_b64_e32 v[86:87], 0
	v_mov_b64_e32 v[88:89], 0
	v_mov_b64_e32 v[90:91], 0
	v_mov_b64_e32 v[92:93], 0
	v_mov_b64_e32 v[94:95], 0
	v_mov_b64_e32 v[96:97], 0
	v_mov_b64_e32 v[98:99], 0
	v_mov_b64_e32 v[100:101], 0
	v_mov_b64_e32 v[102:103], 0
	v_mov_b64_e32 v[104:105], 0
	v_mov_b64_e32 v[106:107], 0
	v_mov_b64_e32 v[108:109], 0
	v_mov_b64_e32 v[110:111], 0
	v_mov_b64_e32 v[112:113], 0
	v_mov_b64_e32 v[114:115], 0
	v_mov_b64_e32 v[116:117], 0
	v_mov_b64_e32 v[118:119], 0
	v_mov_b64_e32 v[120:121], 0
	v_mov_b64_e32 v[122:123], 0
	v_mov_b64_e32 v[124:125], 0
	v_mov_b64_e32 v[126:127], 0
.LBB0_457:
	ds_read_b128 v[128:131], v190
	ds_read_b128 v[132:135], v190 offset:1024
	ds_read_b128 v[136:139], v190 offset:2048
	ds_read_b128 v[140:143], v190 offset:3072
	ds_read_b128 v[182:185], v192
	ds_read_b128 v[194:197], v192 offset:1024
	ds_read_b128 v[198:201], v192 offset:2048
	ds_read_b128 v[202:205], v192 offset:3072
	s_add_u32 s56, s54, 0xfff80080
	s_addc_u32 s57, s55, -1
	s_cmp_eq_u32 s61, 28
	s_cselect_b32 s59, s7, s57
	s_cselect_b32 s58, s42, s56
	s_cselect_b32 s57, s27, s60
	s_cselect_b32 s56, s43, s49
	s_add_i32 m0, s71, 0xc000
	ds_read_b128 v[206:209], v191
	ds_read_b128 v[210:213], v191 offset:1024
	ds_read_b128 v[214:217], v191 offset:2048
	ds_read_b128 v[218:221], v191 offset:3072
	ds_read_b128 v[222:225], v191 offset:4096
	ds_read_b128 v[226:229], v191 offset:5120
	ds_read_b128 v[230:233], v191 offset:6144
	ds_read_b128 v[234:237], v191 offset:7168
	global_load_lds_dwordx4 v174, s[54:55]
	s_add_i32 m0, s71, 0xe000
	s_nop 0
	global_load_lds_dwordx4 v176, s[54:55]
	s_waitcnt vmcnt(8) lgkmcnt(0)
	s_setprio 1
	s_barrier
	v_mfma_f32_16x16x32_bf16 v[124:127], v[128:131], v[206:209], v[124:127]
	v_mfma_f32_16x16x32_bf16 v[120:123], v[136:139], v[206:209], v[120:123]
	v_mfma_f32_16x16x32_bf16 v[108:111], v[128:131], v[214:217], v[108:111]
	v_mfma_f32_16x16x32_bf16 v[104:107], v[136:139], v[214:217], v[104:107]
	v_mfma_f32_16x16x32_bf16 v[92:95], v[128:131], v[222:225], v[92:95]
	v_mfma_f32_16x16x32_bf16 v[88:91], v[136:139], v[222:225], v[88:91]
	v_mfma_f32_16x16x32_bf16 v[76:79], v[128:131], v[230:233], v[76:79]
	v_mfma_f32_16x16x32_bf16 v[72:75], v[136:139], v[230:233], v[72:75]
	v_mfma_f32_16x16x32_bf16 v[124:127], v[132:135], v[210:213], v[124:127]
	v_mfma_f32_16x16x32_bf16 v[120:123], v[140:143], v[210:213], v[120:123]
	v_mfma_f32_16x16x32_bf16 v[108:111], v[132:135], v[218:221], v[108:111]
	v_mfma_f32_16x16x32_bf16 v[104:107], v[140:143], v[218:221], v[104:107]
	v_mfma_f32_16x16x32_bf16 v[92:95], v[132:135], v[226:229], v[92:95]
	v_mfma_f32_16x16x32_bf16 v[88:91], v[140:143], v[226:229], v[88:91]
	v_mfma_f32_16x16x32_bf16 v[76:79], v[132:135], v[234:237], v[76:79]
	v_mfma_f32_16x16x32_bf16 v[72:75], v[140:143], v[234:237], v[72:75]
	v_mfma_f32_16x16x32_bf16 v[116:119], v[182:185], v[206:209], v[116:119]
	v_mfma_f32_16x16x32_bf16 v[112:115], v[198:201], v[206:209], v[112:115]
	v_mfma_f32_16x16x32_bf16 v[100:103], v[182:185], v[214:217], v[100:103]
	v_mfma_f32_16x16x32_bf16 v[96:99], v[198:201], v[214:217], v[96:99]
	v_mfma_f32_16x16x32_bf16 v[84:87], v[182:185], v[222:225], v[84:87]
	v_mfma_f32_16x16x32_bf16 v[80:83], v[198:201], v[222:225], v[80:83]
	v_mfma_f32_16x16x32_bf16 v[68:71], v[182:185], v[230:233], v[68:71]
	v_mfma_f32_16x16x32_bf16 v[64:67], v[198:201], v[230:233], v[64:67]
	v_mfma_f32_16x16x32_bf16 v[116:119], v[194:197], v[210:213], v[116:119]
	v_mfma_f32_16x16x32_bf16 v[112:115], v[202:205], v[210:213], v[112:115]
	v_mfma_f32_16x16x32_bf16 v[100:103], v[194:197], v[218:221], v[100:103]
	v_mfma_f32_16x16x32_bf16 v[96:99], v[202:205], v[218:221], v[96:99]
	v_mfma_f32_16x16x32_bf16 v[84:87], v[194:197], v[226:229], v[84:87]
	v_mfma_f32_16x16x32_bf16 v[80:83], v[202:205], v[226:229], v[80:83]
	v_mfma_f32_16x16x32_bf16 v[68:71], v[194:197], v[234:237], v[68:71]
	s_setprio 0
	v_mfma_f32_16x16x32_bf16 v[64:67], v[202:205], v[234:237], v[64:67]
	s_barrier
; #define PG8_STAGE(bufoff, gbase, voff) do { _Pragma("unroll") for (int _i = 0; _i < 2; ++_i) \
;         __builtin_amdgcn_global_load_lds((const unsigned*)((const char*)(gbase) + (voff)[_i]), (LAS unsigned*)(lds + (bufoff) + ldsw + _i * 8192), 16, 0, 0); } while (0)
; #define PG8_LDA(dst, b, h) do { _Pragma("unroll") for (int m = 0; m < 4; ++m) _Pragma("unroll") for (int k = 0; k < 2; ++k) dst[m][k] = *(const LAS bf16x8*)(lds + PG8_SA(b, h) + aoff + m * 2048 + k * 1024); } while (0)
; #define PG8_LDB(dst, b, h) do { _Pragma("unroll") for (int n = 0; n < 2; ++n) _Pragma("unroll") for (int k = 0; k < 2; ++k) dst[n][k] = *(const LAS bf16x8*)(lds + PG8_SB(b, h) + boff + n * 2048 + k * 1024); } while (0)
; #define PG8_WAIT_V(n) asm volatile("s_waitcnt vmcnt(" #n ")" ::: "memory")
; #define PG8_WAIT_L(n) asm volatile("s_waitcnt lgkmcnt(" #n ")" ::: "memory")
; #define PG8_BAR __builtin_amdgcn_s_barrier()
; #define PG8_SCHED __builtin_amdgcn_sched_barrier(0)
; template <class Epi, bool FP8 = false>
; __device__ __forceinline__ void gemm_phase(LAS unsigned char* lds, const Gemm g, const StaticOrder& S_, const Epi& E, const int tid) {
;     ...
;             PG8_LDA(At, 0, 1); PG8_STAGE(PG8_SB(0, 0), b2, voffB); PG8_STAGE(PG8_SB(0, 1), b2 + hstepB, voffB); PG8_STAGE(PG8_SA(0, 0), a2, voffA);
;             PG8_WAIT_V(8); PG8_WAIT_L(0); PG8_BAR; PG8_MMA(1, 0, At, B0); PG8_MMA(1, 1, At, B1); PG8_BAR; PG8_SCHED;
;             PG8_LDB(B0, 1, 0); PG8_LDB(B1, 1, 1); PG8_SCHED; PG8_LDA(At, 1, 0); PG8_STAGE(PG8_SA(0, 1), a2 + hstepA, voffA);
;             PG8_WAIT_V(8); PG8_WAIT_L(0); PG8_BAR; PG8_MMA(0, 0, At, B0); PG8_MMA(0, 1, At, B1); PG8_BAR; PG8_SCHED;
	s_add_u32 s98, s56, s14
	s_addc_u32 s99, s57, s15
	s_add_u32 s100, s58, s14
	s_addc_u32 s101, s59, s15
	s_add_i32 s62, s85, s70
	s_mov_b32 m0, s62
	ds_read_b128 v[206:209], v191 offset:16384
	ds_read_b128 v[210:213], v191 offset:17408
	ds_read_b128 v[214:217], v191 offset:18432
	ds_read_b128 v[218:221], v191 offset:19456
	ds_read_b128 v[222:225], v191 offset:20480
	ds_read_b128 v[226:229], v191 offset:21504
	ds_read_b128 v[230:233], v191 offset:22528
	ds_read_b128 v[234:237], v191 offset:23552
	global_load_lds_dwordx4 v146, s[56:57]
	s_add_i32 m0, s62, 0x2000
	s_add_u32 s62, s56, 0x80000
	s_addc_u32 s63, s57, 0
	s_add_i32 s66, s86, s70
	global_load_lds_dwordx4 v150, s[56:57]
	s_mov_b32 m0, s66
	s_nop 0
	global_load_lds_dwordx4 v146, s[62:63]
	s_add_i32 m0, s66, 0x2000
	s_nop 0
	global_load_lds_dwordx4 v150, s[62:63]
	s_mov_b32 m0, s71
	s_nop 0
	global_load_lds_dwordx4 v144, s[58:59]
	s_mov_b32 m0, s72
	s_nop 0
	global_load_lds_dwordx4 v148, s[58:59]
	s_waitcnt vmcnt(8) lgkmcnt(0)
	s_setprio 1
	s_barrier
	v_mfma_f32_16x16x32_bf16 v[60:63], v[128:131], v[206:209], v[60:63]
	v_mfma_f32_16x16x32_bf16 v[56:59], v[136:139], v[206:209], v[56:59]
	v_mfma_f32_16x16x32_bf16 v[44:47], v[128:131], v[214:217], v[44:47]
	v_mfma_f32_16x16x32_bf16 v[40:43], v[136:139], v[214:217], v[40:43]
	v_mfma_f32_16x16x32_bf16 v[28:31], v[128:131], v[222:225], v[28:31]
	v_mfma_f32_16x16x32_bf16 v[24:27], v[136:139], v[222:225], v[24:27]
	v_mfma_f32_16x16x32_bf16 v[12:15], v[128:131], v[230:233], v[12:15]
	v_mfma_f32_16x16x32_bf16 v[8:11], v[136:139], v[230:233], v[8:11]
	v_mfma_f32_16x16x32_bf16 v[60:63], v[132:135], v[210:213], v[60:63]
	v_mfma_f32_16x16x32_bf16 v[56:59], v[140:143], v[210:213], v[56:59]
	v_mfma_f32_16x16x32_bf16 v[44:47], v[132:135], v[218:221], v[44:47]
	v_mfma_f32_16x16x32_bf16 v[40:43], v[140:143], v[218:221], v[40:43]
	v_mfma_f32_16x16x32_bf16 v[28:31], v[132:135], v[226:229], v[28:31]
	v_mfma_f32_16x16x32_bf16 v[24:27], v[140:143], v[226:229], v[24:27]
	v_mfma_f32_16x16x32_bf16 v[12:15], v[132:135], v[234:237], v[12:15]
	v_mfma_f32_16x16x32_bf16 v[8:11], v[140:143], v[234:237], v[8:11]
	v_mfma_f32_16x16x32_bf16 v[52:55], v[182:185], v[206:209], v[52:55]
	v_mfma_f32_16x16x32_bf16 v[48:51], v[198:201], v[206:209], v[48:51]
	v_mfma_f32_16x16x32_bf16 v[36:39], v[182:185], v[214:217], v[36:39]
	v_mfma_f32_16x16x32_bf16 v[32:35], v[198:201], v[214:217], v[32:35]
	v_mfma_f32_16x16x32_bf16 v[20:23], v[182:185], v[222:225], v[20:23]
	v_mfma_f32_16x16x32_bf16 v[16:19], v[198:201], v[222:225], v[16:19]
	v_mfma_f32_16x16x32_bf16 v[4:7], v[182:185], v[230:233], v[4:7]
	v_mfma_f32_16x16x32_bf16 v[0:3], v[198:201], v[230:233], v[0:3]
	v_mfma_f32_16x16x32_bf16 v[52:55], v[194:197], v[210:213], v[52:55]
	v_mfma_f32_16x16x32_bf16 v[48:51], v[202:205], v[210:213], v[48:51]
	v_mfma_f32_16x16x32_bf16 v[36:39], v[194:197], v[218:221], v[36:39]
	v_mfma_f32_16x16x32_bf16 v[32:35], v[202:205], v[218:221], v[32:35]
	v_mfma_f32_16x16x32_bf16 v[20:23], v[194:197], v[226:229], v[20:23]
	v_mfma_f32_16x16x32_bf16 v[16:19], v[202:205], v[226:229], v[16:19]
	v_mfma_f32_16x16x32_bf16 v[4:7], v[194:197], v[234:237], v[4:7]
	s_setprio 0
	v_mfma_f32_16x16x32_bf16 v[0:3], v[202:205], v[234:237], v[0:3]
	s_barrier
	s_add_i32 s62, 0, 0x18000
	s_add_i32 s63, 0, 0x1c000
	v_add_u32_e32 v140, s62, v163
	v_add_u32_e32 v152, s63, v163
	ds_read_b128 v[128:131], v140
	ds_read_b128 v[132:135], v140 offset:1024
	ds_read_b128 v[136:139], v140 offset:2048
	ds_read_b128 v[140:143], v140 offset:3072
	ds_read_b128 v[182:185], v152
	ds_read_b128 v[194:197], v152 offset:1024
	ds_read_b128 v[198:201], v152 offset:2048
	ds_read_b128 v[202:205], v152 offset:3072
	s_add_u32 s58, s58, 0x80000
	s_addc_u32 s59, s59, 0
	s_mov_b32 m0, s73
	ds_read_b128 v[206:209], v191 offset:32768
	ds_read_b128 v[210:213], v191 offset:33792
	ds_read_b128 v[214:217], v191 offset:34816
	ds_read_b128 v[218:221], v191 offset:35840
	ds_read_b128 v[222:225], v191 offset:36864
	ds_read_b128 v[226:229], v191 offset:37888
	ds_read_b128 v[230:233], v191 offset:38912
	ds_read_b128 v[234:237], v191 offset:39936
	global_load_lds_dwordx4 v144, s[58:59]
	s_mov_b32 m0, s74
	s_nop 0
	global_load_lds_dwordx4 v148, s[58:59]
	s_waitcnt vmcnt(8) lgkmcnt(0)
	s_setprio 1
	s_barrier
; #define PG8_STAGE(bufoff, gbase, voff) do { _Pragma("unroll") for (int _i = 0; _i < 2; ++_i) \
;         __builtin_amdgcn_global_load_lds((const unsigned*)((const char*)(gbase) + (voff)[_i]), (LAS unsigned*)(lds + (bufoff) + ldsw + _i * 8192), 16, 0, 0); } while (0)
; #define PG8_LDA(dst, b, h) do { _Pragma("unroll") for (int m = 0; m < 4; ++m) _Pragma("unroll") for (int k = 0; k < 2; ++k) dst[m][k] = *(const LAS bf16x8*)(lds + PG8_SA(b, h) + aoff + m * 2048 + k * 1024); } while (0)
; #define PG8_WAIT_V(n) asm volatile("s_waitcnt vmcnt(" #n ")" ::: "memory")
; #define PG8_WAIT_L(n) asm volatile("s_waitcnt lgkmcnt(" #n ")" ::: "memory")
; #define PG8_BAR __builtin_amdgcn_s_barrier()
; #define PG8_SCHED __builtin_amdgcn_sched_barrier(0)
; template <class Epi, bool FP8 = false>
; __device__ __forceinline__ void gemm_phase(LAS unsigned char* lds, const Gemm g, const StaticOrder& S_, const Epi& E, const int tid) {
;     ...
;             PG8_WAIT_V(8); PG8_WAIT_L(0); PG8_BAR; PG8_MMA(0, 0, At, B0); PG8_MMA(0, 1, At, B1); PG8_BAR; PG8_SCHED;
;             PG8_LDA(At, 1, 1); PG8_STAGE(PG8_SB(1, 0), b3, voffB); PG8_STAGE(PG8_SB(1, 1), b3 + hstepB, voffB); PG8_STAGE(PG8_SA(1, 0), a3, voffA);
;             PG8_WAIT_V(8); PG8_WAIT_L(0); PG8_BAR; PG8_MMA(1, 0, At, B0); PG8_MMA(1, 1, At, B1); PG8_BAR; PG8_SCHED;
;         }
;         if (wr == 0) PG8_BAR;
	v_mfma_f32_16x16x32_bf16 v[124:127], v[128:131], v[206:209], v[124:127]
	v_mfma_f32_16x16x32_bf16 v[120:123], v[136:139], v[206:209], v[120:123]
	v_mfma_f32_16x16x32_bf16 v[108:111], v[128:131], v[214:217], v[108:111]
	v_mfma_f32_16x16x32_bf16 v[104:107], v[136:139], v[214:217], v[104:107]
	v_mfma_f32_16x16x32_bf16 v[92:95], v[128:131], v[222:225], v[92:95]
	v_mfma_f32_16x16x32_bf16 v[88:91], v[136:139], v[222:225], v[88:91]
	v_mfma_f32_16x16x32_bf16 v[76:79], v[128:131], v[230:233], v[76:79]
	v_mfma_f32_16x16x32_bf16 v[72:75], v[136:139], v[230:233], v[72:75]
	v_mfma_f32_16x16x32_bf16 v[124:127], v[132:135], v[210:213], v[124:127]
	v_mfma_f32_16x16x32_bf16 v[120:123], v[140:143], v[210:213], v[120:123]
	v_mfma_f32_16x16x32_bf16 v[108:111], v[132:135], v[218:221], v[108:111]
	v_mfma_f32_16x16x32_bf16 v[104:107], v[140:143], v[218:221], v[104:107]
	v_mfma_f32_16x16x32_bf16 v[92:95], v[132:135], v[226:229], v[92:95]
	v_mfma_f32_16x16x32_bf16 v[88:91], v[140:143], v[226:229], v[88:91]
	v_mfma_f32_16x16x32_bf16 v[76:79], v[132:135], v[234:237], v[76:79]
	v_mfma_f32_16x16x32_bf16 v[72:75], v[140:143], v[234:237], v[72:75]
	v_mfma_f32_16x16x32_bf16 v[116:119], v[182:185], v[206:209], v[116:119]
	v_mfma_f32_16x16x32_bf16 v[112:115], v[198:201], v[206:209], v[112:115]
	v_mfma_f32_16x16x32_bf16 v[100:103], v[182:185], v[214:217], v[100:103]
	v_mfma_f32_16x16x32_bf16 v[96:99], v[198:201], v[214:217], v[96:99]
	v_mfma_f32_16x16x32_bf16 v[84:87], v[182:185], v[222:225], v[84:87]
	v_mfma_f32_16x16x32_bf16 v[80:83], v[198:201], v[222:225], v[80:83]
	v_mfma_f32_16x16x32_bf16 v[68:71], v[182:185], v[230:233], v[68:71]
	v_mfma_f32_16x16x32_bf16 v[64:67], v[198:201], v[230:233], v[64:67]
	v_mfma_f32_16x16x32_bf16 v[116:119], v[194:197], v[210:213], v[116:119]
	v_mfma_f32_16x16x32_bf16 v[112:115], v[202:205], v[210:213], v[112:115]
	v_mfma_f32_16x16x32_bf16 v[100:103], v[194:197], v[218:221], v[100:103]
	v_mfma_f32_16x16x32_bf16 v[96:99], v[202:205], v[218:221], v[96:99]
	v_mfma_f32_16x16x32_bf16 v[84:87], v[194:197], v[226:229], v[84:87]
	v_mfma_f32_16x16x32_bf16 v[80:83], v[202:205], v[226:229], v[80:83]
	v_mfma_f32_16x16x32_bf16 v[68:71], v[194:197], v[234:237], v[68:71]
	s_setprio 0
	v_mfma_f32_16x16x32_bf16 v[64:67], v[202:205], v[234:237], v[64:67]
	s_barrier
	s_add_i32 s58, s62, s70
	s_mov_b32 m0, s58
	ds_read_b128 v[206:209], v191 offset:49152
	ds_read_b128 v[210:213], v191 offset:50176
	ds_read_b128 v[214:217], v191 offset:51200
	ds_read_b128 v[218:221], v191 offset:52224
	ds_read_b128 v[222:225], v191 offset:53248
	ds_read_b128 v[226:229], v191 offset:54272
	ds_read_b128 v[230:233], v191 offset:55296
	ds_read_b128 v[234:237], v191 offset:56320
	global_load_lds_dwordx4 v146, s[98:99]
	s_add_i32 m0, s58, 0x2000
	s_add_u32 s56, s56, 0x80080
	s_addc_u32 s57, s57, 0
	s_add_i32 s58, s63, s70
	global_load_lds_dwordx4 v150, s[98:99]
	s_mov_b32 m0, s58
	s_nop 0
	global_load_lds_dwordx4 v146, s[56:57]
	s_add_i32 m0, s58, 0x2000
	s_nop 0
	global_load_lds_dwordx4 v150, s[56:57]
	s_mov_b32 m0, s79
	s_nop 0
	global_load_lds_dwordx4 v144, s[100:101]
	s_mov_b32 m0, s80
	s_nop 0
	global_load_lds_dwordx4 v148, s[100:101]
	s_waitcnt vmcnt(8) lgkmcnt(0)
	s_setprio 1
	s_barrier
	v_mfma_f32_16x16x32_bf16 v[60:63], v[128:131], v[206:209], v[60:63]
	v_mfma_f32_16x16x32_bf16 v[56:59], v[136:139], v[206:209], v[56:59]
	v_mfma_f32_16x16x32_bf16 v[44:47], v[128:131], v[214:217], v[44:47]
	v_mfma_f32_16x16x32_bf16 v[40:43], v[136:139], v[214:217], v[40:43]
	v_mfma_f32_16x16x32_bf16 v[28:31], v[128:131], v[222:225], v[28:31]
	v_mfma_f32_16x16x32_bf16 v[24:27], v[136:139], v[222:225], v[24:27]
	v_mfma_f32_16x16x32_bf16 v[12:15], v[128:131], v[230:233], v[12:15]
	v_mfma_f32_16x16x32_bf16 v[8:11], v[136:139], v[230:233], v[8:11]
	v_mfma_f32_16x16x32_bf16 v[60:63], v[132:135], v[210:213], v[60:63]
	v_mfma_f32_16x16x32_bf16 v[56:59], v[140:143], v[210:213], v[56:59]
	v_mfma_f32_16x16x32_bf16 v[44:47], v[132:135], v[218:221], v[44:47]
	v_mfma_f32_16x16x32_bf16 v[40:43], v[140:143], v[218:221], v[40:43]
	v_mfma_f32_16x16x32_bf16 v[28:31], v[132:135], v[226:229], v[28:31]
	v_mfma_f32_16x16x32_bf16 v[24:27], v[140:143], v[226:229], v[24:27]
	v_mfma_f32_16x16x32_bf16 v[12:15], v[132:135], v[234:237], v[12:15]
	v_mfma_f32_16x16x32_bf16 v[8:11], v[140:143], v[234:237], v[8:11]
	v_mfma_f32_16x16x32_bf16 v[52:55], v[182:185], v[206:209], v[52:55]
	v_mfma_f32_16x16x32_bf16 v[48:51], v[198:201], v[206:209], v[48:51]
	v_mfma_f32_16x16x32_bf16 v[36:39], v[182:185], v[214:217], v[36:39]
	v_mfma_f32_16x16x32_bf16 v[32:35], v[198:201], v[214:217], v[32:35]
	v_mfma_f32_16x16x32_bf16 v[20:23], v[182:185], v[222:225], v[20:23]
	v_mfma_f32_16x16x32_bf16 v[16:19], v[198:201], v[222:225], v[16:19]
	v_mfma_f32_16x16x32_bf16 v[4:7], v[182:185], v[230:233], v[4:7]
	v_mfma_f32_16x16x32_bf16 v[0:3], v[198:201], v[230:233], v[0:3]
	v_mfma_f32_16x16x32_bf16 v[52:55], v[194:197], v[210:213], v[52:55]
	v_mfma_f32_16x16x32_bf16 v[48:51], v[202:205], v[210:213], v[48:51]
	v_mfma_f32_16x16x32_bf16 v[36:39], v[194:197], v[218:221], v[36:39]
	v_mfma_f32_16x16x32_bf16 v[32:35], v[202:205], v[218:221], v[32:35]
	v_mfma_f32_16x16x32_bf16 v[20:23], v[194:197], v[226:229], v[20:23]
	v_mfma_f32_16x16x32_bf16 v[16:19], v[202:205], v[226:229], v[16:19]
	v_mfma_f32_16x16x32_bf16 v[4:7], v[194:197], v[234:237], v[4:7]
	s_setprio 0
	v_mfma_f32_16x16x32_bf16 v[0:3], v[202:205], v[234:237], v[0:3]
	s_barrier
	s_add_i32 s61, s61, 2
	s_add_u32 s54, s54, 0x100
	s_addc_u32 s55, s55, 0
	s_add_u32 s49, s49, 0x100
	s_addc_u32 s60, s60, 0
	s_cmp_gt_u32 s61, 29
	s_cbranch_scc0 .LBB0_457
	s_and_b64 vcc, exec, s[16:17]
	s_cbranch_vccz .LBB0_460
	s_barrier

; #define PG8_WAIT_V(n) asm volatile("s_waitcnt vmcnt(" #n ")" ::: "memory")
; #define PG8_WAIT_L(n) asm volatile("s_waitcnt lgkmcnt(" #n ")" ::: "memory")
; template <class Epi, bool FP8 = false>
; __device__ __forceinline__ void gemm_phase(LAS unsigned char* lds, const Gemm g, const StaticOrder& S_, const Epi& E, const int tid) {
;     ...
;         const bool has_next = S_.next(ui + 1, nxt);
;         const char* nA = has_next ? (const char*)g.A + (size_t)nxt.pm * tstepA : cA; const char* nB = has_next ? (const char*)g.Bt + (size_t)nxt.pn * tstepB : cB;
;         for (int t = 0; t < nt; t += 2) {
;             const bool last = (t == nt - 2);
;             const char* a1 = cA + (size_t)(t + 1) * kstep;
;             const char* a2 = last ? nA : cA + (size_t)(t + 2) * kstep; const char* b2 = last ? nB : cB + (size_t)(t + 2) * kstep;
;             const char* a3 = a2 + kstep; const char* b3 = b2 + kstep;
;             PG8_LDB(B0, 0, 0); PG8_LDB(B1, 0, 1); PG8_SCHED; PG8_LDA(At, 0, 0); PG8_STAGE(PG8_SA(1, 1), a1 + hstepA, voffA);
;             PG8_WAIT_V(8); PG8_WAIT_L(0); PG8_BAR; PG8_MMA(0, 0, At, B0); PG8_MMA(0, 1, At, B1); PG8_BAR; PG8_SCHED;
;             PG8_LDA(At, 0, 1); PG8_STAGE(PG8_SB(0, 0), b2, voffB); PG8_STAGE(PG8_SB(0, 1), b2 + hstepB, voffB); PG8_STAGE(PG8_SA(0, 0), a2, voffA);
;             PG8_WAIT_V(8); PG8_WAIT_L(0); PG8_BAR; PG8_MMA(1, 0, At, B0); PG8_MMA(1, 1, At, B1); PG8_BAR; PG8_SCHED;
;             PG8_LDB(B0, 1, 0); PG8_LDB(B1, 1, 1); PG8_SCHED; PG8_LDA(At, 1, 0); PG8_STAGE(PG8_SA(0, 1), a2 + hstepA, voffA);
;             PG8_WAIT_V(8); PG8_WAIT_L(0); PG8_BAR; PG8_MMA(0, 0, At, B0); PG8_MMA(0, 1, At, B1); PG8_BAR; PG8_SCHED;
;             PG8_LDA(At, 1, 1); PG8_STAGE(PG8_SB(1, 0), b3, voffB); PG8_STAGE(PG8_SB(1, 1), b3 + hstepB, voffB); PG8_STAGE(PG8_SA(1, 0), a3, voffA);
;             PG8_WAIT_V(8); PG8_WAIT_L(0); PG8_BAR; PG8_MMA(1, 0, At, B0); PG8_MMA(1, 1, At, B1); PG8_BAR; PG8_SCHED;
;         }
;         if (wr == 0) PG8_BAR;
;         E(acc, cur, wr, wc, fr, fq);
;         if (!has_next) break;
; #pragma unroll
;         for (int a = 0; a < 2; ++a)
; #pragma unroll
;             for (int b = 0; b < 2; ++b)
; #pragma unroll
;                 for (int m = 0; m < 4; ++m)
; #pragma unroll
;                     for (int n = 0; n < 2; ++n) acc[a][b][m][n] = (f32x4){0.f, 0.f, 0.f, 0.f};
;         cur = nxt; cA = nA; cB = nB; ++ui;
.LBB0_595:
	s_ashr_i32 s27, s26, 31
	s_lshl_b64 s[42:43], s[26:27], 19
	s_add_u32 s48, s3, s42
	s_addc_u32 s49, s35, s43
	s_and_b64 s[42:43], s[4:5], exec
	s_cselect_b32 s27, s49, s53
	s_cselect_b32 s42, s48, s52
	s_ashr_i32 s25, s24, 31
	s_lshl_b64 s[50:51], s[24:25], 19
	s_add_u32 s50, s58, s50
	s_addc_u32 s51, s59, s51
	s_and_b64 s[56:57], s[4:5], exec
	s_cselect_b32 s25, s51, s55
	s_cselect_b32 s43, s50, s54
	s_add_u32 s52, s52, 0x40080
	s_addc_u32 s53, s53, 0
	s_add_u32 s66, s54, 0x100
	v_mov_b32_e32 v0, 0
	s_addc_u32 s84, s55, 0
	s_mov_b32 s85, -2
	v_mov_b64_e32 v[0:1], 0
	v_mov_b64_e32 v[2:3], 0
	v_mov_b64_e32 v[4:5], 0
	v_mov_b64_e32 v[6:7], 0
	v_mov_b64_e32 v[8:9], 0
	v_mov_b64_e32 v[10:11], 0
	v_mov_b64_e32 v[12:13], 0
	v_mov_b64_e32 v[14:15], 0
	v_mov_b64_e32 v[16:17], 0
	v_mov_b64_e32 v[18:19], 0
	v_mov_b64_e32 v[20:21], 0
	v_mov_b64_e32 v[22:23], 0
	v_mov_b64_e32 v[24:25], 0
	v_mov_b64_e32 v[26:27], 0
	v_mov_b64_e32 v[28:29], 0
	v_mov_b64_e32 v[30:31], 0
	v_mov_b64_e32 v[32:33], 0
	v_mov_b64_e32 v[34:35], 0
	v_mov_b64_e32 v[36:37], 0
	v_mov_b64_e32 v[38:39], 0
	v_mov_b64_e32 v[40:41], 0
	v_mov_b64_e32 v[42:43], 0
	v_mov_b64_e32 v[44:45], 0
	v_mov_b64_e32 v[46:47], 0
	v_mov_b64_e32 v[48:49], 0
	v_mov_b64_e32 v[50:51], 0
	v_mov_b64_e32 v[52:53], 0
	v_mov_b64_e32 v[54:55], 0
	v_mov_b64_e32 v[56:57], 0
	v_mov_b64_e32 v[58:59], 0
	v_mov_b64_e32 v[60:61], 0
	v_mov_b64_e32 v[62:63], 0
	v_mov_b64_e32 v[64:65], 0
	v_mov_b64_e32 v[66:67], 0
	v_mov_b64_e32 v[68:69], 0
	v_mov_b64_e32 v[70:71], 0
	v_mov_b64_e32 v[72:73], 0
	v_mov_b64_e32 v[74:75], 0
	v_mov_b64_e32 v[76:77], 0
	v_mov_b64_e32 v[78:79], 0
	v_mov_b64_e32 v[80:81], 0
	v_mov_b64_e32 v[82:83], 0
	v_mov_b64_e32 v[84:85], 0
	v_mov_b64_e32 v[86:87], 0
	v_mov_b64_e32 v[88:89], 0
	v_mov_b64_e32 v[90:91], 0
	v_mov_b64_e32 v[92:93], 0
	v_mov_b64_e32 v[94:95], 0
	v_mov_b64_e32 v[96:97], 0
	v_mov_b64_e32 v[98:99], 0
	v_mov_b64_e32 v[100:101], 0
	v_mov_b64_e32 v[102:103], 0
	v_mov_b64_e32 v[104:105], 0
	v_mov_b64_e32 v[106:107], 0
	v_mov_b64_e32 v[108:109], 0
	v_mov_b64_e32 v[110:111], 0
	v_mov_b64_e32 v[112:113], 0
	v_mov_b64_e32 v[114:115], 0
	v_mov_b64_e32 v[116:117], 0
	v_mov_b64_e32 v[118:119], 0
	v_mov_b64_e32 v[120:121], 0
	v_mov_b64_e32 v[122:123], 0
	v_mov_b64_e32 v[124:125], 0
	v_mov_b64_e32 v[126:127], 0
.LBB0_596:
	ds_read_b128 v[156:159], v197 offset:1024
	ds_read_b128 v[152:155], v197
	ds_read_b128 v[148:151], v197 offset:3072
	ds_read_b128 v[144:147], v197 offset:2048
	ds_read_b128 v[140:143], v198 offset:1024
	ds_read_b128 v[136:139], v198
	ds_read_b128 v[132:135], v198 offset:3072
	ds_read_b128 v[128:131], v198 offset:2048
	s_add_u32 s54, s52, 0xfffc0080
	s_addc_u32 s55, s53, -1
	s_cmp_eq_u32 s85, 12
	s_cselect_b32 s57, s27, s55
	s_cselect_b32 s56, s42, s54
	s_cselect_b32 s55, s25, s84
	s_cselect_b32 s54, s43, s66
	s_add_i32 m0, s63, 0xc000
	ds_read_b128 v[186:189], v199
	ds_read_b128 v[190:193], v199 offset:1024
	ds_read_b128 v[200:203], v199 offset:2048
	ds_read_b128 v[204:207], v199 offset:3072
	ds_read_b128 v[208:211], v199 offset:4096
	ds_read_b128 v[212:215], v199 offset:5120
	ds_read_b128 v[216:219], v199 offset:6144
	ds_read_b128 v[220:223], v199 offset:7168
	global_load_lds_dwordx4 v178, s[52:53]
	s_add_i32 m0, s63, 0xe000
	s_nop 0
	global_load_lds_dwordx4 v180, s[52:53]
	s_waitcnt vmcnt(8) lgkmcnt(0)
	s_setprio 1
	s_barrier
	v_mfma_f32_16x16x128_f8f6f4 v[124:127], v[152:159], v[186:193], v[124:127]
	v_mfma_f32_16x16x128_f8f6f4 v[120:123], v[144:151], v[186:193], v[120:123]
	v_mfma_f32_16x16x128_f8f6f4 v[112:115], v[152:159], v[200:207], v[112:115]
	v_mfma_f32_16x16x128_f8f6f4 v[104:107], v[144:151], v[200:207], v[104:107]
	v_mfma_f32_16x16x128_f8f6f4 v[96:99], v[152:159], v[208:215], v[96:99]
	v_mfma_f32_16x16x128_f8f6f4 v[88:91], v[144:151], v[208:215], v[88:91]
	v_mfma_f32_16x16x128_f8f6f4 v[84:87], v[152:159], v[216:223], v[84:87]
	v_mfma_f32_16x16x128_f8f6f4 v[72:75], v[144:151], v[216:223], v[72:75]
	v_mfma_f32_16x16x128_f8f6f4 v[116:119], v[136:143], v[186:193], v[116:119]
	v_mfma_f32_16x16x128_f8f6f4 v[108:111], v[128:135], v[186:193], v[108:111]
	v_mfma_f32_16x16x128_f8f6f4 v[100:103], v[136:143], v[200:207], v[100:103]
	v_mfma_f32_16x16x128_f8f6f4 v[92:95], v[128:135], v[200:207], v[92:95]
	v_mfma_f32_16x16x128_f8f6f4 v[80:83], v[136:143], v[208:215], v[80:83]
	v_mfma_f32_16x16x128_f8f6f4 v[76:79], v[128:135], v[208:215], v[76:79]
	v_mfma_f32_16x16x128_f8f6f4 v[68:71], v[136:143], v[216:223], v[68:71]
	s_setprio 0
	v_mfma_f32_16x16x128_f8f6f4 v[64:67], v[128:135], v[216:223], v[64:67]
	s_barrier
	s_add_u32 s98, s54, s10
	s_addc_u32 s99, s55, s11
	s_add_u32 s100, s56, s10
	s_addc_u32 s101, s57, s11
	s_add_i32 s86, s74, s60
	s_mov_b32 m0, s86
	ds_read_b128 v[200:203], v199 offset:16384
	ds_read_b128 v[204:207], v199 offset:17408
	ds_read_b128 v[208:211], v199 offset:18432
	ds_read_b128 v[212:215], v199 offset:19456
	ds_read_b128 v[216:219], v199 offset:20480
	ds_read_b128 v[220:223], v199 offset:21504
	ds_read_b128 v[224:227], v199 offset:22528
	ds_read_b128 v[228:231], v199 offset:23552
	global_load_lds_dwordx4 v160, s[54:55]
	s_add_i32 m0, s86, 0x2000
	s_add_u32 s86, s54, 0x40000
	s_addc_u32 s87, s55, 0
	s_add_i32 s88, s75, s60
	global_load_lds_dwordx4 v162, s[54:55]
	s_mov_b32 m0, s88
	s_nop 0
	global_load_lds_dwordx4 v160, s[86:87]
	s_add_i32 m0, s88, 0x2000
	s_nop 0
	global_load_lds_dwordx4 v162, s[86:87]
	s_mov_b32 m0, s63
	s_nop 0
	global_load_lds_dwordx4 v166, s[56:57]
	s_mov_b32 m0, s68
	s_nop 0
	global_load_lds_dwordx4 v164, s[56:57]
	s_waitcnt vmcnt(8) lgkmcnt(0)
	s_setprio 1
	s_barrier
; #define PG8_STAGE(bufoff, gbase, voff) do { _Pragma("unroll") for (int _i = 0; _i < 2; ++_i) \
;         __builtin_amdgcn_global_load_lds((const unsigned*)((const char*)(gbase) + (voff)[_i]), (LAS unsigned*)(lds + (bufoff) + ldsw + _i * 8192), 16, 0, 0); } while (0)
; #define PG8_LDA(dst, b, h) do { _Pragma("unroll") for (int m = 0; m < 4; ++m) _Pragma("unroll") for (int k = 0; k < 2; ++k) dst[m][k] = *(const LAS bf16x8*)(lds + PG8_SA(b, h) + aoff + m * 2048 + k * 1024); } while (0)
; #define PG8_LDB(dst, b, h) do { _Pragma("unroll") for (int n = 0; n < 2; ++n) _Pragma("unroll") for (int k = 0; k < 2; ++k) dst[n][k] = *(const LAS bf16x8*)(lds + PG8_SB(b, h) + boff + n * 2048 + k * 1024); } while (0)
; #define PG8_WAIT_V(n) asm volatile("s_waitcnt vmcnt(" #n ")" ::: "memory")
; #define PG8_WAIT_L(n) asm volatile("s_waitcnt lgkmcnt(" #n ")" ::: "memory")
; #define PG8_BAR __builtin_amdgcn_s_barrier()
; #define PG8_SCHED __builtin_amdgcn_sched_barrier(0)
; template <class Epi, bool FP8 = false>
; __device__ __forceinline__ void gemm_phase(LAS unsigned char* lds, const Gemm g, const StaticOrder& S_, const Epi& E, const int tid) {
;     ...
;             PG8_WAIT_V(8); PG8_WAIT_L(0); PG8_BAR; PG8_MMA(1, 0, At, B0); PG8_MMA(1, 1, At, B1); PG8_BAR; PG8_SCHED;
;             PG8_LDB(B0, 1, 0); PG8_LDB(B1, 1, 1); PG8_SCHED; PG8_LDA(At, 1, 0); PG8_STAGE(PG8_SA(0, 1), a2 + hstepA, voffA);
;             PG8_WAIT_V(8); PG8_WAIT_L(0); PG8_BAR; PG8_MMA(0, 0, At, B0); PG8_MMA(0, 1, At, B1); PG8_BAR; PG8_SCHED;
;             PG8_LDA(At, 1, 1); PG8_STAGE(PG8_SB(1, 0), b3, voffB); PG8_STAGE(PG8_SB(1, 1), b3 + hstepB, voffB); PG8_STAGE(PG8_SA(1, 0), a3, voffA);
;             PG8_WAIT_V(8); PG8_WAIT_L(0); PG8_BAR; PG8_MMA(1, 0, At, B0); PG8_MMA(1, 1, At, B1); PG8_BAR; PG8_SCHED;
;         }
;         if (wr == 0) PG8_BAR;
	v_mfma_f32_16x16x128_f8f6f4 v[60:63], v[152:159], v[200:207], v[60:63]
	v_mfma_f32_16x16x128_f8f6f4 v[56:59], v[144:151], v[200:207], v[56:59]
	v_mfma_f32_16x16x128_f8f6f4 v[48:51], v[152:159], v[208:215], v[48:51]
	v_mfma_f32_16x16x128_f8f6f4 v[40:43], v[144:151], v[208:215], v[40:43]
	v_mfma_f32_16x16x128_f8f6f4 v[32:35], v[152:159], v[216:223], v[32:35]
	v_mfma_f32_16x16x128_f8f6f4 v[24:27], v[144:151], v[216:223], v[24:27]
	v_mfma_f32_16x16x128_f8f6f4 v[16:19], v[152:159], v[224:231], v[16:19]
	v_mfma_f32_16x16x128_f8f6f4 v[8:11], v[144:151], v[224:231], v[8:11]
	v_mfma_f32_16x16x128_f8f6f4 v[52:55], v[136:143], v[200:207], v[52:55]
	v_mfma_f32_16x16x128_f8f6f4 v[44:47], v[128:135], v[200:207], v[44:47]
	v_mfma_f32_16x16x128_f8f6f4 v[36:39], v[136:143], v[208:215], v[36:39]
	v_mfma_f32_16x16x128_f8f6f4 v[28:31], v[128:135], v[208:215], v[28:31]
	v_mfma_f32_16x16x128_f8f6f4 v[20:23], v[136:143], v[216:223], v[20:23]
	v_mfma_f32_16x16x128_f8f6f4 v[12:15], v[128:135], v[216:223], v[12:15]
	v_mfma_f32_16x16x128_f8f6f4 v[4:7], v[136:143], v[224:231], v[4:7]
	s_setprio 0
	v_mfma_f32_16x16x128_f8f6f4 v[0:3], v[128:135], v[224:231], v[0:3]
	s_barrier
	s_add_i32 s86, 0, 0x18000
	v_add_u32_e32 v128, s86, v195
	s_add_i32 s87, 0, 0x1c000
	ds_read_b128 v[156:159], v128 offset:1024
	ds_read_b128 v[152:155], v128
	ds_read_b128 v[148:151], v128 offset:3072
	ds_read_b128 v[144:147], v128 offset:2048
	v_add_u32_e32 v128, s87, v195
	ds_read_b128 v[140:143], v128 offset:1024
	ds_read_b128 v[136:139], v128
	ds_read_b128 v[132:135], v128 offset:3072
	ds_read_b128 v[128:131], v128 offset:2048
	s_add_u32 s56, s56, 0x40000
	s_addc_u32 s57, s57, 0
	s_mov_b32 m0, s69
	ds_read_b128 v[200:203], v199 offset:32768
	ds_read_b128 v[204:207], v199 offset:33792
	ds_read_b128 v[208:211], v199 offset:34816
	ds_read_b128 v[212:215], v199 offset:35840
	ds_read_b128 v[216:219], v199 offset:36864
	ds_read_b128 v[220:223], v199 offset:37888
	ds_read_b128 v[224:227], v199 offset:38912
	ds_read_b128 v[228:231], v199 offset:39936
	global_load_lds_dwordx4 v166, s[56:57]
	s_mov_b32 m0, s70
	s_nop 0
	global_load_lds_dwordx4 v164, s[56:57]
	s_waitcnt vmcnt(8) lgkmcnt(0)
	s_setprio 1
	s_barrier
	v_mfma_f32_16x16x128_f8f6f4 v[124:127], v[152:159], v[200:207], v[124:127]
	v_mfma_f32_16x16x128_f8f6f4 v[120:123], v[144:151], v[200:207], v[120:123]
	v_mfma_f32_16x16x128_f8f6f4 v[112:115], v[152:159], v[208:215], v[112:115]
	v_mfma_f32_16x16x128_f8f6f4 v[104:107], v[144:151], v[208:215], v[104:107]
	v_mfma_f32_16x16x128_f8f6f4 v[96:99], v[152:159], v[216:223], v[96:99]
	v_mfma_f32_16x16x128_f8f6f4 v[88:91], v[144:151], v[216:223], v[88:91]
	v_mfma_f32_16x16x128_f8f6f4 v[84:87], v[152:159], v[224:231], v[84:87]
	v_mfma_f32_16x16x128_f8f6f4 v[72:75], v[144:151], v[224:231], v[72:75]
	v_mfma_f32_16x16x128_f8f6f4 v[116:119], v[136:143], v[200:207], v[116:119]
	v_mfma_f32_16x16x128_f8f6f4 v[108:111], v[128:135], v[200:207], v[108:111]
	v_mfma_f32_16x16x128_f8f6f4 v[100:103], v[136:143], v[208:215], v[100:103]
	v_mfma_f32_16x16x128_f8f6f4 v[92:95], v[128:135], v[208:215], v[92:95]
	v_mfma_f32_16x16x128_f8f6f4 v[80:83], v[136:143], v[216:223], v[80:83]
	v_mfma_f32_16x16x128_f8f6f4 v[76:79], v[128:135], v[216:223], v[76:79]
	v_mfma_f32_16x16x128_f8f6f4 v[68:71], v[136:143], v[224:231], v[68:71]
	s_setprio 0
	v_mfma_f32_16x16x128_f8f6f4 v[64:67], v[128:135], v[224:231], v[64:67]
	s_barrier
	s_add_i32 s56, s86, s60
	s_mov_b32 m0, s56
	ds_read_b128 v[200:203], v199 offset:49152
	ds_read_b128 v[204:207], v199 offset:50176
	ds_read_b128 v[208:211], v199 offset:51200
	ds_read_b128 v[212:215], v199 offset:52224
	ds_read_b128 v[216:219], v199 offset:53248
	ds_read_b128 v[220:223], v199 offset:54272
	ds_read_b128 v[224:227], v199 offset:55296
	ds_read_b128 v[228:231], v199 offset:56320
	global_load_lds_dwordx4 v160, s[98:99]
	s_add_i32 m0, s56, 0x2000
	s_add_u32 s54, s54, 0x40080
	s_addc_u32 s55, s55, 0
	s_add_i32 s56, s87, s60
	global_load_lds_dwordx4 v162, s[98:99]
	s_mov_b32 m0, s56
	s_nop 0
	global_load_lds_dwordx4 v160, s[54:55]
	s_add_i32 m0, s56, 0x2000
	s_nop 0
	global_load_lds_dwordx4 v162, s[54:55]
	s_mov_b32 m0, s72
	s_nop 0
	global_load_lds_dwordx4 v166, s[100:101]
	s_mov_b32 m0, s73
	s_nop 0
	global_load_lds_dwordx4 v164, s[100:101]
	s_waitcnt vmcnt(8) lgkmcnt(0)
	s_setprio 1
	s_barrier
	v_mfma_f32_16x16x128_f8f6f4 v[60:63], v[152:159], v[200:207], v[60:63]
	v_mfma_f32_16x16x128_f8f6f4 v[56:59], v[144:151], v[200:207], v[56:59]
	v_mfma_f32_16x16x128_f8f6f4 v[48:51], v[152:159], v[208:215], v[48:51]
	v_mfma_f32_16x16x128_f8f6f4 v[40:43], v[144:151], v[208:215], v[40:43]
	v_mfma_f32_16x16x128_f8f6f4 v[32:35], v[152:159], v[216:223], v[32:35]
	v_mfma_f32_16x16x128_f8f6f4 v[24:27], v[144:151], v[216:223], v[24:27]
	v_mfma_f32_16x16x128_f8f6f4 v[16:19], v[152:159], v[224:231], v[16:19]
	v_mfma_f32_16x16x128_f8f6f4 v[8:11], v[144:151], v[224:231], v[8:11]
	v_mfma_f32_16x16x128_f8f6f4 v[52:55], v[136:143], v[200:207], v[52:55]
	v_mfma_f32_16x16x128_f8f6f4 v[44:47], v[128:135], v[200:207], v[44:47]
	v_mfma_f32_16x16x128_f8f6f4 v[36:39], v[136:143], v[208:215], v[36:39]
	v_mfma_f32_16x16x128_f8f6f4 v[28:31], v[128:135], v[208:215], v[28:31]
	v_mfma_f32_16x16x128_f8f6f4 v[20:23], v[136:143], v[216:223], v[20:23]
	v_mfma_f32_16x16x128_f8f6f4 v[12:15], v[128:135], v[216:223], v[12:15]
	v_mfma_f32_16x16x128_f8f6f4 v[4:7], v[136:143], v[224:231], v[4:7]
	s_setprio 0
	v_mfma_f32_16x16x128_f8f6f4 v[0:3], v[128:135], v[224:231], v[0:3]
	s_barrier
	s_add_i32 s85, s85, 2
	s_add_u32 s52, s52, 0x100
	s_addc_u32 s53, s53, 0
	s_add_u32 s66, s66, 0x100
	s_addc_u32 s84, s84, 0
	s_cmp_gt_u32 s85, 13
	s_cbranch_scc0 .LBB0_596
	s_and_b64 vcc, exec, s[12:13]
	s_cbranch_vccz .LBB0_599
	s_barrier

; #define PG8_WAIT_V(n) asm volatile("s_waitcnt vmcnt(" #n ")" ::: "memory")
; #define PG8_WAIT_L(n) asm volatile("s_waitcnt lgkmcnt(" #n ")" ::: "memory")
; template <class Epi, bool FP8 = false>
; __device__ __forceinline__ void gemm_phase(LAS unsigned char* lds, const Gemm g, const StaticOrder& S_, const Epi& E, const int tid) {
;     ...
;         const bool has_next = S_.next(ui + 1, nxt);
;         const char* nA = has_next ? (const char*)g.A + (size_t)nxt.pm * tstepA : cA; const char* nB = has_next ? (const char*)g.Bt + (size_t)nxt.pn * tstepB : cB;
;         for (int t = 0; t < nt; t += 2) {
;             const bool last = (t == nt - 2);
;             const char* a1 = cA + (size_t)(t + 1) * kstep;
;             const char* a2 = last ? nA : cA + (size_t)(t + 2) * kstep; const char* b2 = last ? nB : cB + (size_t)(t + 2) * kstep;
;             const char* a3 = a2 + kstep; const char* b3 = b2 + kstep;
;             PG8_LDB(B0, 0, 0); PG8_LDB(B1, 0, 1); PG8_SCHED; PG8_LDA(At, 0, 0); PG8_STAGE(PG8_SA(1, 1), a1 + hstepA, voffA);
;             PG8_WAIT_V(8); PG8_WAIT_L(0); PG8_BAR; PG8_MMA(0, 0, At, B0); PG8_MMA(0, 1, At, B1); PG8_BAR; PG8_SCHED;
;             PG8_LDA(At, 0, 1); PG8_STAGE(PG8_SB(0, 0), b2, voffB); PG8_STAGE(PG8_SB(0, 1), b2 + hstepB, voffB); PG8_STAGE(PG8_SA(0, 0), a2, voffA);
;             PG8_WAIT_V(8); PG8_WAIT_L(0); PG8_BAR; PG8_MMA(1, 0, At, B0); PG8_MMA(1, 1, At, B1); PG8_BAR; PG8_SCHED;
;             PG8_LDB(B0, 1, 0); PG8_LDB(B1, 1, 1); PG8_SCHED; PG8_LDA(At, 1, 0); PG8_STAGE(PG8_SA(0, 1), a2 + hstepA, voffA);
;             PG8_WAIT_V(8); PG8_WAIT_L(0); PG8_BAR; PG8_MMA(0, 0, At, B0); PG8_MMA(0, 1, At, B1); PG8_BAR; PG8_SCHED;
;             PG8_LDA(At, 1, 1); PG8_STAGE(PG8_SB(1, 0), b3, voffB); PG8_STAGE(PG8_SB(1, 1), b3 + hstepB, voffB); PG8_STAGE(PG8_SA(1, 0), a3, voffA);
;             PG8_WAIT_V(8); PG8_WAIT_L(0); PG8_BAR; PG8_MMA(1, 0, At, B0); PG8_MMA(1, 1, At, B1); PG8_BAR; PG8_SCHED;
;         }
;         if (wr == 0) PG8_BAR;
;         E(acc, cur, wr, wc, fr, fq);
;         if (!has_next) break;
; #pragma unroll
;         for (int a = 0; a < 2; ++a)
; #pragma unroll
;             for (int b = 0; b < 2; ++b)
; #pragma unroll
;                 for (int m = 0; m < 4; ++m)
; #pragma unroll
;                     for (int n = 0; n < 2; ++n) acc[a][b][m][n] = (f32x4){0.f, 0.f, 0.f, 0.f};
;         cur = nxt; cA = nA; cB = nB; ++ui;
.LBB0_1094:
	s_ashr_i32 s21, s20, 31
	s_lshl_b64 s[24:25], s[20:21], 19
	s_add_u32 s24, s51, s24
	s_addc_u32 s25, s52, s25
	s_and_b64 s[8:9], s[8:9], exec
	s_cselect_b32 s21, s25, s47
	s_cselect_b32 s66, s24, s46
	s_add_u32 s67, s46, 0x100
	v_mov_b32_e32 v0, 0
	s_addc_u32 s68, s47, 0
	s_mov_b32 s69, -2
	v_mov_b64_e32 v[0:1], 0
	v_mov_b64_e32 v[2:3], 0
	v_mov_b64_e32 v[4:5], 0
	v_mov_b64_e32 v[6:7], 0
	v_mov_b64_e32 v[8:9], 0
	v_mov_b64_e32 v[10:11], 0
	v_mov_b64_e32 v[12:13], 0
	v_mov_b64_e32 v[14:15], 0
	v_mov_b64_e32 v[16:17], 0
	v_mov_b64_e32 v[18:19], 0
	v_mov_b64_e32 v[20:21], 0
	v_mov_b64_e32 v[22:23], 0
	v_mov_b64_e32 v[24:25], 0
	v_mov_b64_e32 v[26:27], 0
	v_mov_b64_e32 v[28:29], 0
	v_mov_b64_e32 v[30:31], 0
	v_mov_b64_e32 v[32:33], 0
	v_mov_b64_e32 v[34:35], 0
	v_mov_b64_e32 v[36:37], 0
	v_mov_b64_e32 v[38:39], 0
	v_mov_b64_e32 v[40:41], 0
	v_mov_b64_e32 v[42:43], 0
	v_mov_b64_e32 v[44:45], 0
	v_mov_b64_e32 v[46:47], 0
	v_mov_b64_e32 v[48:49], 0
	v_mov_b64_e32 v[50:51], 0
	v_mov_b64_e32 v[52:53], 0
	v_mov_b64_e32 v[54:55], 0
	v_mov_b64_e32 v[56:57], 0
	v_mov_b64_e32 v[58:59], 0
	v_mov_b64_e32 v[60:61], 0
	v_mov_b64_e32 v[62:63], 0
	v_mov_b64_e32 v[64:65], 0
	v_mov_b64_e32 v[66:67], 0
	v_mov_b64_e32 v[68:69], 0
	v_mov_b64_e32 v[70:71], 0
	v_mov_b64_e32 v[72:73], 0
	v_mov_b64_e32 v[74:75], 0
	v_mov_b64_e32 v[76:77], 0
	v_mov_b64_e32 v[78:79], 0
	v_mov_b64_e32 v[80:81], 0
	v_mov_b64_e32 v[82:83], 0
	v_mov_b64_e32 v[84:85], 0
	v_mov_b64_e32 v[86:87], 0
	v_mov_b64_e32 v[88:89], 0
	v_mov_b64_e32 v[90:91], 0
	v_mov_b64_e32 v[92:93], 0
	v_mov_b64_e32 v[94:95], 0
	v_mov_b64_e32 v[96:97], 0
	v_mov_b64_e32 v[98:99], 0
	v_mov_b64_e32 v[100:101], 0
	v_mov_b64_e32 v[102:103], 0
	v_mov_b64_e32 v[104:105], 0
	v_mov_b64_e32 v[106:107], 0
	v_mov_b64_e32 v[108:109], 0
	v_mov_b64_e32 v[110:111], 0
	v_mov_b64_e32 v[112:113], 0
	v_mov_b64_e32 v[114:115], 0
	v_mov_b64_e32 v[116:117], 0
	v_mov_b64_e32 v[118:119], 0
	v_mov_b64_e32 v[120:121], 0
	v_mov_b64_e32 v[122:123], 0
	v_mov_b64_e32 v[124:125], 0
	v_mov_b64_e32 v[126:127], 0
.LBB0_1095:
	ds_read_b128 v[144:147], v174
	ds_read_b128 v[178:181], v174 offset:1024
	ds_read_b128 v[182:185], v174 offset:2048
	ds_read_b128 v[186:189], v174 offset:3072
	ds_read_b128 v[190:193], v175
	ds_read_b128 v[194:197], v175 offset:1024
	ds_read_b128 v[198:201], v175 offset:2048
	ds_read_b128 v[202:205], v175 offset:3072
	s_add_u32 s8, s26, 0x100
	s_addc_u32 s9, s27, 0
	s_cmp_eq_u32 s69, 12
	s_cselect_b32 s49, s23, s9
	s_cselect_b32 s48, s22, s8
	s_cselect_b32 s47, s21, s68
	s_cselect_b32 s46, s66, s67
	s_add_i32 m0, s54, 0xc000
	ds_read_b128 v[206:209], v176
	ds_read_b128 v[210:213], v176 offset:1024
	ds_read_b128 v[214:217], v176 offset:2048
	ds_read_b128 v[218:221], v176 offset:3072
	ds_read_b128 v[222:225], v176 offset:4096
	ds_read_b128 v[226:229], v176 offset:5120
	ds_read_b128 v[230:233], v176 offset:6144
	ds_read_b128 v[234:237], v176 offset:7168
	global_load_lds_dwordx4 v136, s[26:27]
	s_add_i32 m0, s54, 0xe000
	s_nop 0
	global_load_lds_dwordx4 v138, s[26:27]
	s_waitcnt vmcnt(8) lgkmcnt(0)
	s_setprio 1
	s_barrier
	v_mfma_f32_16x16x32_bf16 v[124:127], v[144:147], v[206:209], v[124:127]
	v_mfma_f32_16x16x32_bf16 v[120:123], v[182:185], v[206:209], v[120:123]
	v_mfma_f32_16x16x32_bf16 v[108:111], v[144:147], v[214:217], v[108:111]
	v_mfma_f32_16x16x32_bf16 v[104:107], v[182:185], v[214:217], v[104:107]
	v_mfma_f32_16x16x32_bf16 v[92:95], v[144:147], v[222:225], v[92:95]
	v_mfma_f32_16x16x32_bf16 v[88:91], v[182:185], v[222:225], v[88:91]
	v_mfma_f32_16x16x32_bf16 v[76:79], v[144:147], v[230:233], v[76:79]
	v_mfma_f32_16x16x32_bf16 v[72:75], v[182:185], v[230:233], v[72:75]
	v_mfma_f32_16x16x32_bf16 v[124:127], v[178:181], v[210:213], v[124:127]
	v_mfma_f32_16x16x32_bf16 v[120:123], v[186:189], v[210:213], v[120:123]
	v_mfma_f32_16x16x32_bf16 v[108:111], v[178:181], v[218:221], v[108:111]
	v_mfma_f32_16x16x32_bf16 v[104:107], v[186:189], v[218:221], v[104:107]
	v_mfma_f32_16x16x32_bf16 v[92:95], v[178:181], v[226:229], v[92:95]
	v_mfma_f32_16x16x32_bf16 v[88:91], v[186:189], v[226:229], v[88:91]
	v_mfma_f32_16x16x32_bf16 v[76:79], v[178:181], v[234:237], v[76:79]
	v_mfma_f32_16x16x32_bf16 v[72:75], v[186:189], v[234:237], v[72:75]
	v_mfma_f32_16x16x32_bf16 v[116:119], v[190:193], v[206:209], v[116:119]
	v_mfma_f32_16x16x32_bf16 v[112:115], v[198:201], v[206:209], v[112:115]
	v_mfma_f32_16x16x32_bf16 v[100:103], v[190:193], v[214:217], v[100:103]
	v_mfma_f32_16x16x32_bf16 v[96:99], v[198:201], v[214:217], v[96:99]
	v_mfma_f32_16x16x32_bf16 v[84:87], v[190:193], v[222:225], v[84:87]
	v_mfma_f32_16x16x32_bf16 v[80:83], v[198:201], v[222:225], v[80:83]
	v_mfma_f32_16x16x32_bf16 v[68:71], v[190:193], v[230:233], v[68:71]
	v_mfma_f32_16x16x32_bf16 v[64:67], v[198:201], v[230:233], v[64:67]
	v_mfma_f32_16x16x32_bf16 v[116:119], v[194:197], v[210:213], v[116:119]
	v_mfma_f32_16x16x32_bf16 v[112:115], v[202:205], v[210:213], v[112:115]
	v_mfma_f32_16x16x32_bf16 v[100:103], v[194:197], v[218:221], v[100:103]
	v_mfma_f32_16x16x32_bf16 v[96:99], v[202:205], v[218:221], v[96:99]
	v_mfma_f32_16x16x32_bf16 v[84:87], v[194:197], v[226:229], v[84:87]
	v_mfma_f32_16x16x32_bf16 v[80:83], v[202:205], v[226:229], v[80:83]
	v_mfma_f32_16x16x32_bf16 v[68:71], v[194:197], v[234:237], v[68:71]
	s_setprio 0
	v_mfma_f32_16x16x32_bf16 v[64:67], v[202:205], v[234:237], v[64:67]
	s_barrier
; #define PG8_STAGE(bufoff, gbase, voff) do { _Pragma("unroll") for (int _i = 0; _i < 2; ++_i) \
;         __builtin_amdgcn_global_load_lds((const unsigned*)((const char*)(gbase) + (voff)[_i]), (LAS unsigned*)(lds + (bufoff) + ldsw + _i * 8192), 16, 0, 0); } while (0)
; #define PG8_LDA(dst, b, h) do { _Pragma("unroll") for (int m = 0; m < 4; ++m) _Pragma("unroll") for (int k = 0; k < 2; ++k) dst[m][k] = *(const LAS bf16x8*)(lds + PG8_SA(b, h) + aoff + m * 2048 + k * 1024); } while (0)
; #define PG8_LDB(dst, b, h) do { _Pragma("unroll") for (int n = 0; n < 2; ++n) _Pragma("unroll") for (int k = 0; k < 2; ++k) dst[n][k] = *(const LAS bf16x8*)(lds + PG8_SB(b, h) + boff + n * 2048 + k * 1024); } while (0)
; #define PG8_WAIT_V(n) asm volatile("s_waitcnt vmcnt(" #n ")" ::: "memory")
; #define PG8_WAIT_L(n) asm volatile("s_waitcnt lgkmcnt(" #n ")" ::: "memory")
; #define PG8_BAR __builtin_amdgcn_s_barrier()
; #define PG8_SCHED __builtin_amdgcn_sched_barrier(0)
; template <class Epi, bool FP8 = false>
; __device__ __forceinline__ void gemm_phase(LAS unsigned char* lds, const Gemm g, const StaticOrder& S_, const Epi& E, const int tid) {
;     ...
;             PG8_LDA(At, 0, 1); PG8_STAGE(PG8_SB(0, 0), b2, voffB); PG8_STAGE(PG8_SB(0, 1), b2 + hstepB, voffB); PG8_STAGE(PG8_SA(0, 0), a2, voffA);
;             PG8_WAIT_V(8); PG8_WAIT_L(0); PG8_BAR; PG8_MMA(1, 0, At, B0); PG8_MMA(1, 1, At, B1); PG8_BAR; PG8_SCHED;
;             PG8_LDB(B0, 1, 0); PG8_LDB(B1, 1, 1); PG8_SCHED; PG8_LDA(At, 1, 0); PG8_STAGE(PG8_SA(0, 1), a2 + hstepA, voffA);
;             PG8_WAIT_V(8); PG8_WAIT_L(0); PG8_BAR; PG8_MMA(0, 0, At, B0); PG8_MMA(0, 1, At, B1); PG8_BAR; PG8_SCHED;
	s_add_u32 s98, s46, s16
	s_addc_u32 s99, s47, s17
	s_add_u32 s100, s48, s16
	s_addc_u32 s101, s49, s17
	s_add_i32 s26, s61, s53
	s_mov_b32 m0, s26
	ds_read_b128 v[206:209], v176 offset:16384
	ds_read_b128 v[210:213], v176 offset:17408
	ds_read_b128 v[214:217], v176 offset:18432
	ds_read_b128 v[218:221], v176 offset:19456
	ds_read_b128 v[222:225], v176 offset:20480
	ds_read_b128 v[226:229], v176 offset:21504
	ds_read_b128 v[230:233], v176 offset:22528
	ds_read_b128 v[234:237], v176 offset:23552
	global_load_lds_dwordx4 v132, s[46:47]
	s_add_i32 m0, s26, 0x2000
	s_add_u32 s26, s46, 0x40000
	s_addc_u32 s27, s47, 0
	s_add_i32 s70, s62, s53
	global_load_lds_dwordx4 v134, s[46:47]
	s_mov_b32 m0, s70
	s_nop 0
	global_load_lds_dwordx4 v132, s[26:27]
	s_add_i32 m0, s70, 0x2000
	s_nop 0
	global_load_lds_dwordx4 v134, s[26:27]
	s_mov_b32 m0, s54
	s_nop 0
	global_load_lds_dwordx4 v128, s[48:49]
	s_mov_b32 m0, s55
	s_nop 0
	global_load_lds_dwordx4 v130, s[48:49]
	s_waitcnt vmcnt(8) lgkmcnt(0)
	s_setprio 1
	s_barrier
	v_mfma_f32_16x16x32_bf16 v[60:63], v[144:147], v[206:209], v[60:63]
	v_mfma_f32_16x16x32_bf16 v[56:59], v[182:185], v[206:209], v[56:59]
	v_mfma_f32_16x16x32_bf16 v[44:47], v[144:147], v[214:217], v[44:47]
	v_mfma_f32_16x16x32_bf16 v[40:43], v[182:185], v[214:217], v[40:43]
	v_mfma_f32_16x16x32_bf16 v[28:31], v[144:147], v[222:225], v[28:31]
	v_mfma_f32_16x16x32_bf16 v[24:27], v[182:185], v[222:225], v[24:27]
	v_mfma_f32_16x16x32_bf16 v[12:15], v[144:147], v[230:233], v[12:15]
	v_mfma_f32_16x16x32_bf16 v[8:11], v[182:185], v[230:233], v[8:11]
	v_mfma_f32_16x16x32_bf16 v[60:63], v[178:181], v[210:213], v[60:63]
	v_mfma_f32_16x16x32_bf16 v[56:59], v[186:189], v[210:213], v[56:59]
	v_mfma_f32_16x16x32_bf16 v[44:47], v[178:181], v[218:221], v[44:47]
	v_mfma_f32_16x16x32_bf16 v[40:43], v[186:189], v[218:221], v[40:43]
	v_mfma_f32_16x16x32_bf16 v[28:31], v[178:181], v[226:229], v[28:31]
	v_mfma_f32_16x16x32_bf16 v[24:27], v[186:189], v[226:229], v[24:27]
	v_mfma_f32_16x16x32_bf16 v[12:15], v[178:181], v[234:237], v[12:15]
	v_mfma_f32_16x16x32_bf16 v[8:11], v[186:189], v[234:237], v[8:11]
	v_mfma_f32_16x16x32_bf16 v[52:55], v[190:193], v[206:209], v[52:55]
	v_mfma_f32_16x16x32_bf16 v[48:51], v[198:201], v[206:209], v[48:51]
	v_mfma_f32_16x16x32_bf16 v[36:39], v[190:193], v[214:217], v[36:39]
	v_mfma_f32_16x16x32_bf16 v[32:35], v[198:201], v[214:217], v[32:35]
	v_mfma_f32_16x16x32_bf16 v[20:23], v[190:193], v[222:225], v[20:23]
	v_mfma_f32_16x16x32_bf16 v[16:19], v[198:201], v[222:225], v[16:19]
	v_mfma_f32_16x16x32_bf16 v[4:7], v[190:193], v[230:233], v[4:7]
	v_mfma_f32_16x16x32_bf16 v[0:3], v[198:201], v[230:233], v[0:3]
	v_mfma_f32_16x16x32_bf16 v[52:55], v[194:197], v[210:213], v[52:55]
	v_mfma_f32_16x16x32_bf16 v[48:51], v[202:205], v[210:213], v[48:51]
	v_mfma_f32_16x16x32_bf16 v[36:39], v[194:197], v[218:221], v[36:39]
	v_mfma_f32_16x16x32_bf16 v[32:35], v[202:205], v[218:221], v[32:35]
	v_mfma_f32_16x16x32_bf16 v[20:23], v[194:197], v[226:229], v[20:23]
	v_mfma_f32_16x16x32_bf16 v[16:19], v[202:205], v[226:229], v[16:19]
	v_mfma_f32_16x16x32_bf16 v[4:7], v[194:197], v[234:237], v[4:7]
	s_setprio 0
	v_mfma_f32_16x16x32_bf16 v[0:3], v[202:205], v[234:237], v[0:3]
	s_barrier
	s_add_i32 s70, 0, 0x18000
	v_add_u32_e32 v177, s70, v172
	s_add_i32 s71, 0, 0x1c000
	ds_read_b128 v[144:147], v177
	ds_read_b128 v[178:181], v177 offset:1024
	ds_read_b128 v[182:185], v177 offset:2048
	ds_read_b128 v[186:189], v177 offset:3072
	v_add_u32_e32 v177, s71, v172
	ds_read_b128 v[190:193], v177
	ds_read_b128 v[194:197], v177 offset:1024
	ds_read_b128 v[198:201], v177 offset:2048
	ds_read_b128 v[202:205], v177 offset:3072
	s_add_u32 s26, s48, 0x60000
	s_addc_u32 s27, s49, 0
	s_mov_b32 m0, s56
	ds_read_b128 v[206:209], v176 offset:32768
	ds_read_b128 v[210:213], v176 offset:33792
	ds_read_b128 v[214:217], v176 offset:34816
	ds_read_b128 v[218:221], v176 offset:35840
	ds_read_b128 v[222:225], v176 offset:36864
	ds_read_b128 v[226:229], v176 offset:37888
	ds_read_b128 v[230:233], v176 offset:38912
	ds_read_b128 v[234:237], v176 offset:39936
	global_load_lds_dwordx4 v128, s[26:27]
	s_mov_b32 m0, s57
	s_nop 0
	global_load_lds_dwordx4 v130, s[26:27]
	s_waitcnt vmcnt(8) lgkmcnt(0)
	s_setprio 1
	s_barrier
; #define PG8_STAGE(bufoff, gbase, voff) do { _Pragma("unroll") for (int _i = 0; _i < 2; ++_i) \
;         __builtin_amdgcn_global_load_lds((const unsigned*)((const char*)(gbase) + (voff)[_i]), (LAS unsigned*)(lds + (bufoff) + ldsw + _i * 8192), 16, 0, 0); } while (0)
; #define PG8_LDA(dst, b, h) do { _Pragma("unroll") for (int m = 0; m < 4; ++m) _Pragma("unroll") for (int k = 0; k < 2; ++k) dst[m][k] = *(const LAS bf16x8*)(lds + PG8_SA(b, h) + aoff + m * 2048 + k * 1024); } while (0)
; #define PG8_WAIT_V(n) asm volatile("s_waitcnt vmcnt(" #n ")" ::: "memory")
; #define PG8_WAIT_L(n) asm volatile("s_waitcnt lgkmcnt(" #n ")" ::: "memory")
; #define PG8_BAR __builtin_amdgcn_s_barrier()
; #define PG8_SCHED __builtin_amdgcn_sched_barrier(0)
; template <class Epi, bool FP8 = false>
; __device__ __forceinline__ void gemm_phase(LAS unsigned char* lds, const Gemm g, const StaticOrder& S_, const Epi& E, const int tid) {
;     ...
;             PG8_WAIT_V(8); PG8_WAIT_L(0); PG8_BAR; PG8_MMA(0, 0, At, B0); PG8_MMA(0, 1, At, B1); PG8_BAR; PG8_SCHED;
;             PG8_LDA(At, 1, 1); PG8_STAGE(PG8_SB(1, 0), b3, voffB); PG8_STAGE(PG8_SB(1, 1), b3 + hstepB, voffB); PG8_STAGE(PG8_SA(1, 0), a3, voffA);
;             PG8_WAIT_V(8); PG8_WAIT_L(0); PG8_BAR; PG8_MMA(1, 0, At, B0); PG8_MMA(1, 1, At, B1); PG8_BAR; PG8_SCHED;
;         }
;         if (wr == 0) PG8_BAR;
	v_mfma_f32_16x16x32_bf16 v[124:127], v[144:147], v[206:209], v[124:127]
	v_mfma_f32_16x16x32_bf16 v[120:123], v[182:185], v[206:209], v[120:123]
	v_mfma_f32_16x16x32_bf16 v[108:111], v[144:147], v[214:217], v[108:111]
	v_mfma_f32_16x16x32_bf16 v[104:107], v[182:185], v[214:217], v[104:107]
	v_mfma_f32_16x16x32_bf16 v[92:95], v[144:147], v[222:225], v[92:95]
	v_mfma_f32_16x16x32_bf16 v[88:91], v[182:185], v[222:225], v[88:91]
	v_mfma_f32_16x16x32_bf16 v[76:79], v[144:147], v[230:233], v[76:79]
	v_mfma_f32_16x16x32_bf16 v[72:75], v[182:185], v[230:233], v[72:75]
	v_mfma_f32_16x16x32_bf16 v[124:127], v[178:181], v[210:213], v[124:127]
	v_mfma_f32_16x16x32_bf16 v[120:123], v[186:189], v[210:213], v[120:123]
	v_mfma_f32_16x16x32_bf16 v[108:111], v[178:181], v[218:221], v[108:111]
	v_mfma_f32_16x16x32_bf16 v[104:107], v[186:189], v[218:221], v[104:107]
	v_mfma_f32_16x16x32_bf16 v[92:95], v[178:181], v[226:229], v[92:95]
	v_mfma_f32_16x16x32_bf16 v[88:91], v[186:189], v[226:229], v[88:91]
	v_mfma_f32_16x16x32_bf16 v[76:79], v[178:181], v[234:237], v[76:79]
	v_mfma_f32_16x16x32_bf16 v[72:75], v[186:189], v[234:237], v[72:75]
	v_mfma_f32_16x16x32_bf16 v[116:119], v[190:193], v[206:209], v[116:119]
	v_mfma_f32_16x16x32_bf16 v[112:115], v[198:201], v[206:209], v[112:115]
	v_mfma_f32_16x16x32_bf16 v[100:103], v[190:193], v[214:217], v[100:103]
	v_mfma_f32_16x16x32_bf16 v[96:99], v[198:201], v[214:217], v[96:99]
	v_mfma_f32_16x16x32_bf16 v[84:87], v[190:193], v[222:225], v[84:87]
	v_mfma_f32_16x16x32_bf16 v[80:83], v[198:201], v[222:225], v[80:83]
	v_mfma_f32_16x16x32_bf16 v[68:71], v[190:193], v[230:233], v[68:71]
	v_mfma_f32_16x16x32_bf16 v[64:67], v[198:201], v[230:233], v[64:67]
	v_mfma_f32_16x16x32_bf16 v[116:119], v[194:197], v[210:213], v[116:119]
	v_mfma_f32_16x16x32_bf16 v[112:115], v[202:205], v[210:213], v[112:115]
	v_mfma_f32_16x16x32_bf16 v[100:103], v[194:197], v[218:221], v[100:103]
	v_mfma_f32_16x16x32_bf16 v[96:99], v[202:205], v[218:221], v[96:99]
	v_mfma_f32_16x16x32_bf16 v[84:87], v[194:197], v[226:229], v[84:87]
	v_mfma_f32_16x16x32_bf16 v[80:83], v[202:205], v[226:229], v[80:83]
	v_mfma_f32_16x16x32_bf16 v[68:71], v[194:197], v[234:237], v[68:71]
	s_setprio 0
	v_mfma_f32_16x16x32_bf16 v[64:67], v[202:205], v[234:237], v[64:67]
	s_barrier
	s_add_i32 s26, s70, s53
	s_mov_b32 m0, s26
	ds_read_b128 v[206:209], v176 offset:49152
	ds_read_b128 v[210:213], v176 offset:50176
	ds_read_b128 v[214:217], v176 offset:51200
	ds_read_b128 v[218:221], v176 offset:52224
	ds_read_b128 v[222:225], v176 offset:53248
	ds_read_b128 v[226:229], v176 offset:54272
	ds_read_b128 v[230:233], v176 offset:55296
	ds_read_b128 v[234:237], v176 offset:56320
	global_load_lds_dwordx4 v132, s[98:99]
	s_add_i32 m0, s26, 0x2000
	s_add_u32 s26, s46, 0x40080
	s_addc_u32 s27, s47, 0
	s_add_i32 s46, s71, s53
	global_load_lds_dwordx4 v134, s[98:99]
	s_mov_b32 m0, s46
	s_nop 0
	global_load_lds_dwordx4 v132, s[26:27]
	s_add_i32 m0, s46, 0x2000
	s_nop 0
	global_load_lds_dwordx4 v134, s[26:27]
	s_mov_b32 m0, s59
	s_nop 0
	global_load_lds_dwordx4 v128, s[100:101]
	s_mov_b32 m0, s60
	s_nop 0
	global_load_lds_dwordx4 v130, s[100:101]
	s_waitcnt vmcnt(8) lgkmcnt(0)
	s_setprio 1
	s_barrier
	v_mfma_f32_16x16x32_bf16 v[60:63], v[144:147], v[206:209], v[60:63]
	v_mfma_f32_16x16x32_bf16 v[56:59], v[182:185], v[206:209], v[56:59]
	v_mfma_f32_16x16x32_bf16 v[44:47], v[144:147], v[214:217], v[44:47]
	v_mfma_f32_16x16x32_bf16 v[40:43], v[182:185], v[214:217], v[40:43]
	v_mfma_f32_16x16x32_bf16 v[28:31], v[144:147], v[222:225], v[28:31]
	v_mfma_f32_16x16x32_bf16 v[24:27], v[182:185], v[222:225], v[24:27]
	v_mfma_f32_16x16x32_bf16 v[12:15], v[144:147], v[230:233], v[12:15]
	v_mfma_f32_16x16x32_bf16 v[8:11], v[182:185], v[230:233], v[8:11]
	v_mfma_f32_16x16x32_bf16 v[60:63], v[178:181], v[210:213], v[60:63]
	v_mfma_f32_16x16x32_bf16 v[56:59], v[186:189], v[210:213], v[56:59]
	v_mfma_f32_16x16x32_bf16 v[44:47], v[178:181], v[218:221], v[44:47]
	v_mfma_f32_16x16x32_bf16 v[40:43], v[186:189], v[218:221], v[40:43]
	v_mfma_f32_16x16x32_bf16 v[28:31], v[178:181], v[226:229], v[28:31]
	v_mfma_f32_16x16x32_bf16 v[24:27], v[186:189], v[226:229], v[24:27]
	v_mfma_f32_16x16x32_bf16 v[12:15], v[178:181], v[234:237], v[12:15]
	v_mfma_f32_16x16x32_bf16 v[8:11], v[186:189], v[234:237], v[8:11]
	v_mfma_f32_16x16x32_bf16 v[52:55], v[190:193], v[206:209], v[52:55]
	v_mfma_f32_16x16x32_bf16 v[48:51], v[198:201], v[206:209], v[48:51]
	v_mfma_f32_16x16x32_bf16 v[36:39], v[190:193], v[214:217], v[36:39]
	v_mfma_f32_16x16x32_bf16 v[32:35], v[198:201], v[214:217], v[32:35]
	v_mfma_f32_16x16x32_bf16 v[20:23], v[190:193], v[222:225], v[20:23]
	v_mfma_f32_16x16x32_bf16 v[16:19], v[198:201], v[222:225], v[16:19]
	v_mfma_f32_16x16x32_bf16 v[4:7], v[190:193], v[230:233], v[4:7]
	v_mfma_f32_16x16x32_bf16 v[0:3], v[198:201], v[230:233], v[0:3]
	v_mfma_f32_16x16x32_bf16 v[52:55], v[194:197], v[210:213], v[52:55]
	v_mfma_f32_16x16x32_bf16 v[48:51], v[202:205], v[210:213], v[48:51]
	v_mfma_f32_16x16x32_bf16 v[36:39], v[194:197], v[218:221], v[36:39]
	v_mfma_f32_16x16x32_bf16 v[32:35], v[202:205], v[218:221], v[32:35]
	v_mfma_f32_16x16x32_bf16 v[20:23], v[194:197], v[226:229], v[20:23]
	v_mfma_f32_16x16x32_bf16 v[16:19], v[202:205], v[226:229], v[16:19]
	v_mfma_f32_16x16x32_bf16 v[4:7], v[194:197], v[234:237], v[4:7]
	s_setprio 0
	v_mfma_f32_16x16x32_bf16 v[0:3], v[202:205], v[234:237], v[0:3]
	s_barrier
	s_add_i32 s69, s69, 2
	s_add_u32 s67, s67, 0x100
	s_addc_u32 s68, s68, 0
	s_cmp_gt_u32 s69, 13
	s_mov_b64 s[26:27], s[8:9]
	s_cbranch_scc0 .LBB0_1095
	s_and_b64 vcc, exec, s[18:19]
	s_cbranch_vccz .LBB0_1098
	s_barrier

; #define PG8_WAIT_V(n) asm volatile("s_waitcnt vmcnt(" #n ")" ::: "memory")
; #define PG8_WAIT_L(n) asm volatile("s_waitcnt lgkmcnt(" #n ")" ::: "memory")
; template <class Epi, bool FP8 = false>
; __device__ __forceinline__ void gemm_phase(LAS unsigned char* lds, const Gemm g, const StaticOrder& S_, const Epi& E, const int tid) {
;     ...
;         const bool has_next = S_.next(ui + 1, nxt);
;         const char* nA = has_next ? (const char*)g.A + (size_t)nxt.pm * tstepA : cA; const char* nB = has_next ? (const char*)g.Bt + (size_t)nxt.pn * tstepB : cB;
;         for (int t = 0; t < nt; t += 2) {
;             const bool last = (t == nt - 2);
;             const char* a1 = cA + (size_t)(t + 1) * kstep;
;             const char* a2 = last ? nA : cA + (size_t)(t + 2) * kstep; const char* b2 = last ? nB : cB + (size_t)(t + 2) * kstep;
;             const char* a3 = a2 + kstep; const char* b3 = b2 + kstep;
;             PG8_LDB(B0, 0, 0); PG8_LDB(B1, 0, 1); PG8_SCHED; PG8_LDA(At, 0, 0); PG8_STAGE(PG8_SA(1, 1), a1 + hstepA, voffA);
;             PG8_WAIT_V(8); PG8_WAIT_L(0); PG8_BAR; PG8_MMA(0, 0, At, B0); PG8_MMA(0, 1, At, B1); PG8_BAR; PG8_SCHED;
;             PG8_LDA(At, 0, 1); PG8_STAGE(PG8_SB(0, 0), b2, voffB); PG8_STAGE(PG8_SB(0, 1), b2 + hstepB, voffB); PG8_STAGE(PG8_SA(0, 0), a2, voffA);
;             PG8_WAIT_V(8); PG8_WAIT_L(0); PG8_BAR; PG8_MMA(1, 0, At, B0); PG8_MMA(1, 1, At, B1); PG8_BAR; PG8_SCHED;
;             PG8_LDB(B0, 1, 0); PG8_LDB(B1, 1, 1); PG8_SCHED; PG8_LDA(At, 1, 0); PG8_STAGE(PG8_SA(0, 1), a2 + hstepA, voffA);
;             PG8_WAIT_V(8); PG8_WAIT_L(0); PG8_BAR; PG8_MMA(0, 0, At, B0); PG8_MMA(0, 1, At, B1); PG8_BAR; PG8_SCHED;
;             PG8_LDA(At, 1, 1); PG8_STAGE(PG8_SB(1, 0), b3, voffB); PG8_STAGE(PG8_SB(1, 1), b3 + hstepB, voffB); PG8_STAGE(PG8_SA(1, 0), a3, voffA);
;             PG8_WAIT_V(8); PG8_WAIT_L(0); PG8_BAR; PG8_MMA(1, 0, At, B0); PG8_MMA(1, 1, At, B1); PG8_BAR; PG8_SCHED;
;         }
;         if (wr == 0) PG8_BAR;
;         E(acc, cur, wr, wc, fr, fq);
;         if (!has_next) break;
; #pragma unroll
;         for (int a = 0; a < 2; ++a)
; #pragma unroll
;             for (int b = 0; b < 2; ++b)
; #pragma unroll
;                 for (int m = 0; m < 4; ++m)
; #pragma unroll
;                     for (int n = 0; n < 2; ++n) acc[a][b][m][n] = (f32x4){0.f, 0.f, 0.f, 0.f};
;         cur = nxt; cA = nA; cB = nB; ++ui;
.LBB0_1120:
	s_ashr_i32 s21, s20, 31
	s_lshl_b64 s[24:25], s[20:21], 18
	s_add_u32 s24, s51, s24
	s_addc_u32 s25, s52, s25
	s_and_b64 s[8:9], s[8:9], exec
	s_cselect_b32 s21, s25, s47
	s_cselect_b32 s66, s24, s46
	s_add_u32 s67, s46, 0x100
	v_mov_b32_e32 v0, 0
	s_addc_u32 s68, s47, 0
	s_mov_b32 s69, -2
	v_mov_b64_e32 v[0:1], 0
	v_mov_b64_e32 v[2:3], 0
	v_mov_b64_e32 v[4:5], 0
	v_mov_b64_e32 v[6:7], 0
	v_mov_b64_e32 v[8:9], 0
	v_mov_b64_e32 v[10:11], 0
	v_mov_b64_e32 v[12:13], 0
	v_mov_b64_e32 v[14:15], 0
	v_mov_b64_e32 v[16:17], 0
	v_mov_b64_e32 v[18:19], 0
	v_mov_b64_e32 v[20:21], 0
	v_mov_b64_e32 v[22:23], 0
	v_mov_b64_e32 v[24:25], 0
	v_mov_b64_e32 v[26:27], 0
	v_mov_b64_e32 v[28:29], 0
	v_mov_b64_e32 v[30:31], 0
	v_mov_b64_e32 v[32:33], 0
	v_mov_b64_e32 v[34:35], 0
	v_mov_b64_e32 v[36:37], 0
	v_mov_b64_e32 v[38:39], 0
	v_mov_b64_e32 v[40:41], 0
	v_mov_b64_e32 v[42:43], 0
	v_mov_b64_e32 v[44:45], 0
	v_mov_b64_e32 v[46:47], 0
	v_mov_b64_e32 v[48:49], 0
	v_mov_b64_e32 v[50:51], 0
	v_mov_b64_e32 v[52:53], 0
	v_mov_b64_e32 v[54:55], 0
	v_mov_b64_e32 v[56:57], 0
	v_mov_b64_e32 v[58:59], 0
	v_mov_b64_e32 v[60:61], 0
	v_mov_b64_e32 v[62:63], 0
	v_mov_b64_e32 v[64:65], 0
	v_mov_b64_e32 v[66:67], 0
	v_mov_b64_e32 v[68:69], 0
	v_mov_b64_e32 v[70:71], 0
	v_mov_b64_e32 v[72:73], 0
	v_mov_b64_e32 v[74:75], 0
	v_mov_b64_e32 v[76:77], 0
	v_mov_b64_e32 v[78:79], 0
	v_mov_b64_e32 v[80:81], 0
	v_mov_b64_e32 v[82:83], 0
	v_mov_b64_e32 v[84:85], 0
	v_mov_b64_e32 v[86:87], 0
	v_mov_b64_e32 v[88:89], 0
	v_mov_b64_e32 v[90:91], 0
	v_mov_b64_e32 v[92:93], 0
	v_mov_b64_e32 v[94:95], 0
	v_mov_b64_e32 v[96:97], 0
	v_mov_b64_e32 v[98:99], 0
	v_mov_b64_e32 v[100:101], 0
	v_mov_b64_e32 v[102:103], 0
	v_mov_b64_e32 v[104:105], 0
	v_mov_b64_e32 v[106:107], 0
	v_mov_b64_e32 v[108:109], 0
	v_mov_b64_e32 v[110:111], 0
	v_mov_b64_e32 v[112:113], 0
	v_mov_b64_e32 v[114:115], 0
	v_mov_b64_e32 v[116:117], 0
	v_mov_b64_e32 v[118:119], 0
	v_mov_b64_e32 v[120:121], 0
	v_mov_b64_e32 v[122:123], 0
	v_mov_b64_e32 v[124:125], 0
	v_mov_b64_e32 v[126:127], 0
.LBB0_1121:
	ds_read_b128 v[144:147], v148
	ds_read_b128 v[152:155], v148 offset:1024
	ds_read_b128 v[160:163], v148 offset:2048
	ds_read_b128 v[164:167], v148 offset:3072
	ds_read_b128 v[168:171], v149
	ds_read_b128 v[172:175], v149 offset:1024
	ds_read_b128 v[176:179], v149 offset:2048
	ds_read_b128 v[180:183], v149 offset:3072
	s_add_u32 s8, s26, 0x100
	s_addc_u32 s9, s27, 0
	s_cmp_eq_u32 s69, 4
	s_cselect_b32 s49, s23, s9
	s_cselect_b32 s48, s22, s8
	s_cselect_b32 s47, s21, s68
	s_cselect_b32 s46, s66, s67
	s_add_i32 m0, s54, 0xc000
	ds_read_b128 v[184:187], v150
	ds_read_b128 v[188:191], v150 offset:1024
	ds_read_b128 v[192:195], v150 offset:2048
	ds_read_b128 v[196:199], v150 offset:3072
	ds_read_b128 v[200:203], v150 offset:4096
	ds_read_b128 v[204:207], v150 offset:5120
	ds_read_b128 v[208:211], v150 offset:6144
	ds_read_b128 v[212:215], v150 offset:7168
	global_load_lds_dwordx4 v136, s[26:27]
	s_add_i32 m0, s54, 0xe000
	s_nop 0
	global_load_lds_dwordx4 v138, s[26:27]
	s_waitcnt vmcnt(8) lgkmcnt(0)
	s_setprio 1
	s_barrier
	v_mfma_f32_16x16x32_bf16 v[124:127], v[144:147], v[184:187], v[124:127]
	v_mfma_f32_16x16x32_bf16 v[120:123], v[160:163], v[184:187], v[120:123]
	v_mfma_f32_16x16x32_bf16 v[108:111], v[144:147], v[192:195], v[108:111]
	v_mfma_f32_16x16x32_bf16 v[104:107], v[160:163], v[192:195], v[104:107]
	v_mfma_f32_16x16x32_bf16 v[92:95], v[144:147], v[200:203], v[92:95]
	v_mfma_f32_16x16x32_bf16 v[88:91], v[160:163], v[200:203], v[88:91]
	v_mfma_f32_16x16x32_bf16 v[76:79], v[144:147], v[208:211], v[76:79]
	v_mfma_f32_16x16x32_bf16 v[72:75], v[160:163], v[208:211], v[72:75]
	v_mfma_f32_16x16x32_bf16 v[124:127], v[152:155], v[188:191], v[124:127]
	v_mfma_f32_16x16x32_bf16 v[120:123], v[164:167], v[188:191], v[120:123]
	v_mfma_f32_16x16x32_bf16 v[108:111], v[152:155], v[196:199], v[108:111]
	v_mfma_f32_16x16x32_bf16 v[104:107], v[164:167], v[196:199], v[104:107]
	v_mfma_f32_16x16x32_bf16 v[92:95], v[152:155], v[204:207], v[92:95]
	v_mfma_f32_16x16x32_bf16 v[88:91], v[164:167], v[204:207], v[88:91]
	v_mfma_f32_16x16x32_bf16 v[76:79], v[152:155], v[212:215], v[76:79]
	v_mfma_f32_16x16x32_bf16 v[72:75], v[164:167], v[212:215], v[72:75]
	v_mfma_f32_16x16x32_bf16 v[116:119], v[168:171], v[184:187], v[116:119]
	v_mfma_f32_16x16x32_bf16 v[112:115], v[176:179], v[184:187], v[112:115]
	v_mfma_f32_16x16x32_bf16 v[100:103], v[168:171], v[192:195], v[100:103]
	v_mfma_f32_16x16x32_bf16 v[96:99], v[176:179], v[192:195], v[96:99]
	v_mfma_f32_16x16x32_bf16 v[84:87], v[168:171], v[200:203], v[84:87]
	v_mfma_f32_16x16x32_bf16 v[80:83], v[176:179], v[200:203], v[80:83]
	v_mfma_f32_16x16x32_bf16 v[68:71], v[168:171], v[208:211], v[68:71]
	v_mfma_f32_16x16x32_bf16 v[64:67], v[176:179], v[208:211], v[64:67]
	v_mfma_f32_16x16x32_bf16 v[116:119], v[172:175], v[188:191], v[116:119]
	v_mfma_f32_16x16x32_bf16 v[112:115], v[180:183], v[188:191], v[112:115]
	v_mfma_f32_16x16x32_bf16 v[100:103], v[172:175], v[196:199], v[100:103]
	v_mfma_f32_16x16x32_bf16 v[96:99], v[180:183], v[196:199], v[96:99]
	v_mfma_f32_16x16x32_bf16 v[84:87], v[172:175], v[204:207], v[84:87]
	v_mfma_f32_16x16x32_bf16 v[80:83], v[180:183], v[204:207], v[80:83]
	v_mfma_f32_16x16x32_bf16 v[68:71], v[172:175], v[212:215], v[68:71]
	s_setprio 0
	v_mfma_f32_16x16x32_bf16 v[64:67], v[180:183], v[212:215], v[64:67]
	s_barrier
; #define PG8_STAGE(bufoff, gbase, voff) do { _Pragma("unroll") for (int _i = 0; _i < 2; ++_i) \
;         __builtin_amdgcn_global_load_lds((const unsigned*)((const char*)(gbase) + (voff)[_i]), (LAS unsigned*)(lds + (bufoff) + ldsw + _i * 8192), 16, 0, 0); } while (0)
; #define PG8_LDA(dst, b, h) do { _Pragma("unroll") for (int m = 0; m < 4; ++m) _Pragma("unroll") for (int k = 0; k < 2; ++k) dst[m][k] = *(const LAS bf16x8*)(lds + PG8_SA(b, h) + aoff + m * 2048 + k * 1024); } while (0)
; #define PG8_LDB(dst, b, h) do { _Pragma("unroll") for (int n = 0; n < 2; ++n) _Pragma("unroll") for (int k = 0; k < 2; ++k) dst[n][k] = *(const LAS bf16x8*)(lds + PG8_SB(b, h) + boff + n * 2048 + k * 1024); } while (0)
; #define PG8_WAIT_V(n) asm volatile("s_waitcnt vmcnt(" #n ")" ::: "memory")
; #define PG8_WAIT_L(n) asm volatile("s_waitcnt lgkmcnt(" #n ")" ::: "memory")
; #define PG8_BAR __builtin_amdgcn_s_barrier()
; #define PG8_SCHED __builtin_amdgcn_sched_barrier(0)
; template <class Epi, bool FP8 = false>
; __device__ __forceinline__ void gemm_phase(LAS unsigned char* lds, const Gemm g, const StaticOrder& S_, const Epi& E, const int tid) {
;     ...
;             PG8_LDA(At, 0, 1); PG8_STAGE(PG8_SB(0, 0), b2, voffB); PG8_STAGE(PG8_SB(0, 1), b2 + hstepB, voffB); PG8_STAGE(PG8_SA(0, 0), a2, voffA);
;             PG8_WAIT_V(8); PG8_WAIT_L(0); PG8_BAR; PG8_MMA(1, 0, At, B0); PG8_MMA(1, 1, At, B1); PG8_BAR; PG8_SCHED;
;             PG8_LDB(B0, 1, 0); PG8_LDB(B1, 1, 1); PG8_SCHED; PG8_LDA(At, 1, 0); PG8_STAGE(PG8_SA(0, 1), a2 + hstepA, voffA);
;             PG8_WAIT_V(8); PG8_WAIT_L(0); PG8_BAR; PG8_MMA(0, 0, At, B0); PG8_MMA(0, 1, At, B1); PG8_BAR; PG8_SCHED;
	s_add_u32 s98, s46, s16
	s_addc_u32 s99, s47, s17
	s_add_u32 s100, s48, s16
	s_addc_u32 s101, s49, s17
	s_add_i32 s26, s61, s53
	s_mov_b32 m0, s26
	ds_read_b128 v[184:187], v150 offset:16384
	ds_read_b128 v[188:191], v150 offset:17408
	ds_read_b128 v[192:195], v150 offset:18432
	ds_read_b128 v[196:199], v150 offset:19456
	ds_read_b128 v[200:203], v150 offset:20480
	ds_read_b128 v[204:207], v150 offset:21504
	ds_read_b128 v[208:211], v150 offset:22528
	ds_read_b128 v[212:215], v150 offset:23552
	global_load_lds_dwordx4 v132, s[46:47]
	s_add_i32 m0, s26, 0x2000
	s_add_u32 s26, s46, 0x20000
	s_addc_u32 s27, s47, 0
	s_add_i32 s70, s62, s53
	global_load_lds_dwordx4 v134, s[46:47]
	s_mov_b32 m0, s70
	s_nop 0
	global_load_lds_dwordx4 v132, s[26:27]
	s_add_i32 m0, s70, 0x2000
	s_nop 0
	global_load_lds_dwordx4 v134, s[26:27]
	s_mov_b32 m0, s54
	s_nop 0
	global_load_lds_dwordx4 v128, s[48:49]
	s_mov_b32 m0, s55
	s_nop 0
	global_load_lds_dwordx4 v130, s[48:49]
	s_waitcnt vmcnt(8) lgkmcnt(0)
	s_setprio 1
	s_barrier
	v_mfma_f32_16x16x32_bf16 v[60:63], v[144:147], v[184:187], v[60:63]
	v_mfma_f32_16x16x32_bf16 v[56:59], v[160:163], v[184:187], v[56:59]
	v_mfma_f32_16x16x32_bf16 v[44:47], v[144:147], v[192:195], v[44:47]
	v_mfma_f32_16x16x32_bf16 v[40:43], v[160:163], v[192:195], v[40:43]
	v_mfma_f32_16x16x32_bf16 v[28:31], v[144:147], v[200:203], v[28:31]
	v_mfma_f32_16x16x32_bf16 v[24:27], v[160:163], v[200:203], v[24:27]
	v_mfma_f32_16x16x32_bf16 v[12:15], v[144:147], v[208:211], v[12:15]
	v_mfma_f32_16x16x32_bf16 v[8:11], v[160:163], v[208:211], v[8:11]
	v_mfma_f32_16x16x32_bf16 v[60:63], v[152:155], v[188:191], v[60:63]
	v_mfma_f32_16x16x32_bf16 v[56:59], v[164:167], v[188:191], v[56:59]
	v_mfma_f32_16x16x32_bf16 v[44:47], v[152:155], v[196:199], v[44:47]
	v_mfma_f32_16x16x32_bf16 v[40:43], v[164:167], v[196:199], v[40:43]
	v_mfma_f32_16x16x32_bf16 v[28:31], v[152:155], v[204:207], v[28:31]
	v_mfma_f32_16x16x32_bf16 v[24:27], v[164:167], v[204:207], v[24:27]
	v_mfma_f32_16x16x32_bf16 v[12:15], v[152:155], v[212:215], v[12:15]
	v_mfma_f32_16x16x32_bf16 v[8:11], v[164:167], v[212:215], v[8:11]
	v_mfma_f32_16x16x32_bf16 v[52:55], v[168:171], v[184:187], v[52:55]
	v_mfma_f32_16x16x32_bf16 v[48:51], v[176:179], v[184:187], v[48:51]
	v_mfma_f32_16x16x32_bf16 v[36:39], v[168:171], v[192:195], v[36:39]
	v_mfma_f32_16x16x32_bf16 v[32:35], v[176:179], v[192:195], v[32:35]
	v_mfma_f32_16x16x32_bf16 v[20:23], v[168:171], v[200:203], v[20:23]
	v_mfma_f32_16x16x32_bf16 v[16:19], v[176:179], v[200:203], v[16:19]
	v_mfma_f32_16x16x32_bf16 v[4:7], v[168:171], v[208:211], v[4:7]
	v_mfma_f32_16x16x32_bf16 v[0:3], v[176:179], v[208:211], v[0:3]
	v_mfma_f32_16x16x32_bf16 v[52:55], v[172:175], v[188:191], v[52:55]
	v_mfma_f32_16x16x32_bf16 v[48:51], v[180:183], v[188:191], v[48:51]
	v_mfma_f32_16x16x32_bf16 v[36:39], v[172:175], v[196:199], v[36:39]
	v_mfma_f32_16x16x32_bf16 v[32:35], v[180:183], v[196:199], v[32:35]
	v_mfma_f32_16x16x32_bf16 v[20:23], v[172:175], v[204:207], v[20:23]
	v_mfma_f32_16x16x32_bf16 v[16:19], v[180:183], v[204:207], v[16:19]
	v_mfma_f32_16x16x32_bf16 v[4:7], v[172:175], v[212:215], v[4:7]
	s_setprio 0
	v_mfma_f32_16x16x32_bf16 v[0:3], v[180:183], v[212:215], v[0:3]
	s_barrier
	s_add_i32 s70, 0, 0x18000
	v_add_u32_e32 v151, s70, v157
	s_add_i32 s71, 0, 0x1c000
	ds_read_b128 v[144:147], v151
	ds_read_b128 v[152:155], v151 offset:1024
	ds_read_b128 v[160:163], v151 offset:2048
	ds_read_b128 v[164:167], v151 offset:3072
	v_add_u32_e32 v151, s71, v157
	ds_read_b128 v[168:171], v151
	ds_read_b128 v[172:175], v151 offset:1024
	ds_read_b128 v[176:179], v151 offset:2048
	ds_read_b128 v[180:183], v151 offset:3072
	s_add_u32 s26, s48, 0x60000
	s_addc_u32 s27, s49, 0
	s_mov_b32 m0, s56
	ds_read_b128 v[184:187], v150 offset:32768
	ds_read_b128 v[188:191], v150 offset:33792
	ds_read_b128 v[192:195], v150 offset:34816
	ds_read_b128 v[196:199], v150 offset:35840
	ds_read_b128 v[200:203], v150 offset:36864
	ds_read_b128 v[204:207], v150 offset:37888
	ds_read_b128 v[208:211], v150 offset:38912
	ds_read_b128 v[212:215], v150 offset:39936
	global_load_lds_dwordx4 v128, s[26:27]
	s_mov_b32 m0, s57
	s_nop 0
	global_load_lds_dwordx4 v130, s[26:27]
	s_waitcnt vmcnt(8) lgkmcnt(0)
	s_setprio 1
	s_barrier
; #define PG8_STAGE(bufoff, gbase, voff) do { _Pragma("unroll") for (int _i = 0; _i < 2; ++_i) \
;         __builtin_amdgcn_global_load_lds((const unsigned*)((const char*)(gbase) + (voff)[_i]), (LAS unsigned*)(lds + (bufoff) + ldsw + _i * 8192), 16, 0, 0); } while (0)
; #define PG8_LDA(dst, b, h) do { _Pragma("unroll") for (int m = 0; m < 4; ++m) _Pragma("unroll") for (int k = 0; k < 2; ++k) dst[m][k] = *(const LAS bf16x8*)(lds + PG8_SA(b, h) + aoff + m * 2048 + k * 1024); } while (0)
; #define PG8_WAIT_V(n) asm volatile("s_waitcnt vmcnt(" #n ")" ::: "memory")
; #define PG8_WAIT_L(n) asm volatile("s_waitcnt lgkmcnt(" #n ")" ::: "memory")
; #define PG8_BAR __builtin_amdgcn_s_barrier()
; #define PG8_SCHED __builtin_amdgcn_sched_barrier(0)
; template <class Epi, bool FP8 = false>
; __device__ __forceinline__ void gemm_phase(LAS unsigned char* lds, const Gemm g, const StaticOrder& S_, const Epi& E, const int tid) {
;     ...
;             PG8_WAIT_V(8); PG8_WAIT_L(0); PG8_BAR; PG8_MMA(0, 0, At, B0); PG8_MMA(0, 1, At, B1); PG8_BAR; PG8_SCHED;
;             PG8_LDA(At, 1, 1); PG8_STAGE(PG8_SB(1, 0), b3, voffB); PG8_STAGE(PG8_SB(1, 1), b3 + hstepB, voffB); PG8_STAGE(PG8_SA(1, 0), a3, voffA);
;             PG8_WAIT_V(8); PG8_WAIT_L(0); PG8_BAR; PG8_MMA(1, 0, At, B0); PG8_MMA(1, 1, At, B1); PG8_BAR; PG8_SCHED;
;         }
;         if (wr == 0) PG8_BAR;
	v_mfma_f32_16x16x32_bf16 v[124:127], v[144:147], v[184:187], v[124:127]
	v_mfma_f32_16x16x32_bf16 v[120:123], v[160:163], v[184:187], v[120:123]
	v_mfma_f32_16x16x32_bf16 v[108:111], v[144:147], v[192:195], v[108:111]
	v_mfma_f32_16x16x32_bf16 v[104:107], v[160:163], v[192:195], v[104:107]
	v_mfma_f32_16x16x32_bf16 v[92:95], v[144:147], v[200:203], v[92:95]
	v_mfma_f32_16x16x32_bf16 v[88:91], v[160:163], v[200:203], v[88:91]
	v_mfma_f32_16x16x32_bf16 v[76:79], v[144:147], v[208:211], v[76:79]
	v_mfma_f32_16x16x32_bf16 v[72:75], v[160:163], v[208:211], v[72:75]
	v_mfma_f32_16x16x32_bf16 v[124:127], v[152:155], v[188:191], v[124:127]
	v_mfma_f32_16x16x32_bf16 v[120:123], v[164:167], v[188:191], v[120:123]
	v_mfma_f32_16x16x32_bf16 v[108:111], v[152:155], v[196:199], v[108:111]
	v_mfma_f32_16x16x32_bf16 v[104:107], v[164:167], v[196:199], v[104:107]
	v_mfma_f32_16x16x32_bf16 v[92:95], v[152:155], v[204:207], v[92:95]
	v_mfma_f32_16x16x32_bf16 v[88:91], v[164:167], v[204:207], v[88:91]
	v_mfma_f32_16x16x32_bf16 v[76:79], v[152:155], v[212:215], v[76:79]
	v_mfma_f32_16x16x32_bf16 v[72:75], v[164:167], v[212:215], v[72:75]
	v_mfma_f32_16x16x32_bf16 v[116:119], v[168:171], v[184:187], v[116:119]
	v_mfma_f32_16x16x32_bf16 v[112:115], v[176:179], v[184:187], v[112:115]
	v_mfma_f32_16x16x32_bf16 v[100:103], v[168:171], v[192:195], v[100:103]
	v_mfma_f32_16x16x32_bf16 v[96:99], v[176:179], v[192:195], v[96:99]
	v_mfma_f32_16x16x32_bf16 v[84:87], v[168:171], v[200:203], v[84:87]
	v_mfma_f32_16x16x32_bf16 v[80:83], v[176:179], v[200:203], v[80:83]
	v_mfma_f32_16x16x32_bf16 v[68:71], v[168:171], v[208:211], v[68:71]
	v_mfma_f32_16x16x32_bf16 v[64:67], v[176:179], v[208:211], v[64:67]
	v_mfma_f32_16x16x32_bf16 v[116:119], v[172:175], v[188:191], v[116:119]
	v_mfma_f32_16x16x32_bf16 v[112:115], v[180:183], v[188:191], v[112:115]
	v_mfma_f32_16x16x32_bf16 v[100:103], v[172:175], v[196:199], v[100:103]
	v_mfma_f32_16x16x32_bf16 v[96:99], v[180:183], v[196:199], v[96:99]
	v_mfma_f32_16x16x32_bf16 v[84:87], v[172:175], v[204:207], v[84:87]
	v_mfma_f32_16x16x32_bf16 v[80:83], v[180:183], v[204:207], v[80:83]
	v_mfma_f32_16x16x32_bf16 v[68:71], v[172:175], v[212:215], v[68:71]
	s_setprio 0
	v_mfma_f32_16x16x32_bf16 v[64:67], v[180:183], v[212:215], v[64:67]
	s_barrier
	s_add_i32 s26, s70, s53
	s_mov_b32 m0, s26
	ds_read_b128 v[184:187], v150 offset:49152
	ds_read_b128 v[188:191], v150 offset:50176
	ds_read_b128 v[192:195], v150 offset:51200
	ds_read_b128 v[196:199], v150 offset:52224
	ds_read_b128 v[200:203], v150 offset:53248
	ds_read_b128 v[204:207], v150 offset:54272
	ds_read_b128 v[208:211], v150 offset:55296
	ds_read_b128 v[212:215], v150 offset:56320
	global_load_lds_dwordx4 v132, s[98:99]
	s_add_i32 m0, s26, 0x2000
	s_add_u32 s26, s46, 0x20080
	s_addc_u32 s27, s47, 0
	s_add_i32 s46, s71, s53
	global_load_lds_dwordx4 v134, s[98:99]
	s_mov_b32 m0, s46
	s_nop 0
	global_load_lds_dwordx4 v132, s[26:27]
	s_add_i32 m0, s46, 0x2000
	s_nop 0
	global_load_lds_dwordx4 v134, s[26:27]
	s_mov_b32 m0, s59
	s_nop 0
	global_load_lds_dwordx4 v128, s[100:101]
	s_mov_b32 m0, s60
	s_nop 0
	global_load_lds_dwordx4 v130, s[100:101]
	s_waitcnt vmcnt(8) lgkmcnt(0)
	s_setprio 1
	s_barrier
	v_mfma_f32_16x16x32_bf16 v[60:63], v[144:147], v[184:187], v[60:63]
	v_mfma_f32_16x16x32_bf16 v[56:59], v[160:163], v[184:187], v[56:59]
	v_mfma_f32_16x16x32_bf16 v[44:47], v[144:147], v[192:195], v[44:47]
	v_mfma_f32_16x16x32_bf16 v[40:43], v[160:163], v[192:195], v[40:43]
	v_mfma_f32_16x16x32_bf16 v[28:31], v[144:147], v[200:203], v[28:31]
	v_mfma_f32_16x16x32_bf16 v[24:27], v[160:163], v[200:203], v[24:27]
	v_mfma_f32_16x16x32_bf16 v[12:15], v[144:147], v[208:211], v[12:15]
	v_mfma_f32_16x16x32_bf16 v[8:11], v[160:163], v[208:211], v[8:11]
	v_mfma_f32_16x16x32_bf16 v[60:63], v[152:155], v[188:191], v[60:63]
	v_mfma_f32_16x16x32_bf16 v[56:59], v[164:167], v[188:191], v[56:59]
	v_mfma_f32_16x16x32_bf16 v[44:47], v[152:155], v[196:199], v[44:47]
	v_mfma_f32_16x16x32_bf16 v[40:43], v[164:167], v[196:199], v[40:43]
	v_mfma_f32_16x16x32_bf16 v[28:31], v[152:155], v[204:207], v[28:31]
	v_mfma_f32_16x16x32_bf16 v[24:27], v[164:167], v[204:207], v[24:27]
	v_mfma_f32_16x16x32_bf16 v[12:15], v[152:155], v[212:215], v[12:15]
	v_mfma_f32_16x16x32_bf16 v[8:11], v[164:167], v[212:215], v[8:11]
	v_mfma_f32_16x16x32_bf16 v[52:55], v[168:171], v[184:187], v[52:55]
	v_mfma_f32_16x16x32_bf16 v[48:51], v[176:179], v[184:187], v[48:51]
	v_mfma_f32_16x16x32_bf16 v[36:39], v[168:171], v[192:195], v[36:39]
	v_mfma_f32_16x16x32_bf16 v[32:35], v[176:179], v[192:195], v[32:35]
	v_mfma_f32_16x16x32_bf16 v[20:23], v[168:171], v[200:203], v[20:23]
	v_mfma_f32_16x16x32_bf16 v[16:19], v[176:179], v[200:203], v[16:19]
	v_mfma_f32_16x16x32_bf16 v[4:7], v[168:171], v[208:211], v[4:7]
	v_mfma_f32_16x16x32_bf16 v[0:3], v[176:179], v[208:211], v[0:3]
	v_mfma_f32_16x16x32_bf16 v[52:55], v[172:175], v[188:191], v[52:55]
	v_mfma_f32_16x16x32_bf16 v[48:51], v[180:183], v[188:191], v[48:51]
	v_mfma_f32_16x16x32_bf16 v[36:39], v[172:175], v[196:199], v[36:39]
	v_mfma_f32_16x16x32_bf16 v[32:35], v[180:183], v[196:199], v[32:35]
	v_mfma_f32_16x16x32_bf16 v[20:23], v[172:175], v[204:207], v[20:23]
	v_mfma_f32_16x16x32_bf16 v[16:19], v[180:183], v[204:207], v[16:19]
	v_mfma_f32_16x16x32_bf16 v[4:7], v[172:175], v[212:215], v[4:7]
	s_setprio 0
	v_mfma_f32_16x16x32_bf16 v[0:3], v[180:183], v[212:215], v[0:3]
	s_barrier
	s_add_i32 s69, s69, 2
	s_add_u32 s67, s67, 0x100
	s_addc_u32 s68, s68, 0
	s_cmp_gt_u32 s69, 5
	s_mov_b64 s[26:27], s[8:9]
	s_cbranch_scc0 .LBB0_1121
	s_and_b64 vcc, exec, s[18:19]
	s_cbranch_vccz .LBB0_1124
	s_barrier

; #define PG8_STAGE(bufoff, gbase, voff) do { _Pragma("unroll") for (int _i = 0; _i < 2; ++_i) \
;         __builtin_amdgcn_global_load_lds((const unsigned*)((const char*)(gbase) + (voff)[_i]), (LAS unsigned*)(lds + (bufoff) + ldsw + _i * 8192), 16, 0, 0); } while (0)
; #define PG8_LDA(dst, b, h) do { _Pragma("unroll") for (int m = 0; m < 4; ++m) _Pragma("unroll") for (int k = 0; k < 2; ++k) dst[m][k] = *(const LAS bf16x8*)(lds + PG8_SA(b, h) + aoff + m * 2048 + k * 1024); } while (0)
; #define PG8_LDB(dst, b, h) do { _Pragma("unroll") for (int n = 0; n < 2; ++n) _Pragma("unroll") for (int k = 0; k < 2; ++k) dst[n][k] = *(const LAS bf16x8*)(lds + PG8_SB(b, h) + boff + n * 2048 + k * 1024); } while (0)
; #define PG8_WAIT_V(n) asm volatile("s_waitcnt vmcnt(" #n ")" ::: "memory")
; #define PG8_WAIT_L(n) asm volatile("s_waitcnt lgkmcnt(" #n ")" ::: "memory")
; #define PG8_BAR __builtin_amdgcn_s_barrier()
; #define PG8_SCHED __builtin_amdgcn_sched_barrier(0)
; template <class Epi, bool FP8 = false>
; __device__ __forceinline__ void gemm_phase(LAS unsigned char* lds, const Gemm g, const StaticOrder& S_, const Epi& E, const int tid) {
;     ...
;         const bool has_next = S_.next(ui + 1, nxt);
;         const char* nA = has_next ? (const char*)g.A + (size_t)nxt.pm * tstepA : cA; const char* nB = has_next ? (const char*)g.Bt + (size_t)nxt.pn * tstepB : cB;
;         for (int t = 0; t < nt; t += 2) {
;             const bool last = (t == nt - 2);
;             const char* a1 = cA + (size_t)(t + 1) * kstep;
;             const char* a2 = last ? nA : cA + (size_t)(t + 2) * kstep; const char* b2 = last ? nB : cB + (size_t)(t + 2) * kstep;
;             const char* a3 = a2 + kstep; const char* b3 = b2 + kstep;
;             PG8_LDB(B0, 0, 0); PG8_LDB(B1, 0, 1); PG8_SCHED; PG8_LDA(At, 0, 0); PG8_STAGE(PG8_SA(1, 1), a1 + hstepA, voffA);
;             PG8_WAIT_V(8); PG8_WAIT_L(0); PG8_BAR; PG8_MMA(0, 0, At, B0); PG8_MMA(0, 1, At, B1); PG8_BAR; PG8_SCHED;
;     ...
;         if (!has_next) break;
; #pragma unroll
;         for (int a = 0; a < 2; ++a)
; #pragma unroll
;             for (int b = 0; b < 2; ++b)
; #pragma unroll
;                 for (int m = 0; m < 4; ++m)
; #pragma unroll
;                     for (int n = 0; n < 2; ++n) acc[a][b][m][n] = (f32x4){0.f, 0.f, 0.f, 0.f};
;         cur = nxt; cA = nA; cB = nB; ++ui;
;         if (wr == 1) PG8_BAR;
.LBB0_1196:
	s_ashr_i32 s23, s22, 31
	s_lshl_b64 s[24:25], s[22:23], 20
	s_add_u32 s24, s19, s24
	s_addc_u32 s25, s35, s25
	s_and_b64 s[26:27], s[6:7], exec
	s_cselect_b32 s23, s25, s49
	s_cselect_b32 s43, s24, s48
	s_ashr_i32 s21, s20, 31
	s_lshl_b64 s[26:27], s[20:21], 20
	s_add_u32 s26, s54, s26
	s_addc_u32 s27, s55, s27
	s_and_b64 s[52:53], s[6:7], exec
	s_cselect_b32 s21, s27, s51
	s_cselect_b32 s66, s26, s50
	s_add_u32 s48, s48, 0x80080
	s_addc_u32 s49, s49, 0
	s_add_u32 s68, s50, 0x100
	v_mov_b32_e32 v0, 0
	s_addc_u32 s69, s51, 0
	s_mov_b32 s70, -2
	v_mov_b64_e32 v[0:1], 0
	v_mov_b64_e32 v[2:3], 0
	v_mov_b64_e32 v[4:5], 0
	v_mov_b64_e32 v[6:7], 0
	v_mov_b64_e32 v[8:9], 0
	v_mov_b64_e32 v[10:11], 0
	v_mov_b64_e32 v[12:13], 0
	v_mov_b64_e32 v[14:15], 0
	v_mov_b64_e32 v[16:17], 0
	v_mov_b64_e32 v[18:19], 0
	v_mov_b64_e32 v[20:21], 0
	v_mov_b64_e32 v[22:23], 0
	v_mov_b64_e32 v[24:25], 0
	v_mov_b64_e32 v[26:27], 0
	v_mov_b64_e32 v[28:29], 0
	v_mov_b64_e32 v[30:31], 0
	v_mov_b64_e32 v[32:33], 0
	v_mov_b64_e32 v[34:35], 0
	v_mov_b64_e32 v[36:37], 0
	v_mov_b64_e32 v[38:39], 0
	v_mov_b64_e32 v[40:41], 0
	v_mov_b64_e32 v[42:43], 0
	v_mov_b64_e32 v[44:45], 0
	v_mov_b64_e32 v[46:47], 0
	v_mov_b64_e32 v[48:49], 0
	v_mov_b64_e32 v[50:51], 0
	v_mov_b64_e32 v[52:53], 0
	v_mov_b64_e32 v[54:55], 0
	v_mov_b64_e32 v[56:57], 0
	v_mov_b64_e32 v[58:59], 0
	v_mov_b64_e32 v[60:61], 0
	v_mov_b64_e32 v[62:63], 0
	v_mov_b64_e32 v[64:65], 0
	v_mov_b64_e32 v[66:67], 0
	v_mov_b64_e32 v[68:69], 0
	v_mov_b64_e32 v[70:71], 0
	v_mov_b64_e32 v[72:73], 0
	v_mov_b64_e32 v[74:75], 0
	v_mov_b64_e32 v[76:77], 0
	v_mov_b64_e32 v[78:79], 0
	v_mov_b64_e32 v[80:81], 0
	v_mov_b64_e32 v[82:83], 0
	v_mov_b64_e32 v[84:85], 0
	v_mov_b64_e32 v[86:87], 0
	v_mov_b64_e32 v[88:89], 0
	v_mov_b64_e32 v[90:91], 0
	v_mov_b64_e32 v[92:93], 0
	v_mov_b64_e32 v[94:95], 0
	v_mov_b64_e32 v[96:97], 0
	v_mov_b64_e32 v[98:99], 0
	v_mov_b64_e32 v[100:101], 0
	v_mov_b64_e32 v[102:103], 0
	v_mov_b64_e32 v[104:105], 0
	v_mov_b64_e32 v[106:107], 0
	v_mov_b64_e32 v[108:109], 0
	v_mov_b64_e32 v[110:111], 0
	v_mov_b64_e32 v[112:113], 0
	v_mov_b64_e32 v[114:115], 0
	v_mov_b64_e32 v[116:117], 0
	v_mov_b64_e32 v[118:119], 0
	v_mov_b64_e32 v[120:121], 0
	v_mov_b64_e32 v[122:123], 0
	v_mov_b64_e32 v[124:125], 0
	v_mov_b64_e32 v[126:127], 0
.LBB0_1197:
	ds_read_b128 v[140:143], v152
	ds_read_b128 v[144:147], v152 offset:1024
	ds_read_b128 v[156:159], v152 offset:2048
	ds_read_b128 v[160:163], v152 offset:3072
	ds_read_b128 v[164:167], v153
	ds_read_b128 v[168:171], v153 offset:1024
	ds_read_b128 v[172:175], v153 offset:2048
	ds_read_b128 v[176:179], v153 offset:3072
	s_add_u32 s50, s48, 0xfff80080
	s_addc_u32 s51, s49, -1
	s_cmp_eq_u32 s70, 28
	s_cselect_b32 s53, s23, s51
	s_cselect_b32 s52, s43, s50
	s_cselect_b32 s51, s21, s69
	s_cselect_b32 s50, s66, s68
	s_add_i32 m0, s47, 0xc000
	ds_read_b128 v[180:183], v154
	ds_read_b128 v[184:187], v154 offset:1024
	ds_read_b128 v[188:191], v154 offset:2048
	ds_read_b128 v[192:195], v154 offset:3072
	ds_read_b128 v[196:199], v154 offset:4096
	ds_read_b128 v[200:203], v154 offset:5120
	ds_read_b128 v[204:207], v154 offset:6144
	ds_read_b128 v[208:211], v154 offset:7168
	global_load_lds_dwordx4 v132, s[48:49]
	s_add_i32 m0, s47, 0xe000
	s_nop 0
	global_load_lds_dwordx4 v134, s[48:49]
	s_waitcnt vmcnt(8) lgkmcnt(0)
	s_setprio 1
	s_barrier
	v_mfma_f32_16x16x32_bf16 v[124:127], v[140:143], v[180:183], v[124:127]
	v_mfma_f32_16x16x32_bf16 v[120:123], v[156:159], v[180:183], v[120:123]
	v_mfma_f32_16x16x32_bf16 v[108:111], v[140:143], v[188:191], v[108:111]
	v_mfma_f32_16x16x32_bf16 v[104:107], v[156:159], v[188:191], v[104:107]
	v_mfma_f32_16x16x32_bf16 v[92:95], v[140:143], v[196:199], v[92:95]
	v_mfma_f32_16x16x32_bf16 v[88:91], v[156:159], v[196:199], v[88:91]
	v_mfma_f32_16x16x32_bf16 v[76:79], v[140:143], v[204:207], v[76:79]
	v_mfma_f32_16x16x32_bf16 v[72:75], v[156:159], v[204:207], v[72:75]
	v_mfma_f32_16x16x32_bf16 v[124:127], v[144:147], v[184:187], v[124:127]
	v_mfma_f32_16x16x32_bf16 v[120:123], v[160:163], v[184:187], v[120:123]
	v_mfma_f32_16x16x32_bf16 v[108:111], v[144:147], v[192:195], v[108:111]
	v_mfma_f32_16x16x32_bf16 v[104:107], v[160:163], v[192:195], v[104:107]
	v_mfma_f32_16x16x32_bf16 v[92:95], v[144:147], v[200:203], v[92:95]
	v_mfma_f32_16x16x32_bf16 v[88:91], v[160:163], v[200:203], v[88:91]
	v_mfma_f32_16x16x32_bf16 v[76:79], v[144:147], v[208:211], v[76:79]
	v_mfma_f32_16x16x32_bf16 v[72:75], v[160:163], v[208:211], v[72:75]
	v_mfma_f32_16x16x32_bf16 v[116:119], v[164:167], v[180:183], v[116:119]
	v_mfma_f32_16x16x32_bf16 v[112:115], v[172:175], v[180:183], v[112:115]
	v_mfma_f32_16x16x32_bf16 v[100:103], v[164:167], v[188:191], v[100:103]
	v_mfma_f32_16x16x32_bf16 v[96:99], v[172:175], v[188:191], v[96:99]
	v_mfma_f32_16x16x32_bf16 v[84:87], v[164:167], v[196:199], v[84:87]
	v_mfma_f32_16x16x32_bf16 v[80:83], v[172:175], v[196:199], v[80:83]
	v_mfma_f32_16x16x32_bf16 v[68:71], v[164:167], v[204:207], v[68:71]
	v_mfma_f32_16x16x32_bf16 v[64:67], v[172:175], v[204:207], v[64:67]
	v_mfma_f32_16x16x32_bf16 v[116:119], v[168:171], v[184:187], v[116:119]
	v_mfma_f32_16x16x32_bf16 v[112:115], v[176:179], v[184:187], v[112:115]
	v_mfma_f32_16x16x32_bf16 v[100:103], v[168:171], v[192:195], v[100:103]
	v_mfma_f32_16x16x32_bf16 v[96:99], v[176:179], v[192:195], v[96:99]
	v_mfma_f32_16x16x32_bf16 v[84:87], v[168:171], v[200:203], v[84:87]
	v_mfma_f32_16x16x32_bf16 v[80:83], v[176:179], v[200:203], v[80:83]
	v_mfma_f32_16x16x32_bf16 v[68:71], v[168:171], v[208:211], v[68:71]
	s_setprio 0
	v_mfma_f32_16x16x32_bf16 v[64:67], v[176:179], v[208:211], v[64:67]
	s_barrier
; #define PG8_STAGE(bufoff, gbase, voff) do { _Pragma("unroll") for (int _i = 0; _i < 2; ++_i) \
;         __builtin_amdgcn_global_load_lds((const unsigned*)((const char*)(gbase) + (voff)[_i]), (LAS unsigned*)(lds + (bufoff) + ldsw + _i * 8192), 16, 0, 0); } while (0)
; #define PG8_LDA(dst, b, h) do { _Pragma("unroll") for (int m = 0; m < 4; ++m) _Pragma("unroll") for (int k = 0; k < 2; ++k) dst[m][k] = *(const LAS bf16x8*)(lds + PG8_SA(b, h) + aoff + m * 2048 + k * 1024); } while (0)
; #define PG8_LDB(dst, b, h) do { _Pragma("unroll") for (int n = 0; n < 2; ++n) _Pragma("unroll") for (int k = 0; k < 2; ++k) dst[n][k] = *(const LAS bf16x8*)(lds + PG8_SB(b, h) + boff + n * 2048 + k * 1024); } while (0)
; #define PG8_WAIT_V(n) asm volatile("s_waitcnt vmcnt(" #n ")" ::: "memory")
; #define PG8_WAIT_L(n) asm volatile("s_waitcnt lgkmcnt(" #n ")" ::: "memory")
; #define PG8_BAR __builtin_amdgcn_s_barrier()
; #define PG8_SCHED __builtin_amdgcn_sched_barrier(0)
; template <class Epi, bool FP8 = false>
; __device__ __forceinline__ void gemm_phase(LAS unsigned char* lds, const Gemm g, const StaticOrder& S_, const Epi& E, const int tid) {
;     ...
;             PG8_LDA(At, 0, 1); PG8_STAGE(PG8_SB(0, 0), b2, voffB); PG8_STAGE(PG8_SB(0, 1), b2 + hstepB, voffB); PG8_STAGE(PG8_SA(0, 0), a2, voffA);
;             PG8_WAIT_V(8); PG8_WAIT_L(0); PG8_BAR; PG8_MMA(1, 0, At, B0); PG8_MMA(1, 1, At, B1); PG8_BAR; PG8_SCHED;
;             PG8_LDB(B0, 1, 0); PG8_LDB(B1, 1, 1); PG8_SCHED; PG8_LDA(At, 1, 0); PG8_STAGE(PG8_SA(0, 1), a2 + hstepA, voffA);
;             PG8_WAIT_V(8); PG8_WAIT_L(0); PG8_BAR; PG8_MMA(0, 0, At, B0); PG8_MMA(0, 1, At, B1); PG8_BAR; PG8_SCHED;
	s_add_u32 s98, s50, s14
	s_addc_u32 s99, s51, s15
	s_add_u32 s100, s52, s14
	s_addc_u32 s101, s53, s15
	s_add_i32 s71, s63, s56
	s_mov_b32 m0, s71
	ds_read_b128 v[180:183], v154 offset:16384
	ds_read_b128 v[184:187], v154 offset:17408
	ds_read_b128 v[188:191], v154 offset:18432
	ds_read_b128 v[192:195], v154 offset:19456
	ds_read_b128 v[196:199], v154 offset:20480
	ds_read_b128 v[200:203], v154 offset:21504
	ds_read_b128 v[204:207], v154 offset:22528
	ds_read_b128 v[208:211], v154 offset:23552
	global_load_lds_dwordx4 v128, s[50:51]
	s_add_i32 m0, s71, 0x2000
	s_add_u32 s72, s50, 0x80000
	s_addc_u32 s73, s51, 0
	s_add_i32 s71, s67, s56
	global_load_lds_dwordx4 v130, s[50:51]
	s_mov_b32 m0, s71
	s_nop 0
	global_load_lds_dwordx4 v128, s[72:73]
	s_add_i32 m0, s71, 0x2000
	s_nop 0
	global_load_lds_dwordx4 v130, s[72:73]
	s_mov_b32 m0, s47
	s_nop 0
	global_load_lds_dwordx4 v128, s[52:53]
	s_mov_b32 m0, s57
	s_nop 0
	global_load_lds_dwordx4 v130, s[52:53]
	s_waitcnt vmcnt(8) lgkmcnt(0)
	s_setprio 1
	s_barrier
	v_mfma_f32_16x16x32_bf16 v[60:63], v[140:143], v[180:183], v[60:63]
	v_mfma_f32_16x16x32_bf16 v[56:59], v[156:159], v[180:183], v[56:59]
	v_mfma_f32_16x16x32_bf16 v[44:47], v[140:143], v[188:191], v[44:47]
	v_mfma_f32_16x16x32_bf16 v[40:43], v[156:159], v[188:191], v[40:43]
	v_mfma_f32_16x16x32_bf16 v[28:31], v[140:143], v[196:199], v[28:31]
	v_mfma_f32_16x16x32_bf16 v[24:27], v[156:159], v[196:199], v[24:27]
	v_mfma_f32_16x16x32_bf16 v[12:15], v[140:143], v[204:207], v[12:15]
	v_mfma_f32_16x16x32_bf16 v[8:11], v[156:159], v[204:207], v[8:11]
	v_mfma_f32_16x16x32_bf16 v[60:63], v[144:147], v[184:187], v[60:63]
	v_mfma_f32_16x16x32_bf16 v[56:59], v[160:163], v[184:187], v[56:59]
	v_mfma_f32_16x16x32_bf16 v[44:47], v[144:147], v[192:195], v[44:47]
	v_mfma_f32_16x16x32_bf16 v[40:43], v[160:163], v[192:195], v[40:43]
	v_mfma_f32_16x16x32_bf16 v[28:31], v[144:147], v[200:203], v[28:31]
	v_mfma_f32_16x16x32_bf16 v[24:27], v[160:163], v[200:203], v[24:27]
	v_mfma_f32_16x16x32_bf16 v[12:15], v[144:147], v[208:211], v[12:15]
	v_mfma_f32_16x16x32_bf16 v[8:11], v[160:163], v[208:211], v[8:11]
	v_mfma_f32_16x16x32_bf16 v[52:55], v[164:167], v[180:183], v[52:55]
	v_mfma_f32_16x16x32_bf16 v[48:51], v[172:175], v[180:183], v[48:51]
	v_mfma_f32_16x16x32_bf16 v[36:39], v[164:167], v[188:191], v[36:39]
	v_mfma_f32_16x16x32_bf16 v[32:35], v[172:175], v[188:191], v[32:35]
	v_mfma_f32_16x16x32_bf16 v[20:23], v[164:167], v[196:199], v[20:23]
	v_mfma_f32_16x16x32_bf16 v[16:19], v[172:175], v[196:199], v[16:19]
	v_mfma_f32_16x16x32_bf16 v[4:7], v[164:167], v[204:207], v[4:7]
	v_mfma_f32_16x16x32_bf16 v[0:3], v[172:175], v[204:207], v[0:3]
	v_mfma_f32_16x16x32_bf16 v[52:55], v[168:171], v[184:187], v[52:55]
	v_mfma_f32_16x16x32_bf16 v[48:51], v[176:179], v[184:187], v[48:51]
	v_mfma_f32_16x16x32_bf16 v[36:39], v[168:171], v[192:195], v[36:39]
	v_mfma_f32_16x16x32_bf16 v[32:35], v[176:179], v[192:195], v[32:35]
	v_mfma_f32_16x16x32_bf16 v[20:23], v[168:171], v[200:203], v[20:23]
	v_mfma_f32_16x16x32_bf16 v[16:19], v[176:179], v[200:203], v[16:19]
	v_mfma_f32_16x16x32_bf16 v[4:7], v[168:171], v[208:211], v[4:7]
	s_setprio 0
	v_mfma_f32_16x16x32_bf16 v[0:3], v[176:179], v[208:211], v[0:3]
	s_barrier
	s_add_i32 s71, 0, 0x18000
	v_add_u32_e32 v155, s71, v150
	s_add_i32 s72, 0, 0x1c000
	ds_read_b128 v[140:143], v155
	ds_read_b128 v[144:147], v155 offset:1024
	ds_read_b128 v[156:159], v155 offset:2048
	ds_read_b128 v[160:163], v155 offset:3072
	v_add_u32_e32 v155, s72, v150
	ds_read_b128 v[164:167], v155
	ds_read_b128 v[168:171], v155 offset:1024
	ds_read_b128 v[172:175], v155 offset:2048
	ds_read_b128 v[176:179], v155 offset:3072
	s_add_u32 s52, s52, 0x80000
	s_addc_u32 s53, s53, 0
	s_mov_b32 m0, s58
	ds_read_b128 v[180:183], v154 offset:32768
	ds_read_b128 v[184:187], v154 offset:33792
	ds_read_b128 v[188:191], v154 offset:34816
	ds_read_b128 v[192:195], v154 offset:35840
	ds_read_b128 v[196:199], v154 offset:36864
	ds_read_b128 v[200:203], v154 offset:37888
	ds_read_b128 v[204:207], v154 offset:38912
	ds_read_b128 v[208:211], v154 offset:39936
	global_load_lds_dwordx4 v128, s[52:53]
	s_mov_b32 m0, s59
	s_nop 0
	global_load_lds_dwordx4 v130, s[52:53]
	s_waitcnt vmcnt(8) lgkmcnt(0)
	s_setprio 1
	s_barrier
; #define PG8_STAGE(bufoff, gbase, voff) do { _Pragma("unroll") for (int _i = 0; _i < 2; ++_i) \
;         __builtin_amdgcn_global_load_lds((const unsigned*)((const char*)(gbase) + (voff)[_i]), (LAS unsigned*)(lds + (bufoff) + ldsw + _i * 8192), 16, 0, 0); } while (0)
; #define PG8_LDA(dst, b, h) do { _Pragma("unroll") for (int m = 0; m < 4; ++m) _Pragma("unroll") for (int k = 0; k < 2; ++k) dst[m][k] = *(const LAS bf16x8*)(lds + PG8_SA(b, h) + aoff + m * 2048 + k * 1024); } while (0)
; #define PG8_WAIT_V(n) asm volatile("s_waitcnt vmcnt(" #n ")" ::: "memory")
; #define PG8_WAIT_L(n) asm volatile("s_waitcnt lgkmcnt(" #n ")" ::: "memory")
; #define PG8_BAR __builtin_amdgcn_s_barrier()
; #define PG8_SCHED __builtin_amdgcn_sched_barrier(0)
; template <class Epi, bool FP8 = false>
; __device__ __forceinline__ void gemm_phase(LAS unsigned char* lds, const Gemm g, const StaticOrder& S_, const Epi& E, const int tid) {
;     ...
;             PG8_WAIT_V(8); PG8_WAIT_L(0); PG8_BAR; PG8_MMA(0, 0, At, B0); PG8_MMA(0, 1, At, B1); PG8_BAR; PG8_SCHED;
;             PG8_LDA(At, 1, 1); PG8_STAGE(PG8_SB(1, 0), b3, voffB); PG8_STAGE(PG8_SB(1, 1), b3 + hstepB, voffB); PG8_STAGE(PG8_SA(1, 0), a3, voffA);
;             PG8_WAIT_V(8); PG8_WAIT_L(0); PG8_BAR; PG8_MMA(1, 0, At, B0); PG8_MMA(1, 1, At, B1); PG8_BAR; PG8_SCHED;
;         }
;         if (wr == 0) PG8_BAR;
	v_mfma_f32_16x16x32_bf16 v[124:127], v[140:143], v[180:183], v[124:127]
	v_mfma_f32_16x16x32_bf16 v[120:123], v[156:159], v[180:183], v[120:123]
	v_mfma_f32_16x16x32_bf16 v[108:111], v[140:143], v[188:191], v[108:111]
	v_mfma_f32_16x16x32_bf16 v[104:107], v[156:159], v[188:191], v[104:107]
	v_mfma_f32_16x16x32_bf16 v[92:95], v[140:143], v[196:199], v[92:95]
	v_mfma_f32_16x16x32_bf16 v[88:91], v[156:159], v[196:199], v[88:91]
	v_mfma_f32_16x16x32_bf16 v[76:79], v[140:143], v[204:207], v[76:79]
	v_mfma_f32_16x16x32_bf16 v[72:75], v[156:159], v[204:207], v[72:75]
	v_mfma_f32_16x16x32_bf16 v[124:127], v[144:147], v[184:187], v[124:127]
	v_mfma_f32_16x16x32_bf16 v[120:123], v[160:163], v[184:187], v[120:123]
	v_mfma_f32_16x16x32_bf16 v[108:111], v[144:147], v[192:195], v[108:111]
	v_mfma_f32_16x16x32_bf16 v[104:107], v[160:163], v[192:195], v[104:107]
	v_mfma_f32_16x16x32_bf16 v[92:95], v[144:147], v[200:203], v[92:95]
	v_mfma_f32_16x16x32_bf16 v[88:91], v[160:163], v[200:203], v[88:91]
	v_mfma_f32_16x16x32_bf16 v[76:79], v[144:147], v[208:211], v[76:79]
	v_mfma_f32_16x16x32_bf16 v[72:75], v[160:163], v[208:211], v[72:75]
	v_mfma_f32_16x16x32_bf16 v[116:119], v[164:167], v[180:183], v[116:119]
	v_mfma_f32_16x16x32_bf16 v[112:115], v[172:175], v[180:183], v[112:115]
	v_mfma_f32_16x16x32_bf16 v[100:103], v[164:167], v[188:191], v[100:103]
	v_mfma_f32_16x16x32_bf16 v[96:99], v[172:175], v[188:191], v[96:99]
	v_mfma_f32_16x16x32_bf16 v[84:87], v[164:167], v[196:199], v[84:87]
	v_mfma_f32_16x16x32_bf16 v[80:83], v[172:175], v[196:199], v[80:83]
	v_mfma_f32_16x16x32_bf16 v[68:71], v[164:167], v[204:207], v[68:71]
	v_mfma_f32_16x16x32_bf16 v[64:67], v[172:175], v[204:207], v[64:67]
	v_mfma_f32_16x16x32_bf16 v[116:119], v[168:171], v[184:187], v[116:119]
	v_mfma_f32_16x16x32_bf16 v[112:115], v[176:179], v[184:187], v[112:115]
	v_mfma_f32_16x16x32_bf16 v[100:103], v[168:171], v[192:195], v[100:103]
	v_mfma_f32_16x16x32_bf16 v[96:99], v[176:179], v[192:195], v[96:99]
	v_mfma_f32_16x16x32_bf16 v[84:87], v[168:171], v[200:203], v[84:87]
	v_mfma_f32_16x16x32_bf16 v[80:83], v[176:179], v[200:203], v[80:83]
	v_mfma_f32_16x16x32_bf16 v[68:71], v[168:171], v[208:211], v[68:71]
	s_setprio 0
	v_mfma_f32_16x16x32_bf16 v[64:67], v[176:179], v[208:211], v[64:67]
	s_barrier
	s_add_i32 s52, s71, s56
	s_mov_b32 m0, s52
	ds_read_b128 v[180:183], v154 offset:49152
	ds_read_b128 v[184:187], v154 offset:50176
	ds_read_b128 v[188:191], v154 offset:51200
	ds_read_b128 v[192:195], v154 offset:52224
	ds_read_b128 v[196:199], v154 offset:53248
	ds_read_b128 v[200:203], v154 offset:54272
	ds_read_b128 v[204:207], v154 offset:55296
	ds_read_b128 v[208:211], v154 offset:56320
	global_load_lds_dwordx4 v128, s[98:99]
	s_add_i32 m0, s52, 0x2000
	s_add_u32 s50, s50, 0x80080
	s_addc_u32 s51, s51, 0
	s_add_i32 s52, s72, s56
	global_load_lds_dwordx4 v130, s[98:99]
	s_mov_b32 m0, s52
	s_nop 0
	global_load_lds_dwordx4 v128, s[50:51]
	s_add_i32 m0, s52, 0x2000
	s_nop 0
	global_load_lds_dwordx4 v130, s[50:51]
	s_mov_b32 m0, s61
	s_nop 0
	global_load_lds_dwordx4 v128, s[100:101]
	s_mov_b32 m0, s62
	s_nop 0
	global_load_lds_dwordx4 v130, s[100:101]
	s_waitcnt vmcnt(8) lgkmcnt(0)
	s_setprio 1
	s_barrier
	v_mfma_f32_16x16x32_bf16 v[60:63], v[140:143], v[180:183], v[60:63]
	v_mfma_f32_16x16x32_bf16 v[56:59], v[156:159], v[180:183], v[56:59]
	v_mfma_f32_16x16x32_bf16 v[44:47], v[140:143], v[188:191], v[44:47]
	v_mfma_f32_16x16x32_bf16 v[40:43], v[156:159], v[188:191], v[40:43]
	v_mfma_f32_16x16x32_bf16 v[28:31], v[140:143], v[196:199], v[28:31]
	v_mfma_f32_16x16x32_bf16 v[24:27], v[156:159], v[196:199], v[24:27]
	v_mfma_f32_16x16x32_bf16 v[12:15], v[140:143], v[204:207], v[12:15]
	v_mfma_f32_16x16x32_bf16 v[8:11], v[156:159], v[204:207], v[8:11]
	v_mfma_f32_16x16x32_bf16 v[60:63], v[144:147], v[184:187], v[60:63]
	v_mfma_f32_16x16x32_bf16 v[56:59], v[160:163], v[184:187], v[56:59]
	v_mfma_f32_16x16x32_bf16 v[44:47], v[144:147], v[192:195], v[44:47]
	v_mfma_f32_16x16x32_bf16 v[40:43], v[160:163], v[192:195], v[40:43]
	v_mfma_f32_16x16x32_bf16 v[28:31], v[144:147], v[200:203], v[28:31]
	v_mfma_f32_16x16x32_bf16 v[24:27], v[160:163], v[200:203], v[24:27]
	v_mfma_f32_16x16x32_bf16 v[12:15], v[144:147], v[208:211], v[12:15]
	v_mfma_f32_16x16x32_bf16 v[8:11], v[160:163], v[208:211], v[8:11]
	v_mfma_f32_16x16x32_bf16 v[52:55], v[164:167], v[180:183], v[52:55]
	v_mfma_f32_16x16x32_bf16 v[48:51], v[172:175], v[180:183], v[48:51]
	v_mfma_f32_16x16x32_bf16 v[36:39], v[164:167], v[188:191], v[36:39]
	v_mfma_f32_16x16x32_bf16 v[32:35], v[172:175], v[188:191], v[32:35]
	v_mfma_f32_16x16x32_bf16 v[20:23], v[164:167], v[196:199], v[20:23]
	v_mfma_f32_16x16x32_bf16 v[16:19], v[172:175], v[196:199], v[16:19]
	v_mfma_f32_16x16x32_bf16 v[4:7], v[164:167], v[204:207], v[4:7]
	v_mfma_f32_16x16x32_bf16 v[0:3], v[172:175], v[204:207], v[0:3]
	v_mfma_f32_16x16x32_bf16 v[52:55], v[168:171], v[184:187], v[52:55]
	v_mfma_f32_16x16x32_bf16 v[48:51], v[176:179], v[184:187], v[48:51]
	v_mfma_f32_16x16x32_bf16 v[36:39], v[168:171], v[192:195], v[36:39]
	v_mfma_f32_16x16x32_bf16 v[32:35], v[176:179], v[192:195], v[32:35]
	v_mfma_f32_16x16x32_bf16 v[20:23], v[168:171], v[200:203], v[20:23]
	v_mfma_f32_16x16x32_bf16 v[16:19], v[176:179], v[200:203], v[16:19]
	v_mfma_f32_16x16x32_bf16 v[4:7], v[168:171], v[208:211], v[4:7]
	s_setprio 0
	v_mfma_f32_16x16x32_bf16 v[0:3], v[176:179], v[208:211], v[0:3]
	s_barrier
	s_add_i32 s70, s70, 2
	s_add_u32 s48, s48, 0x100
	s_addc_u32 s49, s49, 0
	s_add_u32 s68, s68, 0x100
	s_addc_u32 s69, s69, 0
	s_cmp_gt_u32 s70, 29
	s_cbranch_scc0 .LBB0_1197
	s_and_b64 vcc, exec, s[16:17]
	s_cbranch_vccz .LBB0_1200
	s_barrier

; #define PG8_STAGE(bufoff, gbase, voff) do { _Pragma("unroll") for (int _i = 0; _i < 2; ++_i) \
;         __builtin_amdgcn_global_load_lds((const unsigned*)((const char*)(gbase) + (voff)[_i]), (LAS unsigned*)(lds + (bufoff) + ldsw + _i * 8192), 16, 0, 0); } while (0)
; #define PG8_LDA(dst, b, h) do { _Pragma("unroll") for (int m = 0; m < 4; ++m) _Pragma("unroll") for (int k = 0; k < 2; ++k) dst[m][k] = *(const LAS bf16x8*)(lds + PG8_SA(b, h) + aoff + m * 2048 + k * 1024); } while (0)
; #define PG8_LDB(dst, b, h) do { _Pragma("unroll") for (int n = 0; n < 2; ++n) _Pragma("unroll") for (int k = 0; k < 2; ++k) dst[n][k] = *(const LAS bf16x8*)(lds + PG8_SB(b, h) + boff + n * 2048 + k * 1024); } while (0)
; #define PG8_WAIT_V(n) asm volatile("s_waitcnt vmcnt(" #n ")" ::: "memory")
; #define PG8_WAIT_L(n) asm volatile("s_waitcnt lgkmcnt(" #n ")" ::: "memory")
; #define PG8_BAR __builtin_amdgcn_s_barrier()
; #define PG8_SCHED __builtin_amdgcn_sched_barrier(0)
; template <class Epi, bool FP8 = false>
; __device__ __forceinline__ void gemm_phase(LAS unsigned char* lds, const Gemm g, const StaticOrder& S_, const Epi& E, const int tid) {
;     ...
;         const bool has_next = S_.next(ui + 1, nxt);
;         const char* nA = has_next ? (const char*)g.A + (size_t)nxt.pm * tstepA : cA; const char* nB = has_next ? (const char*)g.Bt + (size_t)nxt.pn * tstepB : cB;
;         for (int t = 0; t < nt; t += 2) {
;             const bool last = (t == nt - 2);
;             const char* a1 = cA + (size_t)(t + 1) * kstep;
;             const char* a2 = last ? nA : cA + (size_t)(t + 2) * kstep; const char* b2 = last ? nB : cB + (size_t)(t + 2) * kstep;
;             const char* a3 = a2 + kstep; const char* b3 = b2 + kstep;
;             PG8_LDB(B0, 0, 0); PG8_LDB(B1, 0, 1); PG8_SCHED; PG8_LDA(At, 0, 0); PG8_STAGE(PG8_SA(1, 1), a1 + hstepA, voffA);
;             PG8_WAIT_V(8); PG8_WAIT_L(0); PG8_BAR; PG8_MMA(0, 0, At, B0); PG8_MMA(0, 1, At, B1); PG8_BAR; PG8_SCHED;
;     ...
;         if (!has_next) break;
; #pragma unroll
;         for (int a = 0; a < 2; ++a)
; #pragma unroll
;             for (int b = 0; b < 2; ++b)
; #pragma unroll
;                 for (int m = 0; m < 4; ++m)
; #pragma unroll
;                     for (int n = 0; n < 2; ++n) acc[a][b][m][n] = (f32x4){0.f, 0.f, 0.f, 0.f};
;         cur = nxt; cA = nA; cB = nB; ++ui;
;         if (wr == 1) PG8_BAR;
.LBB0_1339:
	s_ashr_i32 s23, s22, 31
	s_lshl_b64 s[24:25], s[22:23], 20
	s_add_u32 s24, s3, s24
	s_addc_u32 s25, s35, s25
	s_and_b64 s[26:27], s[6:7], exec
	s_cselect_b32 s23, s25, s31
	s_cselect_b32 s63, s24, s30
	s_ashr_i32 s21, s20, 31
	s_lshl_b64 s[26:27], s[20:21], 20
	s_add_u32 s26, s48, s26
	s_addc_u32 s27, s49, s27
	s_and_b64 s[46:47], s[6:7], exec
	s_cselect_b32 s21, s27, s43
	s_cselect_b32 s66, s26, s42
	s_add_u32 s30, s30, 0x80080
	s_addc_u32 s31, s31, 0
	s_add_u32 s67, s42, 0x100
	v_mov_b32_e32 v0, 0
	s_addc_u32 s68, s43, 0
	s_mov_b32 s69, -2
	v_mov_b64_e32 v[0:1], 0
	v_mov_b64_e32 v[2:3], 0
	v_mov_b64_e32 v[4:5], 0
	v_mov_b64_e32 v[6:7], 0
	v_mov_b64_e32 v[8:9], 0
	v_mov_b64_e32 v[10:11], 0
	v_mov_b64_e32 v[12:13], 0
	v_mov_b64_e32 v[14:15], 0
	v_mov_b64_e32 v[16:17], 0
	v_mov_b64_e32 v[18:19], 0
	v_mov_b64_e32 v[20:21], 0
	v_mov_b64_e32 v[22:23], 0
	v_mov_b64_e32 v[24:25], 0
	v_mov_b64_e32 v[26:27], 0
	v_mov_b64_e32 v[28:29], 0
	v_mov_b64_e32 v[30:31], 0
	v_mov_b64_e32 v[32:33], 0
	v_mov_b64_e32 v[34:35], 0
	v_mov_b64_e32 v[36:37], 0
	v_mov_b64_e32 v[38:39], 0
	v_mov_b64_e32 v[40:41], 0
	v_mov_b64_e32 v[42:43], 0
	v_mov_b64_e32 v[44:45], 0
	v_mov_b64_e32 v[46:47], 0
	v_mov_b64_e32 v[48:49], 0
	v_mov_b64_e32 v[50:51], 0
	v_mov_b64_e32 v[52:53], 0
	v_mov_b64_e32 v[54:55], 0
	v_mov_b64_e32 v[56:57], 0
	v_mov_b64_e32 v[58:59], 0
	v_mov_b64_e32 v[60:61], 0
	v_mov_b64_e32 v[62:63], 0
	v_mov_b64_e32 v[64:65], 0
	v_mov_b64_e32 v[66:67], 0
	v_mov_b64_e32 v[68:69], 0
	v_mov_b64_e32 v[70:71], 0
	v_mov_b64_e32 v[72:73], 0
	v_mov_b64_e32 v[74:75], 0
	v_mov_b64_e32 v[76:77], 0
	v_mov_b64_e32 v[78:79], 0
	v_mov_b64_e32 v[80:81], 0
	v_mov_b64_e32 v[82:83], 0
	v_mov_b64_e32 v[84:85], 0
	v_mov_b64_e32 v[86:87], 0
	v_mov_b64_e32 v[88:89], 0
	v_mov_b64_e32 v[90:91], 0
	v_mov_b64_e32 v[92:93], 0
	v_mov_b64_e32 v[94:95], 0
	v_mov_b64_e32 v[96:97], 0
	v_mov_b64_e32 v[98:99], 0
	v_mov_b64_e32 v[100:101], 0
	v_mov_b64_e32 v[102:103], 0
	v_mov_b64_e32 v[104:105], 0
	v_mov_b64_e32 v[106:107], 0
	v_mov_b64_e32 v[108:109], 0
	v_mov_b64_e32 v[110:111], 0
	v_mov_b64_e32 v[112:113], 0
	v_mov_b64_e32 v[114:115], 0
	v_mov_b64_e32 v[116:117], 0
	v_mov_b64_e32 v[118:119], 0
	v_mov_b64_e32 v[120:121], 0
	v_mov_b64_e32 v[122:123], 0
	v_mov_b64_e32 v[124:125], 0
	v_mov_b64_e32 v[126:127], 0
.LBB0_1340:
	ds_read_b128 v[150:153], v147
	ds_read_b128 v[154:157], v147 offset:1024
	ds_read_b128 v[158:161], v147 offset:2048
	ds_read_b128 v[162:165], v147 offset:3072
	ds_read_b128 v[166:169], v148
	ds_read_b128 v[170:173], v148 offset:1024
	ds_read_b128 v[174:177], v148 offset:2048
	ds_read_b128 v[178:181], v148 offset:3072
	s_add_u32 s42, s30, 0xfff80080
	s_addc_u32 s43, s31, -1
	s_cmp_eq_u32 s69, 28
	s_cselect_b32 s47, s23, s43
	s_cselect_b32 s46, s63, s42
	s_cselect_b32 s43, s21, s68
	s_cselect_b32 s42, s66, s67
	s_add_i32 m0, s29, 0xc000
	ds_read_b128 v[182:185], v149
	ds_read_b128 v[186:189], v149 offset:1024
	ds_read_b128 v[190:193], v149 offset:2048
	ds_read_b128 v[194:197], v149 offset:3072
	ds_read_b128 v[198:201], v149 offset:4096
	ds_read_b128 v[202:205], v149 offset:5120
	ds_read_b128 v[206:209], v149 offset:6144
	ds_read_b128 v[210:213], v149 offset:7168
	global_load_lds_dwordx4 v136, s[30:31]
	s_add_i32 m0, s29, 0xe000
	s_nop 0
	global_load_lds_dwordx4 v138, s[30:31]
	s_waitcnt vmcnt(8) lgkmcnt(0)
	s_setprio 1
	s_barrier
	v_mfma_f32_16x16x32_bf16 v[124:127], v[150:153], v[182:185], v[124:127]
	v_mfma_f32_16x16x32_bf16 v[120:123], v[158:161], v[182:185], v[120:123]
	v_mfma_f32_16x16x32_bf16 v[108:111], v[150:153], v[190:193], v[108:111]
	v_mfma_f32_16x16x32_bf16 v[104:107], v[158:161], v[190:193], v[104:107]
	v_mfma_f32_16x16x32_bf16 v[92:95], v[150:153], v[198:201], v[92:95]
	v_mfma_f32_16x16x32_bf16 v[88:91], v[158:161], v[198:201], v[88:91]
	v_mfma_f32_16x16x32_bf16 v[76:79], v[150:153], v[206:209], v[76:79]
	v_mfma_f32_16x16x32_bf16 v[72:75], v[158:161], v[206:209], v[72:75]
	v_mfma_f32_16x16x32_bf16 v[124:127], v[154:157], v[186:189], v[124:127]
	v_mfma_f32_16x16x32_bf16 v[120:123], v[162:165], v[186:189], v[120:123]
	v_mfma_f32_16x16x32_bf16 v[108:111], v[154:157], v[194:197], v[108:111]
	v_mfma_f32_16x16x32_bf16 v[104:107], v[162:165], v[194:197], v[104:107]
	v_mfma_f32_16x16x32_bf16 v[92:95], v[154:157], v[202:205], v[92:95]
	v_mfma_f32_16x16x32_bf16 v[88:91], v[162:165], v[202:205], v[88:91]
	v_mfma_f32_16x16x32_bf16 v[76:79], v[154:157], v[210:213], v[76:79]
	v_mfma_f32_16x16x32_bf16 v[72:75], v[162:165], v[210:213], v[72:75]
	v_mfma_f32_16x16x32_bf16 v[116:119], v[166:169], v[182:185], v[116:119]
	v_mfma_f32_16x16x32_bf16 v[112:115], v[174:177], v[182:185], v[112:115]
	v_mfma_f32_16x16x32_bf16 v[100:103], v[166:169], v[190:193], v[100:103]
	v_mfma_f32_16x16x32_bf16 v[96:99], v[174:177], v[190:193], v[96:99]
	v_mfma_f32_16x16x32_bf16 v[84:87], v[166:169], v[198:201], v[84:87]
	v_mfma_f32_16x16x32_bf16 v[80:83], v[174:177], v[198:201], v[80:83]
	v_mfma_f32_16x16x32_bf16 v[68:71], v[166:169], v[206:209], v[68:71]
	v_mfma_f32_16x16x32_bf16 v[64:67], v[174:177], v[206:209], v[64:67]
	v_mfma_f32_16x16x32_bf16 v[116:119], v[170:173], v[186:189], v[116:119]
	v_mfma_f32_16x16x32_bf16 v[112:115], v[178:181], v[186:189], v[112:115]
	v_mfma_f32_16x16x32_bf16 v[100:103], v[170:173], v[194:197], v[100:103]
	v_mfma_f32_16x16x32_bf16 v[96:99], v[178:181], v[194:197], v[96:99]
	v_mfma_f32_16x16x32_bf16 v[84:87], v[170:173], v[202:205], v[84:87]
	v_mfma_f32_16x16x32_bf16 v[80:83], v[178:181], v[202:205], v[80:83]
	v_mfma_f32_16x16x32_bf16 v[68:71], v[170:173], v[210:213], v[68:71]
	s_setprio 0
	v_mfma_f32_16x16x32_bf16 v[64:67], v[178:181], v[210:213], v[64:67]
	s_barrier
; #define PG8_STAGE(bufoff, gbase, voff) do { _Pragma("unroll") for (int _i = 0; _i < 2; ++_i) \
;         __builtin_amdgcn_global_load_lds((const unsigned*)((const char*)(gbase) + (voff)[_i]), (LAS unsigned*)(lds + (bufoff) + ldsw + _i * 8192), 16, 0, 0); } while (0)
; #define PG8_LDA(dst, b, h) do { _Pragma("unroll") for (int m = 0; m < 4; ++m) _Pragma("unroll") for (int k = 0; k < 2; ++k) dst[m][k] = *(const LAS bf16x8*)(lds + PG8_SA(b, h) + aoff + m * 2048 + k * 1024); } while (0)
; #define PG8_LDB(dst, b, h) do { _Pragma("unroll") for (int n = 0; n < 2; ++n) _Pragma("unroll") for (int k = 0; k < 2; ++k) dst[n][k] = *(const LAS bf16x8*)(lds + PG8_SB(b, h) + boff + n * 2048 + k * 1024); } while (0)
; #define PG8_WAIT_V(n) asm volatile("s_waitcnt vmcnt(" #n ")" ::: "memory")
; #define PG8_WAIT_L(n) asm volatile("s_waitcnt lgkmcnt(" #n ")" ::: "memory")
; #define PG8_BAR __builtin_amdgcn_s_barrier()
; #define PG8_SCHED __builtin_amdgcn_sched_barrier(0)
; template <class Epi, bool FP8 = false>
; __device__ __forceinline__ void gemm_phase(LAS unsigned char* lds, const Gemm g, const StaticOrder& S_, const Epi& E, const int tid) {
;     ...
;             PG8_LDA(At, 0, 1); PG8_STAGE(PG8_SB(0, 0), b2, voffB); PG8_STAGE(PG8_SB(0, 1), b2 + hstepB, voffB); PG8_STAGE(PG8_SA(0, 0), a2, voffA);
;             PG8_WAIT_V(8); PG8_WAIT_L(0); PG8_BAR; PG8_MMA(1, 0, At, B0); PG8_MMA(1, 1, At, B1); PG8_BAR; PG8_SCHED;
;             PG8_LDB(B0, 1, 0); PG8_LDB(B1, 1, 1); PG8_SCHED; PG8_LDA(At, 1, 0); PG8_STAGE(PG8_SA(0, 1), a2 + hstepA, voffA);
;             PG8_WAIT_V(8); PG8_WAIT_L(0); PG8_BAR; PG8_MMA(0, 0, At, B0); PG8_MMA(0, 1, At, B1); PG8_BAR; PG8_SCHED;
	s_add_u32 s98, s42, s16
	s_addc_u32 s99, s43, s17
	s_add_u32 s100, s46, s16
	s_addc_u32 s101, s47, s17
	s_add_i32 s70, s59, s50
	s_mov_b32 m0, s70
	ds_read_b128 v[182:185], v149 offset:16384
	ds_read_b128 v[186:189], v149 offset:17408
	ds_read_b128 v[190:193], v149 offset:18432
	ds_read_b128 v[194:197], v149 offset:19456
	ds_read_b128 v[198:201], v149 offset:20480
	ds_read_b128 v[202:205], v149 offset:21504
	ds_read_b128 v[206:209], v149 offset:22528
	ds_read_b128 v[210:213], v149 offset:23552
	global_load_lds_dwordx4 v128, s[42:43]
	s_add_i32 m0, s70, 0x2000
	s_add_u32 s70, s42, 0x80000
	s_addc_u32 s71, s43, 0
	s_add_i32 s72, s60, s50
	global_load_lds_dwordx4 v130, s[42:43]
	s_mov_b32 m0, s72
	s_nop 0
	global_load_lds_dwordx4 v128, s[70:71]
	s_add_i32 m0, s72, 0x2000
	s_nop 0
	global_load_lds_dwordx4 v130, s[70:71]
	s_mov_b32 m0, s29
	s_nop 0
	global_load_lds_dwordx4 v134, s[46:47]
	s_mov_b32 m0, s53
	s_nop 0
	global_load_lds_dwordx4 v132, s[46:47]
	s_waitcnt vmcnt(8) lgkmcnt(0)
	s_setprio 1
	s_barrier
	v_mfma_f32_16x16x32_bf16 v[60:63], v[150:153], v[182:185], v[60:63]
	v_mfma_f32_16x16x32_bf16 v[56:59], v[158:161], v[182:185], v[56:59]
	v_mfma_f32_16x16x32_bf16 v[44:47], v[150:153], v[190:193], v[44:47]
	v_mfma_f32_16x16x32_bf16 v[40:43], v[158:161], v[190:193], v[40:43]
	v_mfma_f32_16x16x32_bf16 v[28:31], v[150:153], v[198:201], v[28:31]
	v_mfma_f32_16x16x32_bf16 v[24:27], v[158:161], v[198:201], v[24:27]
	v_mfma_f32_16x16x32_bf16 v[12:15], v[150:153], v[206:209], v[12:15]
	v_mfma_f32_16x16x32_bf16 v[8:11], v[158:161], v[206:209], v[8:11]
	v_mfma_f32_16x16x32_bf16 v[60:63], v[154:157], v[186:189], v[60:63]
	v_mfma_f32_16x16x32_bf16 v[56:59], v[162:165], v[186:189], v[56:59]
	v_mfma_f32_16x16x32_bf16 v[44:47], v[154:157], v[194:197], v[44:47]
	v_mfma_f32_16x16x32_bf16 v[40:43], v[162:165], v[194:197], v[40:43]
	v_mfma_f32_16x16x32_bf16 v[28:31], v[154:157], v[202:205], v[28:31]
	v_mfma_f32_16x16x32_bf16 v[24:27], v[162:165], v[202:205], v[24:27]
	v_mfma_f32_16x16x32_bf16 v[12:15], v[154:157], v[210:213], v[12:15]
	v_mfma_f32_16x16x32_bf16 v[8:11], v[162:165], v[210:213], v[8:11]
	v_mfma_f32_16x16x32_bf16 v[52:55], v[166:169], v[182:185], v[52:55]
	v_mfma_f32_16x16x32_bf16 v[48:51], v[174:177], v[182:185], v[48:51]
	v_mfma_f32_16x16x32_bf16 v[36:39], v[166:169], v[190:193], v[36:39]
	v_mfma_f32_16x16x32_bf16 v[32:35], v[174:177], v[190:193], v[32:35]
	v_mfma_f32_16x16x32_bf16 v[20:23], v[166:169], v[198:201], v[20:23]
	v_mfma_f32_16x16x32_bf16 v[16:19], v[174:177], v[198:201], v[16:19]
	v_mfma_f32_16x16x32_bf16 v[4:7], v[166:169], v[206:209], v[4:7]
	v_mfma_f32_16x16x32_bf16 v[0:3], v[174:177], v[206:209], v[0:3]
	v_mfma_f32_16x16x32_bf16 v[52:55], v[170:173], v[186:189], v[52:55]
	v_mfma_f32_16x16x32_bf16 v[48:51], v[178:181], v[186:189], v[48:51]
	v_mfma_f32_16x16x32_bf16 v[36:39], v[170:173], v[194:197], v[36:39]
	v_mfma_f32_16x16x32_bf16 v[32:35], v[178:181], v[194:197], v[32:35]
	v_mfma_f32_16x16x32_bf16 v[20:23], v[170:173], v[202:205], v[20:23]
	v_mfma_f32_16x16x32_bf16 v[16:19], v[178:181], v[202:205], v[16:19]
	v_mfma_f32_16x16x32_bf16 v[4:7], v[170:173], v[210:213], v[4:7]
	s_setprio 0
	v_mfma_f32_16x16x32_bf16 v[0:3], v[178:181], v[210:213], v[0:3]
	s_barrier
	s_add_i32 s70, 0, 0x18000
	s_add_i32 s71, 0, 0x1c000
	v_add_u32_e32 v162, s70, v145
	v_add_u32_e32 v178, s71, v145
	ds_read_b128 v[150:153], v162
	ds_read_b128 v[154:157], v162 offset:1024
	ds_read_b128 v[158:161], v162 offset:2048
	ds_read_b128 v[162:165], v162 offset:3072
	ds_read_b128 v[166:169], v178
	ds_read_b128 v[170:173], v178 offset:1024
	ds_read_b128 v[174:177], v178 offset:2048
	ds_read_b128 v[178:181], v178 offset:3072
	s_add_u32 s46, s46, 0x80000
	s_addc_u32 s47, s47, 0
	s_mov_b32 m0, s54
	ds_read_b128 v[182:185], v149 offset:32768
	ds_read_b128 v[186:189], v149 offset:33792
	ds_read_b128 v[190:193], v149 offset:34816
	ds_read_b128 v[194:197], v149 offset:35840
	ds_read_b128 v[198:201], v149 offset:36864
	ds_read_b128 v[202:205], v149 offset:37888
	ds_read_b128 v[206:209], v149 offset:38912
	ds_read_b128 v[210:213], v149 offset:39936
	global_load_lds_dwordx4 v134, s[46:47]
	s_mov_b32 m0, s55
	s_nop 0
	global_load_lds_dwordx4 v132, s[46:47]
	s_waitcnt vmcnt(8) lgkmcnt(0)
	s_setprio 1
	s_barrier
; #define PG8_STAGE(bufoff, gbase, voff) do { _Pragma("unroll") for (int _i = 0; _i < 2; ++_i) \
;         __builtin_amdgcn_global_load_lds((const unsigned*)((const char*)(gbase) + (voff)[_i]), (LAS unsigned*)(lds + (bufoff) + ldsw + _i * 8192), 16, 0, 0); } while (0)
; #define PG8_LDA(dst, b, h) do { _Pragma("unroll") for (int m = 0; m < 4; ++m) _Pragma("unroll") for (int k = 0; k < 2; ++k) dst[m][k] = *(const LAS bf16x8*)(lds + PG8_SA(b, h) + aoff + m * 2048 + k * 1024); } while (0)
; #define PG8_WAIT_V(n) asm volatile("s_waitcnt vmcnt(" #n ")" ::: "memory")
; #define PG8_WAIT_L(n) asm volatile("s_waitcnt lgkmcnt(" #n ")" ::: "memory")
; #define PG8_BAR __builtin_amdgcn_s_barrier()
; #define PG8_SCHED __builtin_amdgcn_sched_barrier(0)
; template <class Epi, bool FP8 = false>
; __device__ __forceinline__ void gemm_phase(LAS unsigned char* lds, const Gemm g, const StaticOrder& S_, const Epi& E, const int tid) {
;     ...
;             PG8_WAIT_V(8); PG8_WAIT_L(0); PG8_BAR; PG8_MMA(0, 0, At, B0); PG8_MMA(0, 1, At, B1); PG8_BAR; PG8_SCHED;
;             PG8_LDA(At, 1, 1); PG8_STAGE(PG8_SB(1, 0), b3, voffB); PG8_STAGE(PG8_SB(1, 1), b3 + hstepB, voffB); PG8_STAGE(PG8_SA(1, 0), a3, voffA);
;             PG8_WAIT_V(8); PG8_WAIT_L(0); PG8_BAR; PG8_MMA(1, 0, At, B0); PG8_MMA(1, 1, At, B1); PG8_BAR; PG8_SCHED;
;         }
;         if (wr == 0) PG8_BAR;
	v_mfma_f32_16x16x32_bf16 v[124:127], v[150:153], v[182:185], v[124:127]
	v_mfma_f32_16x16x32_bf16 v[120:123], v[158:161], v[182:185], v[120:123]
	v_mfma_f32_16x16x32_bf16 v[108:111], v[150:153], v[190:193], v[108:111]
	v_mfma_f32_16x16x32_bf16 v[104:107], v[158:161], v[190:193], v[104:107]
	v_mfma_f32_16x16x32_bf16 v[92:95], v[150:153], v[198:201], v[92:95]
	v_mfma_f32_16x16x32_bf16 v[88:91], v[158:161], v[198:201], v[88:91]
	v_mfma_f32_16x16x32_bf16 v[76:79], v[150:153], v[206:209], v[76:79]
	v_mfma_f32_16x16x32_bf16 v[72:75], v[158:161], v[206:209], v[72:75]
	v_mfma_f32_16x16x32_bf16 v[124:127], v[154:157], v[186:189], v[124:127]
	v_mfma_f32_16x16x32_bf16 v[120:123], v[162:165], v[186:189], v[120:123]
	v_mfma_f32_16x16x32_bf16 v[108:111], v[154:157], v[194:197], v[108:111]
	v_mfma_f32_16x16x32_bf16 v[104:107], v[162:165], v[194:197], v[104:107]
	v_mfma_f32_16x16x32_bf16 v[92:95], v[154:157], v[202:205], v[92:95]
	v_mfma_f32_16x16x32_bf16 v[88:91], v[162:165], v[202:205], v[88:91]
	v_mfma_f32_16x16x32_bf16 v[76:79], v[154:157], v[210:213], v[76:79]
	v_mfma_f32_16x16x32_bf16 v[72:75], v[162:165], v[210:213], v[72:75]
	v_mfma_f32_16x16x32_bf16 v[116:119], v[166:169], v[182:185], v[116:119]
	v_mfma_f32_16x16x32_bf16 v[112:115], v[174:177], v[182:185], v[112:115]
	v_mfma_f32_16x16x32_bf16 v[100:103], v[166:169], v[190:193], v[100:103]
	v_mfma_f32_16x16x32_bf16 v[96:99], v[174:177], v[190:193], v[96:99]
	v_mfma_f32_16x16x32_bf16 v[84:87], v[166:169], v[198:201], v[84:87]
	v_mfma_f32_16x16x32_bf16 v[80:83], v[174:177], v[198:201], v[80:83]
	v_mfma_f32_16x16x32_bf16 v[68:71], v[166:169], v[206:209], v[68:71]
	v_mfma_f32_16x16x32_bf16 v[64:67], v[174:177], v[206:209], v[64:67]
	v_mfma_f32_16x16x32_bf16 v[116:119], v[170:173], v[186:189], v[116:119]
	v_mfma_f32_16x16x32_bf16 v[112:115], v[178:181], v[186:189], v[112:115]
	v_mfma_f32_16x16x32_bf16 v[100:103], v[170:173], v[194:197], v[100:103]
	v_mfma_f32_16x16x32_bf16 v[96:99], v[178:181], v[194:197], v[96:99]
	v_mfma_f32_16x16x32_bf16 v[84:87], v[170:173], v[202:205], v[84:87]
	v_mfma_f32_16x16x32_bf16 v[80:83], v[178:181], v[202:205], v[80:83]
	v_mfma_f32_16x16x32_bf16 v[68:71], v[170:173], v[210:213], v[68:71]
	s_setprio 0
	v_mfma_f32_16x16x32_bf16 v[64:67], v[178:181], v[210:213], v[64:67]
	s_barrier
	s_add_i32 s46, s70, s50
	s_mov_b32 m0, s46
	ds_read_b128 v[182:185], v149 offset:49152
	ds_read_b128 v[186:189], v149 offset:50176
	ds_read_b128 v[190:193], v149 offset:51200
	ds_read_b128 v[194:197], v149 offset:52224
	ds_read_b128 v[198:201], v149 offset:53248
	ds_read_b128 v[202:205], v149 offset:54272
	ds_read_b128 v[206:209], v149 offset:55296
	ds_read_b128 v[210:213], v149 offset:56320
	global_load_lds_dwordx4 v128, s[98:99]
	s_add_i32 m0, s46, 0x2000
	s_add_u32 s42, s42, 0x80080
	s_addc_u32 s43, s43, 0
	s_add_i32 s46, s71, s50
	global_load_lds_dwordx4 v130, s[98:99]
	s_mov_b32 m0, s46
	s_nop 0
	global_load_lds_dwordx4 v128, s[42:43]
	s_add_i32 m0, s46, 0x2000
	s_nop 0
	global_load_lds_dwordx4 v130, s[42:43]
	s_mov_b32 m0, s57
	s_nop 0
	global_load_lds_dwordx4 v134, s[100:101]
	s_mov_b32 m0, s58
	s_nop 0
	global_load_lds_dwordx4 v132, s[100:101]
	s_waitcnt vmcnt(8) lgkmcnt(0)
	s_setprio 1
	s_barrier
	v_mfma_f32_16x16x32_bf16 v[60:63], v[150:153], v[182:185], v[60:63]
	v_mfma_f32_16x16x32_bf16 v[56:59], v[158:161], v[182:185], v[56:59]
	v_mfma_f32_16x16x32_bf16 v[44:47], v[150:153], v[190:193], v[44:47]
	v_mfma_f32_16x16x32_bf16 v[40:43], v[158:161], v[190:193], v[40:43]
	v_mfma_f32_16x16x32_bf16 v[28:31], v[150:153], v[198:201], v[28:31]
	v_mfma_f32_16x16x32_bf16 v[24:27], v[158:161], v[198:201], v[24:27]
	v_mfma_f32_16x16x32_bf16 v[12:15], v[150:153], v[206:209], v[12:15]
	v_mfma_f32_16x16x32_bf16 v[8:11], v[158:161], v[206:209], v[8:11]
	v_mfma_f32_16x16x32_bf16 v[60:63], v[154:157], v[186:189], v[60:63]
	v_mfma_f32_16x16x32_bf16 v[56:59], v[162:165], v[186:189], v[56:59]
	v_mfma_f32_16x16x32_bf16 v[44:47], v[154:157], v[194:197], v[44:47]
	v_mfma_f32_16x16x32_bf16 v[40:43], v[162:165], v[194:197], v[40:43]
	v_mfma_f32_16x16x32_bf16 v[28:31], v[154:157], v[202:205], v[28:31]
	v_mfma_f32_16x16x32_bf16 v[24:27], v[162:165], v[202:205], v[24:27]
	v_mfma_f32_16x16x32_bf16 v[12:15], v[154:157], v[210:213], v[12:15]
	v_mfma_f32_16x16x32_bf16 v[8:11], v[162:165], v[210:213], v[8:11]
	v_mfma_f32_16x16x32_bf16 v[52:55], v[166:169], v[182:185], v[52:55]
	v_mfma_f32_16x16x32_bf16 v[48:51], v[174:177], v[182:185], v[48:51]
	v_mfma_f32_16x16x32_bf16 v[36:39], v[166:169], v[190:193], v[36:39]
	v_mfma_f32_16x16x32_bf16 v[32:35], v[174:177], v[190:193], v[32:35]
	v_mfma_f32_16x16x32_bf16 v[20:23], v[166:169], v[198:201], v[20:23]
	v_mfma_f32_16x16x32_bf16 v[16:19], v[174:177], v[198:201], v[16:19]
	v_mfma_f32_16x16x32_bf16 v[4:7], v[166:169], v[206:209], v[4:7]
	v_mfma_f32_16x16x32_bf16 v[0:3], v[174:177], v[206:209], v[0:3]
	v_mfma_f32_16x16x32_bf16 v[52:55], v[170:173], v[186:189], v[52:55]
	v_mfma_f32_16x16x32_bf16 v[48:51], v[178:181], v[186:189], v[48:51]
	v_mfma_f32_16x16x32_bf16 v[36:39], v[170:173], v[194:197], v[36:39]
	v_mfma_f32_16x16x32_bf16 v[32:35], v[178:181], v[194:197], v[32:35]
	v_mfma_f32_16x16x32_bf16 v[20:23], v[170:173], v[202:205], v[20:23]
	v_mfma_f32_16x16x32_bf16 v[16:19], v[178:181], v[202:205], v[16:19]
	v_mfma_f32_16x16x32_bf16 v[4:7], v[170:173], v[210:213], v[4:7]
	s_setprio 0
	v_mfma_f32_16x16x32_bf16 v[0:3], v[178:181], v[210:213], v[0:3]
	s_barrier
	s_add_i32 s69, s69, 2
	s_add_u32 s30, s30, 0x100
	s_addc_u32 s31, s31, 0
	s_add_u32 s67, s67, 0x100
	s_addc_u32 s68, s68, 0
	s_cmp_gt_u32 s69, 29
	s_cbranch_scc0 .LBB0_1340
	s_and_b64 vcc, exec, s[18:19]
	s_cbranch_vccz .LBB0_1343
	s_barrier

; #define PG8_STAGE(bufoff, gbase, voff) do { _Pragma("unroll") for (int _i = 0; _i < 2; ++_i) \
;         __builtin_amdgcn_global_load_lds((const unsigned*)((const char*)(gbase) + (voff)[_i]), (LAS unsigned*)(lds + (bufoff) + ldsw + _i * 8192), 16, 0, 0); } while (0)
; #define PG8_LDA(dst, b, h) do { _Pragma("unroll") for (int m = 0; m < 4; ++m) _Pragma("unroll") for (int k = 0; k < 2; ++k) dst[m][k] = *(const LAS bf16x8*)(lds + PG8_SA(b, h) + aoff + m * 2048 + k * 1024); } while (0)
; #define PG8_LDB(dst, b, h) do { _Pragma("unroll") for (int n = 0; n < 2; ++n) _Pragma("unroll") for (int k = 0; k < 2; ++k) dst[n][k] = *(const LAS bf16x8*)(lds + PG8_SB(b, h) + boff + n * 2048 + k * 1024); } while (0)
; #define PG8_WAIT_V(n) asm volatile("s_waitcnt vmcnt(" #n ")" ::: "memory")
; #define PG8_WAIT_L(n) asm volatile("s_waitcnt lgkmcnt(" #n ")" ::: "memory")
; #define PG8_BAR __builtin_amdgcn_s_barrier()
; #define PG8_SCHED __builtin_amdgcn_sched_barrier(0)
; template <class Epi, bool FP8 = false>
; __device__ __forceinline__ void gemm_phase(LAS unsigned char* lds, const Gemm g, const StaticOrder& S_, const Epi& E, const int tid) {
;     ...
;         const bool has_next = S_.next(ui + 1, nxt);
;         const char* nA = has_next ? (const char*)g.A + (size_t)nxt.pm * tstepA : cA; const char* nB = has_next ? (const char*)g.Bt + (size_t)nxt.pn * tstepB : cB;
;         for (int t = 0; t < nt; t += 2) {
;             const bool last = (t == nt - 2);
;             const char* a1 = cA + (size_t)(t + 1) * kstep;
;             const char* a2 = last ? nA : cA + (size_t)(t + 2) * kstep; const char* b2 = last ? nB : cB + (size_t)(t + 2) * kstep;
;             const char* a3 = a2 + kstep; const char* b3 = b2 + kstep;
;             PG8_LDB(B0, 0, 0); PG8_LDB(B1, 0, 1); PG8_SCHED; PG8_LDA(At, 0, 0); PG8_STAGE(PG8_SA(1, 1), a1 + hstepA, voffA);
;             PG8_WAIT_V(8); PG8_WAIT_L(0); PG8_BAR; PG8_MMA(0, 0, At, B0); PG8_MMA(0, 1, At, B1); PG8_BAR; PG8_SCHED;
;     ...
;         for (int a = 0; a < 2; ++a)
; #pragma unroll
;             for (int b = 0; b < 2; ++b)
; #pragma unroll
;                 for (int m = 0; m < 4; ++m)
; #pragma unroll
;                     for (int n = 0; n < 2; ++n) acc[a][b][m][n] = (f32x4){0.f, 0.f, 0.f, 0.f};
;         cur = nxt; cA = nA; cB = nB; ++ui;
;         if (wr == 1) PG8_BAR;
.LBB0_1419:
	s_add_u32 s62, s28, 0x100
	v_mov_b32_e32 v0, 0
	s_addc_u32 s63, s29, 0
	s_mov_b32 s66, -2
	v_mov_b64_e32 v[0:1], 0
	v_mov_b64_e32 v[2:3], 0
	v_mov_b64_e32 v[4:5], 0
	v_mov_b64_e32 v[6:7], 0
	v_mov_b64_e32 v[8:9], 0
	v_mov_b64_e32 v[10:11], 0
	v_mov_b64_e32 v[12:13], 0
	v_mov_b64_e32 v[14:15], 0
	v_mov_b64_e32 v[16:17], 0
	v_mov_b64_e32 v[18:19], 0
	v_mov_b64_e32 v[20:21], 0
	v_mov_b64_e32 v[22:23], 0
	v_mov_b64_e32 v[24:25], 0
	v_mov_b64_e32 v[26:27], 0
	v_mov_b64_e32 v[28:29], 0
	v_mov_b64_e32 v[30:31], 0
	v_mov_b64_e32 v[32:33], 0
	v_mov_b64_e32 v[34:35], 0
	v_mov_b64_e32 v[36:37], 0
	v_mov_b64_e32 v[38:39], 0
	v_mov_b64_e32 v[40:41], 0
	v_mov_b64_e32 v[42:43], 0
	v_mov_b64_e32 v[44:45], 0
	v_mov_b64_e32 v[46:47], 0
	v_mov_b64_e32 v[48:49], 0
	v_mov_b64_e32 v[50:51], 0
	v_mov_b64_e32 v[52:53], 0
	v_mov_b64_e32 v[54:55], 0
	v_mov_b64_e32 v[56:57], 0
	v_mov_b64_e32 v[58:59], 0
	v_mov_b64_e32 v[60:61], 0
	v_mov_b64_e32 v[62:63], 0
	v_mov_b64_e32 v[64:65], 0
	v_mov_b64_e32 v[66:67], 0
	v_mov_b64_e32 v[68:69], 0
	v_mov_b64_e32 v[70:71], 0
	v_mov_b64_e32 v[72:73], 0
	v_mov_b64_e32 v[74:75], 0
	v_mov_b64_e32 v[76:77], 0
	v_mov_b64_e32 v[78:79], 0
	v_mov_b64_e32 v[80:81], 0
	v_mov_b64_e32 v[82:83], 0
	v_mov_b64_e32 v[84:85], 0
	v_mov_b64_e32 v[86:87], 0
	v_mov_b64_e32 v[88:89], 0
	v_mov_b64_e32 v[90:91], 0
	v_mov_b64_e32 v[92:93], 0
	v_mov_b64_e32 v[94:95], 0
	v_mov_b64_e32 v[96:97], 0
	v_mov_b64_e32 v[98:99], 0
	v_mov_b64_e32 v[100:101], 0
	v_mov_b64_e32 v[102:103], 0
	v_mov_b64_e32 v[104:105], 0
	v_mov_b64_e32 v[106:107], 0
	v_mov_b64_e32 v[108:109], 0
	v_mov_b64_e32 v[110:111], 0
	v_mov_b64_e32 v[112:113], 0
	v_mov_b64_e32 v[114:115], 0
	v_mov_b64_e32 v[116:117], 0
	v_mov_b64_e32 v[118:119], 0
	v_mov_b64_e32 v[120:121], 0
	v_mov_b64_e32 v[122:123], 0
	v_mov_b64_e32 v[124:125], 0
	v_mov_b64_e32 v[126:127], 0
.LBB0_1420:
	ds_read_b128 v[140:143], v152
	ds_read_b128 v[144:147], v152 offset:1024
	ds_read_b128 v[156:159], v152 offset:2048
	ds_read_b128 v[160:163], v152 offset:3072
	ds_read_b128 v[164:167], v153
	ds_read_b128 v[168:171], v153 offset:1024
	ds_read_b128 v[172:175], v153 offset:2048
	ds_read_b128 v[176:179], v153 offset:3072
	s_add_u32 s28, s26, 0x100
	s_addc_u32 s29, s27, 0
	s_cmpk_eq_i32 s66, 0x54
	s_cselect_b32 s43, s7, s29
	s_cselect_b32 s42, s6, s28
	s_cselect_b32 s31, s25, s63
	s_cselect_b32 s30, s24, s62
	s_add_i32 m0, s49, 0xc000
	ds_read_b128 v[180:183], v154
	ds_read_b128 v[184:187], v154 offset:1024
	ds_read_b128 v[188:191], v154 offset:2048
	ds_read_b128 v[192:195], v154 offset:3072
	ds_read_b128 v[196:199], v154 offset:4096
	ds_read_b128 v[200:203], v154 offset:5120
	ds_read_b128 v[204:207], v154 offset:6144
	ds_read_b128 v[208:211], v154 offset:7168
	global_load_lds_dwordx4 v132, s[26:27]
	s_add_i32 m0, s49, 0xe000
	s_nop 0
	global_load_lds_dwordx4 v134, s[26:27]
	s_waitcnt vmcnt(8) lgkmcnt(0)
	s_setprio 1
	s_barrier
	v_mfma_f32_16x16x32_bf16 v[124:127], v[140:143], v[180:183], v[124:127]
	v_mfma_f32_16x16x32_bf16 v[120:123], v[156:159], v[180:183], v[120:123]
	v_mfma_f32_16x16x32_bf16 v[108:111], v[140:143], v[188:191], v[108:111]
	v_mfma_f32_16x16x32_bf16 v[104:107], v[156:159], v[188:191], v[104:107]
	v_mfma_f32_16x16x32_bf16 v[92:95], v[140:143], v[196:199], v[92:95]
	v_mfma_f32_16x16x32_bf16 v[88:91], v[156:159], v[196:199], v[88:91]
	v_mfma_f32_16x16x32_bf16 v[76:79], v[140:143], v[204:207], v[76:79]
	v_mfma_f32_16x16x32_bf16 v[72:75], v[156:159], v[204:207], v[72:75]
	v_mfma_f32_16x16x32_bf16 v[124:127], v[144:147], v[184:187], v[124:127]
	v_mfma_f32_16x16x32_bf16 v[120:123], v[160:163], v[184:187], v[120:123]
	v_mfma_f32_16x16x32_bf16 v[108:111], v[144:147], v[192:195], v[108:111]
	v_mfma_f32_16x16x32_bf16 v[104:107], v[160:163], v[192:195], v[104:107]
	v_mfma_f32_16x16x32_bf16 v[92:95], v[144:147], v[200:203], v[92:95]
	v_mfma_f32_16x16x32_bf16 v[88:91], v[160:163], v[200:203], v[88:91]
	v_mfma_f32_16x16x32_bf16 v[76:79], v[144:147], v[208:211], v[76:79]
	v_mfma_f32_16x16x32_bf16 v[72:75], v[160:163], v[208:211], v[72:75]
	v_mfma_f32_16x16x32_bf16 v[116:119], v[164:167], v[180:183], v[116:119]
	v_mfma_f32_16x16x32_bf16 v[112:115], v[172:175], v[180:183], v[112:115]
	v_mfma_f32_16x16x32_bf16 v[100:103], v[164:167], v[188:191], v[100:103]
	v_mfma_f32_16x16x32_bf16 v[96:99], v[172:175], v[188:191], v[96:99]
	v_mfma_f32_16x16x32_bf16 v[84:87], v[164:167], v[196:199], v[84:87]
	v_mfma_f32_16x16x32_bf16 v[80:83], v[172:175], v[196:199], v[80:83]
	v_mfma_f32_16x16x32_bf16 v[68:71], v[164:167], v[204:207], v[68:71]
	v_mfma_f32_16x16x32_bf16 v[64:67], v[172:175], v[204:207], v[64:67]
	v_mfma_f32_16x16x32_bf16 v[116:119], v[168:171], v[184:187], v[116:119]
	v_mfma_f32_16x16x32_bf16 v[112:115], v[176:179], v[184:187], v[112:115]
	v_mfma_f32_16x16x32_bf16 v[100:103], v[168:171], v[192:195], v[100:103]
	v_mfma_f32_16x16x32_bf16 v[96:99], v[176:179], v[192:195], v[96:99]
	v_mfma_f32_16x16x32_bf16 v[84:87], v[168:171], v[200:203], v[84:87]
	v_mfma_f32_16x16x32_bf16 v[80:83], v[176:179], v[200:203], v[80:83]
	v_mfma_f32_16x16x32_bf16 v[68:71], v[168:171], v[208:211], v[68:71]
	s_setprio 0
	v_mfma_f32_16x16x32_bf16 v[64:67], v[176:179], v[208:211], v[64:67]
	s_barrier
; #define PG8_STAGE(bufoff, gbase, voff) do { _Pragma("unroll") for (int _i = 0; _i < 2; ++_i) \
;         __builtin_amdgcn_global_load_lds((const unsigned*)((const char*)(gbase) + (voff)[_i]), (LAS unsigned*)(lds + (bufoff) + ldsw + _i * 8192), 16, 0, 0); } while (0)
; #define PG8_LDA(dst, b, h) do { _Pragma("unroll") for (int m = 0; m < 4; ++m) _Pragma("unroll") for (int k = 0; k < 2; ++k) dst[m][k] = *(const LAS bf16x8*)(lds + PG8_SA(b, h) + aoff + m * 2048 + k * 1024); } while (0)
; #define PG8_LDB(dst, b, h) do { _Pragma("unroll") for (int n = 0; n < 2; ++n) _Pragma("unroll") for (int k = 0; k < 2; ++k) dst[n][k] = *(const LAS bf16x8*)(lds + PG8_SB(b, h) + boff + n * 2048 + k * 1024); } while (0)
; #define PG8_WAIT_V(n) asm volatile("s_waitcnt vmcnt(" #n ")" ::: "memory")
; #define PG8_WAIT_L(n) asm volatile("s_waitcnt lgkmcnt(" #n ")" ::: "memory")
; #define PG8_BAR __builtin_amdgcn_s_barrier()
; #define PG8_SCHED __builtin_amdgcn_sched_barrier(0)
; template <class Epi, bool FP8 = false>
; __device__ __forceinline__ void gemm_phase(LAS unsigned char* lds, const Gemm g, const StaticOrder& S_, const Epi& E, const int tid) {
;     ...
;             PG8_LDA(At, 0, 1); PG8_STAGE(PG8_SB(0, 0), b2, voffB); PG8_STAGE(PG8_SB(0, 1), b2 + hstepB, voffB); PG8_STAGE(PG8_SA(0, 0), a2, voffA);
;             PG8_WAIT_V(8); PG8_WAIT_L(0); PG8_BAR; PG8_MMA(1, 0, At, B0); PG8_MMA(1, 1, At, B1); PG8_BAR; PG8_SCHED;
;             PG8_LDB(B0, 1, 0); PG8_LDB(B1, 1, 1); PG8_SCHED; PG8_LDA(At, 1, 0); PG8_STAGE(PG8_SA(0, 1), a2 + hstepA, voffA);
;             PG8_WAIT_V(8); PG8_WAIT_L(0); PG8_BAR; PG8_MMA(0, 0, At, B0); PG8_MMA(0, 1, At, B1); PG8_BAR; PG8_SCHED;
	s_add_u32 s98, s30, s18
	s_addc_u32 s99, s31, s19
	s_add_u32 s100, s42, s18
	s_addc_u32 s101, s43, s19
	s_add_i32 s26, s56, s48
	s_mov_b32 m0, s26
	ds_read_b128 v[180:183], v154 offset:16384
	ds_read_b128 v[184:187], v154 offset:17408
	ds_read_b128 v[188:191], v154 offset:18432
	ds_read_b128 v[192:195], v154 offset:19456
	ds_read_b128 v[196:199], v154 offset:20480
	ds_read_b128 v[200:203], v154 offset:21504
	ds_read_b128 v[204:207], v154 offset:22528
	ds_read_b128 v[208:211], v154 offset:23552
	global_load_lds_dwordx4 v128, s[30:31]
	s_add_i32 m0, s26, 0x2000
	s_add_u32 s26, s30, 0x160000
	s_addc_u32 s27, s31, 0
	s_add_i32 s67, s57, s48
	global_load_lds_dwordx4 v130, s[30:31]
	s_mov_b32 m0, s67
	s_nop 0
	global_load_lds_dwordx4 v128, s[26:27]
	s_add_i32 m0, s67, 0x2000
	s_nop 0
	global_load_lds_dwordx4 v130, s[26:27]
	s_mov_b32 m0, s49
	s_nop 0
	global_load_lds_dwordx4 v128, s[42:43]
	s_mov_b32 m0, s50
	s_nop 0
	global_load_lds_dwordx4 v130, s[42:43]
	s_waitcnt vmcnt(8) lgkmcnt(0)
	s_setprio 1
	s_barrier
	v_mfma_f32_16x16x32_bf16 v[60:63], v[140:143], v[180:183], v[60:63]
	v_mfma_f32_16x16x32_bf16 v[56:59], v[156:159], v[180:183], v[56:59]
	v_mfma_f32_16x16x32_bf16 v[44:47], v[140:143], v[188:191], v[44:47]
	v_mfma_f32_16x16x32_bf16 v[40:43], v[156:159], v[188:191], v[40:43]
	v_mfma_f32_16x16x32_bf16 v[28:31], v[140:143], v[196:199], v[28:31]
	v_mfma_f32_16x16x32_bf16 v[24:27], v[156:159], v[196:199], v[24:27]
	v_mfma_f32_16x16x32_bf16 v[12:15], v[140:143], v[204:207], v[12:15]
	v_mfma_f32_16x16x32_bf16 v[8:11], v[156:159], v[204:207], v[8:11]
	v_mfma_f32_16x16x32_bf16 v[60:63], v[144:147], v[184:187], v[60:63]
	v_mfma_f32_16x16x32_bf16 v[56:59], v[160:163], v[184:187], v[56:59]
	v_mfma_f32_16x16x32_bf16 v[44:47], v[144:147], v[192:195], v[44:47]
	v_mfma_f32_16x16x32_bf16 v[40:43], v[160:163], v[192:195], v[40:43]
	v_mfma_f32_16x16x32_bf16 v[28:31], v[144:147], v[200:203], v[28:31]
	v_mfma_f32_16x16x32_bf16 v[24:27], v[160:163], v[200:203], v[24:27]
	v_mfma_f32_16x16x32_bf16 v[12:15], v[144:147], v[208:211], v[12:15]
	v_mfma_f32_16x16x32_bf16 v[8:11], v[160:163], v[208:211], v[8:11]
	v_mfma_f32_16x16x32_bf16 v[52:55], v[164:167], v[180:183], v[52:55]
	v_mfma_f32_16x16x32_bf16 v[48:51], v[172:175], v[180:183], v[48:51]
	v_mfma_f32_16x16x32_bf16 v[36:39], v[164:167], v[188:191], v[36:39]
	v_mfma_f32_16x16x32_bf16 v[32:35], v[172:175], v[188:191], v[32:35]
	v_mfma_f32_16x16x32_bf16 v[20:23], v[164:167], v[196:199], v[20:23]
	v_mfma_f32_16x16x32_bf16 v[16:19], v[172:175], v[196:199], v[16:19]
	v_mfma_f32_16x16x32_bf16 v[4:7], v[164:167], v[204:207], v[4:7]
	v_mfma_f32_16x16x32_bf16 v[0:3], v[172:175], v[204:207], v[0:3]
	v_mfma_f32_16x16x32_bf16 v[52:55], v[168:171], v[184:187], v[52:55]
	v_mfma_f32_16x16x32_bf16 v[48:51], v[176:179], v[184:187], v[48:51]
	v_mfma_f32_16x16x32_bf16 v[36:39], v[168:171], v[192:195], v[36:39]
	v_mfma_f32_16x16x32_bf16 v[32:35], v[176:179], v[192:195], v[32:35]
	v_mfma_f32_16x16x32_bf16 v[20:23], v[168:171], v[200:203], v[20:23]
	v_mfma_f32_16x16x32_bf16 v[16:19], v[176:179], v[200:203], v[16:19]
	v_mfma_f32_16x16x32_bf16 v[4:7], v[168:171], v[208:211], v[4:7]
	s_setprio 0
	v_mfma_f32_16x16x32_bf16 v[0:3], v[176:179], v[208:211], v[0:3]
	s_barrier
	s_add_i32 s67, 0, 0x18000
	v_add_u32_e32 v155, s67, v150
	s_add_i32 s68, 0, 0x1c000
	ds_read_b128 v[140:143], v155
	ds_read_b128 v[144:147], v155 offset:1024
	ds_read_b128 v[156:159], v155 offset:2048
	ds_read_b128 v[160:163], v155 offset:3072
	v_add_u32_e32 v155, s68, v150
	ds_read_b128 v[164:167], v155
	ds_read_b128 v[168:171], v155 offset:1024
	ds_read_b128 v[172:175], v155 offset:2048
	ds_read_b128 v[176:179], v155 offset:3072
	s_add_u32 s26, s42, 0x160000
	s_addc_u32 s27, s43, 0
	s_mov_b32 m0, s51
	ds_read_b128 v[180:183], v154 offset:32768
	ds_read_b128 v[184:187], v154 offset:33792
	ds_read_b128 v[188:191], v154 offset:34816
	ds_read_b128 v[192:195], v154 offset:35840
	ds_read_b128 v[196:199], v154 offset:36864
	ds_read_b128 v[200:203], v154 offset:37888
	ds_read_b128 v[204:207], v154 offset:38912
	ds_read_b128 v[208:211], v154 offset:39936
	global_load_lds_dwordx4 v128, s[26:27]
	s_mov_b32 m0, s52
	s_nop 0
	global_load_lds_dwordx4 v130, s[26:27]
	s_waitcnt vmcnt(8) lgkmcnt(0)
	s_setprio 1
	s_barrier
; #define PG8_STAGE(bufoff, gbase, voff) do { _Pragma("unroll") for (int _i = 0; _i < 2; ++_i) \
;         __builtin_amdgcn_global_load_lds((const unsigned*)((const char*)(gbase) + (voff)[_i]), (LAS unsigned*)(lds + (bufoff) + ldsw + _i * 8192), 16, 0, 0); } while (0)
; #define PG8_LDA(dst, b, h) do { _Pragma("unroll") for (int m = 0; m < 4; ++m) _Pragma("unroll") for (int k = 0; k < 2; ++k) dst[m][k] = *(const LAS bf16x8*)(lds + PG8_SA(b, h) + aoff + m * 2048 + k * 1024); } while (0)
; #define PG8_WAIT_V(n) asm volatile("s_waitcnt vmcnt(" #n ")" ::: "memory")
; #define PG8_WAIT_L(n) asm volatile("s_waitcnt lgkmcnt(" #n ")" ::: "memory")
; #define PG8_BAR __builtin_amdgcn_s_barrier()
; #define PG8_SCHED __builtin_amdgcn_sched_barrier(0)
; template <class Epi, bool FP8 = false>
; __device__ __forceinline__ void gemm_phase(LAS unsigned char* lds, const Gemm g, const StaticOrder& S_, const Epi& E, const int tid) {
;     ...
;             PG8_WAIT_V(8); PG8_WAIT_L(0); PG8_BAR; PG8_MMA(0, 0, At, B0); PG8_MMA(0, 1, At, B1); PG8_BAR; PG8_SCHED;
;             PG8_LDA(At, 1, 1); PG8_STAGE(PG8_SB(1, 0), b3, voffB); PG8_STAGE(PG8_SB(1, 1), b3 + hstepB, voffB); PG8_STAGE(PG8_SA(1, 0), a3, voffA);
;             PG8_WAIT_V(8); PG8_WAIT_L(0); PG8_BAR; PG8_MMA(1, 0, At, B0); PG8_MMA(1, 1, At, B1); PG8_BAR; PG8_SCHED;
;         }
;         if (wr == 0) PG8_BAR;
	v_mfma_f32_16x16x32_bf16 v[124:127], v[140:143], v[180:183], v[124:127]
	v_mfma_f32_16x16x32_bf16 v[120:123], v[156:159], v[180:183], v[120:123]
	v_mfma_f32_16x16x32_bf16 v[108:111], v[140:143], v[188:191], v[108:111]
	v_mfma_f32_16x16x32_bf16 v[104:107], v[156:159], v[188:191], v[104:107]
	v_mfma_f32_16x16x32_bf16 v[92:95], v[140:143], v[196:199], v[92:95]
	v_mfma_f32_16x16x32_bf16 v[88:91], v[156:159], v[196:199], v[88:91]
	v_mfma_f32_16x16x32_bf16 v[76:79], v[140:143], v[204:207], v[76:79]
	v_mfma_f32_16x16x32_bf16 v[72:75], v[156:159], v[204:207], v[72:75]
	v_mfma_f32_16x16x32_bf16 v[124:127], v[144:147], v[184:187], v[124:127]
	v_mfma_f32_16x16x32_bf16 v[120:123], v[160:163], v[184:187], v[120:123]
	v_mfma_f32_16x16x32_bf16 v[108:111], v[144:147], v[192:195], v[108:111]
	v_mfma_f32_16x16x32_bf16 v[104:107], v[160:163], v[192:195], v[104:107]
	v_mfma_f32_16x16x32_bf16 v[92:95], v[144:147], v[200:203], v[92:95]
	v_mfma_f32_16x16x32_bf16 v[88:91], v[160:163], v[200:203], v[88:91]
	v_mfma_f32_16x16x32_bf16 v[76:79], v[144:147], v[208:211], v[76:79]
	v_mfma_f32_16x16x32_bf16 v[72:75], v[160:163], v[208:211], v[72:75]
	v_mfma_f32_16x16x32_bf16 v[116:119], v[164:167], v[180:183], v[116:119]
	v_mfma_f32_16x16x32_bf16 v[112:115], v[172:175], v[180:183], v[112:115]
	v_mfma_f32_16x16x32_bf16 v[100:103], v[164:167], v[188:191], v[100:103]
	v_mfma_f32_16x16x32_bf16 v[96:99], v[172:175], v[188:191], v[96:99]
	v_mfma_f32_16x16x32_bf16 v[84:87], v[164:167], v[196:199], v[84:87]
	v_mfma_f32_16x16x32_bf16 v[80:83], v[172:175], v[196:199], v[80:83]
	v_mfma_f32_16x16x32_bf16 v[68:71], v[164:167], v[204:207], v[68:71]
	v_mfma_f32_16x16x32_bf16 v[64:67], v[172:175], v[204:207], v[64:67]
	v_mfma_f32_16x16x32_bf16 v[116:119], v[168:171], v[184:187], v[116:119]
	v_mfma_f32_16x16x32_bf16 v[112:115], v[176:179], v[184:187], v[112:115]
	v_mfma_f32_16x16x32_bf16 v[100:103], v[168:171], v[192:195], v[100:103]
	v_mfma_f32_16x16x32_bf16 v[96:99], v[176:179], v[192:195], v[96:99]
	v_mfma_f32_16x16x32_bf16 v[84:87], v[168:171], v[200:203], v[84:87]
	v_mfma_f32_16x16x32_bf16 v[80:83], v[176:179], v[200:203], v[80:83]
	v_mfma_f32_16x16x32_bf16 v[68:71], v[168:171], v[208:211], v[68:71]
	s_setprio 0
	v_mfma_f32_16x16x32_bf16 v[64:67], v[176:179], v[208:211], v[64:67]
	s_barrier
	s_add_i32 s26, s67, s48
	s_mov_b32 m0, s26
	ds_read_b128 v[180:183], v154 offset:49152
	ds_read_b128 v[184:187], v154 offset:50176
	ds_read_b128 v[188:191], v154 offset:51200
	ds_read_b128 v[192:195], v154 offset:52224
	ds_read_b128 v[196:199], v154 offset:53248
	ds_read_b128 v[200:203], v154 offset:54272
	ds_read_b128 v[204:207], v154 offset:55296
	ds_read_b128 v[208:211], v154 offset:56320
	global_load_lds_dwordx4 v128, s[98:99]
	s_add_i32 m0, s26, 0x2000
	s_add_u32 s26, s30, 0x160080
	s_addc_u32 s27, s31, 0
	s_add_i32 s30, s68, s48
	global_load_lds_dwordx4 v130, s[98:99]
	s_mov_b32 m0, s30
	s_nop 0
	global_load_lds_dwordx4 v128, s[26:27]
	s_add_i32 m0, s30, 0x2000
	s_nop 0
	global_load_lds_dwordx4 v130, s[26:27]
	s_mov_b32 m0, s54
	s_nop 0
	global_load_lds_dwordx4 v128, s[100:101]
	s_mov_b32 m0, s55
	s_nop 0
	global_load_lds_dwordx4 v130, s[100:101]
	s_waitcnt vmcnt(8) lgkmcnt(0)
	s_setprio 1
	s_barrier
	v_mfma_f32_16x16x32_bf16 v[60:63], v[140:143], v[180:183], v[60:63]
	v_mfma_f32_16x16x32_bf16 v[56:59], v[156:159], v[180:183], v[56:59]
	v_mfma_f32_16x16x32_bf16 v[44:47], v[140:143], v[188:191], v[44:47]
	v_mfma_f32_16x16x32_bf16 v[40:43], v[156:159], v[188:191], v[40:43]
	v_mfma_f32_16x16x32_bf16 v[28:31], v[140:143], v[196:199], v[28:31]
	v_mfma_f32_16x16x32_bf16 v[24:27], v[156:159], v[196:199], v[24:27]
	v_mfma_f32_16x16x32_bf16 v[12:15], v[140:143], v[204:207], v[12:15]
	v_mfma_f32_16x16x32_bf16 v[8:11], v[156:159], v[204:207], v[8:11]
	v_mfma_f32_16x16x32_bf16 v[60:63], v[144:147], v[184:187], v[60:63]
	v_mfma_f32_16x16x32_bf16 v[56:59], v[160:163], v[184:187], v[56:59]
	v_mfma_f32_16x16x32_bf16 v[44:47], v[144:147], v[192:195], v[44:47]
	v_mfma_f32_16x16x32_bf16 v[40:43], v[160:163], v[192:195], v[40:43]
	v_mfma_f32_16x16x32_bf16 v[28:31], v[144:147], v[200:203], v[28:31]
	v_mfma_f32_16x16x32_bf16 v[24:27], v[160:163], v[200:203], v[24:27]
	v_mfma_f32_16x16x32_bf16 v[12:15], v[144:147], v[208:211], v[12:15]
	v_mfma_f32_16x16x32_bf16 v[8:11], v[160:163], v[208:211], v[8:11]
	v_mfma_f32_16x16x32_bf16 v[52:55], v[164:167], v[180:183], v[52:55]
	v_mfma_f32_16x16x32_bf16 v[48:51], v[172:175], v[180:183], v[48:51]
	v_mfma_f32_16x16x32_bf16 v[36:39], v[164:167], v[188:191], v[36:39]
	v_mfma_f32_16x16x32_bf16 v[32:35], v[172:175], v[188:191], v[32:35]
	v_mfma_f32_16x16x32_bf16 v[20:23], v[164:167], v[196:199], v[20:23]
	v_mfma_f32_16x16x32_bf16 v[16:19], v[172:175], v[196:199], v[16:19]
	v_mfma_f32_16x16x32_bf16 v[4:7], v[164:167], v[204:207], v[4:7]
	v_mfma_f32_16x16x32_bf16 v[0:3], v[172:175], v[204:207], v[0:3]
	v_mfma_f32_16x16x32_bf16 v[52:55], v[168:171], v[184:187], v[52:55]
	v_mfma_f32_16x16x32_bf16 v[48:51], v[176:179], v[184:187], v[48:51]
	v_mfma_f32_16x16x32_bf16 v[36:39], v[168:171], v[192:195], v[36:39]
	v_mfma_f32_16x16x32_bf16 v[32:35], v[176:179], v[192:195], v[32:35]
	v_mfma_f32_16x16x32_bf16 v[20:23], v[168:171], v[200:203], v[20:23]
	v_mfma_f32_16x16x32_bf16 v[16:19], v[176:179], v[200:203], v[16:19]
	v_mfma_f32_16x16x32_bf16 v[4:7], v[168:171], v[208:211], v[4:7]
	s_setprio 0
	v_mfma_f32_16x16x32_bf16 v[0:3], v[176:179], v[208:211], v[0:3]
	s_barrier
	s_add_i32 s66, s66, 2
	s_add_u32 s62, s62, 0x100
	s_addc_u32 s63, s63, 0
	s_cmpk_gt_u32 s66, 0x55
	s_mov_b64 s[26:27], s[28:29]
	s_cbranch_scc0 .LBB0_1420
	s_and_b64 vcc, exec, s[20:21]
	s_cbranch_vccz .LBB0_1423
	s_barrier
